# S5 scan loops: first u-row (u0) of the next step prefetched from LDS during the current step (counted lgkmcnt), all 16 loops
# baseline (speedup 1.0000x reference)
; DI void s5_disc(const S5P& P, int dir, int g, int p, float& lr, float& li, f32x2 (&bb)[16]) {
;     const float dt = expf(P.log_dt[dir * 64 + g]); const float are = P.a_re[(dir * 64 + g) * 64 + p], aim = P.a_im[(dir * 64 + g) * 64 + p];
;     const float mag = expf(dt * are); lr = mag * cosf(dt * aim); li = mag * sinf(dt * aim);
;     const float den = are * are + aim * aim, nr = lr - 1.0f; const float cr = (nr * are + li * aim) / den, ci = (li * are - nr * aim) / den;
;     const f32x4* br = (const f32x4*)(P.b_re + (size_t)(g * 64 + p) * 16); const f32x4* bi = (const f32x4*)(P.b_im + (size_t)(g * 64 + p) * 16);
; #pragma unroll
;     for (int q = 0; q < 4; ++q) { const f32x4 r = br[q], i = bi[q];
; #pragma unroll
;         for (int e = 0; e < 4; ++e) bb[4 * q + e] = (f32x2){cr * r[e] - ci * i[e], cr * i[e] + ci * r[e]}; }
.LBB0_622:
	v_add_f32_e32 v128, -1.0, v126
	v_mov_b32_e32 v2, v73
	v_pk_mul_f32 v[74:75], v[72:73], v[72:73]
	v_pk_mul_f32 v[76:77], v[2:3], v[128:129] op_sel:[0,1] op_sel_hi:[0,0]
	v_pk_fma_f32 v[78:79], v[72:73], v[128:129], v[76:77]
	v_pk_fma_f32 v[72:73], v[72:73], v[128:129], v[76:77] op_sel_hi:[0,1,1] neg_lo:[0,0,1] neg_hi:[0,0,1]
	v_pk_add_f32 v[74:75], v[74:75], v[74:75] op_sel:[0,1] op_sel_hi:[0,1]
	v_div_scale_f32 v1, s[0:1], v75, v75, v73
	v_rcp_f32_e32 v2, v1
	s_waitcnt vmcnt(3)
	v_mov_b32_e32 v134, v13
	v_mov_b32_e32 v135, v13
	v_mov_b32_e32 v130, v9
	v_fma_f32 v71, -v1, v2, 1.0
	v_fmac_f32_e32 v2, v71, v2
	v_div_scale_f32 v71, vcc, v73, v75, v73
	v_mul_f32_e32 v72, v71, v2
	v_fma_f32 v76, -v1, v72, v71
	v_fmac_f32_e32 v72, v76, v2
	v_fma_f32 v1, -v1, v72, v71
	v_div_fmas_f32 v1, v1, v2, v72
	v_div_fixup_f32 v73, v1, v75, v73
	v_div_scale_f32 v1, s[0:1], v74, v74, v78
	v_rcp_f32_e32 v2, v1
	v_mov_b32_e32 v76, v13
	v_mov_b32_e32 v13, v12
	v_mov_b32_e32 v131, v9
	v_fma_f32 v71, -v1, v2, 1.0
	v_fmac_f32_e32 v2, v71, v2
	v_div_scale_f32 v71, vcc, v78, v74, v78
	v_mul_f32_e32 v72, v71, v2
	v_fma_f32 v75, -v1, v72, v71
	v_fmac_f32_e32 v72, v75, v2
	v_fma_f32 v1, -v1, v72, v71
	v_div_fmas_f32 v1, v1, v2, v72
	v_div_fixup_f32 v72, v1, v74, v78
	v_mov_b32_e32 v2, v9
	v_pk_mul_f32 v[76:77], v[76:77], v[72:73] op_sel_hi:[0,1]
	v_pk_fma_f32 v[176:177], v[2:3], v[72:73], v[76:77] op_sel:[0,0,1] op_sel_hi:[0,1,0] neg_lo:[0,0,1] neg_hi:[0,0,1]
	v_pk_fma_f32 v[76:77], v[2:3], v[72:73], v[76:77] op_sel:[0,0,1] op_sel_hi:[0,1,0]
	v_mov_b32_e32 v177, v77
	s_waitcnt vmcnt(0)
	v_pk_mul_f32 v[76:77], v[34:35], v[72:73] op_sel_hi:[0,1]
	v_pk_fma_f32 v[178:179], v[30:31], v[72:73], v[76:77] op_sel:[0,0,1] op_sel_hi:[1,1,0] neg_lo:[0,0,1] neg_hi:[0,0,1]
	v_pk_fma_f32 v[76:77], v[30:31], v[72:73], v[76:77] op_sel:[0,0,1] op_sel_hi:[0,1,0]
	v_mov_b32_e32 v179, v77
	v_pk_mul_f32 v[76:77], v[36:37], v[72:73] op_sel_hi:[0,1]
	v_pk_fma_f32 v[182:183], v[32:33], v[72:73], v[76:77] op_sel:[0,0,1] op_sel_hi:[1,1,0] neg_lo:[0,0,1] neg_hi:[0,0,1]
	v_pk_fma_f32 v[76:77], v[32:33], v[72:73], v[76:77] op_sel:[0,0,1] op_sel_hi:[0,1,0]
	v_mov_b32_e32 v76, v37
	v_mov_b32_e32 v183, v77
	v_mov_b32_e32 v2, v33
	v_pk_mul_f32 v[76:77], v[76:77], v[72:73] op_sel_hi:[0,1]
	v_pk_fma_f32 v[184:185], v[2:3], v[72:73], v[76:77] op_sel:[0,0,1] op_sel_hi:[0,1,0] neg_lo:[0,0,1] neg_hi:[0,0,1]
	v_pk_fma_f32 v[76:77], v[2:3], v[72:73], v[76:77] op_sel:[0,0,1] op_sel_hi:[0,1,0]
	v_mov_b32_e32 v185, v77
	v_pk_mul_f32 v[76:77], v[26:27], v[72:73] op_sel_hi:[0,1]
	v_pk_fma_f32 v[186:187], v[22:23], v[72:73], v[76:77] op_sel:[0,0,1] op_sel_hi:[1,1,0] neg_lo:[0,0,1] neg_hi:[0,0,1]
	v_pk_fma_f32 v[76:77], v[22:23], v[72:73], v[76:77] op_sel:[0,0,1] op_sel_hi:[0,1,0]
	v_mov_b32_e32 v76, v27
	v_mov_b32_e32 v187, v77
	v_mov_b32_e32 v2, v23
	v_pk_mul_f32 v[76:77], v[76:77], v[72:73] op_sel_hi:[0,1]
	v_pk_fma_f32 v[188:189], v[2:3], v[72:73], v[76:77] op_sel:[0,0,1] op_sel_hi:[0,1,0] neg_lo:[0,0,1] neg_hi:[0,0,1]
	v_pk_fma_f32 v[76:77], v[2:3], v[72:73], v[76:77] op_sel:[0,0,1] op_sel_hi:[0,1,0]
	v_mov_b32_e32 v189, v77
	v_pk_mul_f32 v[76:77], v[28:29], v[72:73] op_sel_hi:[0,1]
	v_pk_fma_f32 v[190:191], v[24:25], v[72:73], v[76:77] op_sel:[0,0,1] op_sel_hi:[1,1,0] neg_lo:[0,0,1] neg_hi:[0,0,1]
	v_pk_fma_f32 v[76:77], v[24:25], v[72:73], v[76:77] op_sel:[0,0,1] op_sel_hi:[0,1,0]
	v_mov_b32_e32 v76, v29
	v_mov_b32_e32 v191, v77
	v_mov_b32_e32 v2, v25
	v_pk_mul_f32 v[76:77], v[76:77], v[72:73] op_sel_hi:[0,1]
	v_pk_fma_f32 v[192:193], v[2:3], v[72:73], v[76:77] op_sel:[0,0,1] op_sel_hi:[0,1,0] neg_lo:[0,0,1] neg_hi:[0,0,1]
	v_pk_fma_f32 v[76:77], v[2:3], v[72:73], v[76:77] op_sel:[0,0,1] op_sel_hi:[0,1,0]
	v_mov_b32_e32 v193, v77
	v_pk_mul_f32 v[76:77], v[18:19], v[72:73] op_sel_hi:[0,1]
	v_pk_fma_f32 v[194:195], v[14:15], v[72:73], v[76:77] op_sel:[0,0,1] op_sel_hi:[1,1,0] neg_lo:[0,0,1] neg_hi:[0,0,1]
	v_pk_fma_f32 v[76:77], v[14:15], v[72:73], v[76:77] op_sel:[0,0,1] op_sel_hi:[0,1,0]
	v_mov_b32_e32 v76, v19
	v_mov_b32_e32 v195, v77
	v_mov_b32_e32 v2, v15
	v_pk_mul_f32 v[76:77], v[76:77], v[72:73] op_sel_hi:[0,1]
	v_pk_fma_f32 v[196:197], v[2:3], v[72:73], v[76:77] op_sel:[0,0,1] op_sel_hi:[0,1,0] neg_lo:[0,0,1] neg_hi:[0,0,1]
	v_pk_fma_f32 v[76:77], v[2:3], v[72:73], v[76:77] op_sel:[0,0,1] op_sel_hi:[0,1,0]
	v_mov_b32_e32 v197, v77
	v_pk_mul_f32 v[76:77], v[20:21], v[72:73] op_sel_hi:[0,1]
	v_pk_fma_f32 v[198:199], v[16:17], v[72:73], v[76:77] op_sel:[0,0,1] op_sel_hi:[1,1,0] neg_lo:[0,0,1] neg_hi:[0,0,1]
	v_pk_fma_f32 v[76:77], v[16:17], v[72:73], v[76:77] op_sel:[0,0,1] op_sel_hi:[0,1,0]
	v_mov_b32_e32 v76, v21
	v_mov_b32_e32 v199, v77
	v_mov_b32_e32 v2, v17
	v_pk_mul_f32 v[76:77], v[76:77], v[72:73] op_sel_hi:[0,1]
	v_pk_fma_f32 v[200:201], v[2:3], v[72:73], v[76:77] op_sel:[0,0,1] op_sel_hi:[0,1,0] neg_lo:[0,0,1] neg_hi:[0,0,1]
	v_pk_fma_f32 v[76:77], v[2:3], v[72:73], v[76:77] op_sel:[0,0,1] op_sel_hi:[0,1,0]
	v_mov_b32_e32 v201, v77
	v_pk_mul_f32 v[76:77], v[10:11], v[72:73] op_sel_hi:[0,1]
	v_pk_fma_f32 v[202:203], v[6:7], v[72:73], v[76:77] op_sel:[0,0,1] op_sel_hi:[1,1,0] neg_lo:[0,0,1] neg_hi:[0,0,1]
	v_pk_fma_f32 v[76:77], v[6:7], v[72:73], v[76:77] op_sel:[0,0,1] op_sel_hi:[0,1,0]
	v_mov_b32_e32 v76, v11
	v_mov_b32_e32 v203, v77
	v_mov_b32_e32 v2, v7
	v_pk_mul_f32 v[76:77], v[76:77], v[72:73] op_sel_hi:[0,1]
	v_pk_fma_f32 v[204:205], v[2:3], v[72:73], v[76:77] op_sel:[0,0,1] op_sel_hi:[0,1,0] neg_lo:[0,0,1] neg_hi:[0,0,1]
	v_pk_fma_f32 v[76:77], v[2:3], v[72:73], v[76:77] op_sel:[0,0,1] op_sel_hi:[0,1,0]
	v_mov_b32_e32 v74, v8
	v_mov_b32_e32 v75, v9
	v_mov_b32_e32 v138, v34
; #define LAS __attribute__((address_space(3)))
; DI unsigned pk2(float lo, float hi) { return pg8::cvt_pk_bf16(lo, hi); }
; template <int DIRN, int SUB> DI void s5_subtile(const LAS float* UF, LAS bf16* XT, float lr, float li, const f32x2 (&bb)[16], f32x2& x,
;                                                 const bf16x8 (&bfr)[4], f32x4& acc0, f32x4& acc1, int lane) {
;     ...
;     for (int i = 0; i < 32; ++i) { const int r = DIRN ? 31 - i : i;
;         x = s5_step((const LAS f32x4*)(UF + (32 * SUB + r) * 16), bb, lr, li, x);
;         const unsigned pkd = pk2(x.x, x.y); XT[r * 136 + lane] = (bf16)(pkd & 0xffffu); XT[r * 136 + 64 + lane] = (bf16)(pkd >> 16); }
	v_mov_b32_e32 v139, v34
	v_mov_b32_e32 v140, v35
	v_mov_b32_e32 v141, v35
	v_pk_mul_f32 v[34:35], v[34:35], v[72:73] op_sel:[1,0]
	v_mov_b32_e32 v205, v77
	v_mov_b32_e32 v9, v8
	v_pk_mul_f32 v[76:77], v[12:13], v[72:73] op_sel_hi:[0,1]
	v_mov_b32_e32 v132, v30
	v_mov_b32_e32 v133, v30
	v_mov_b32_e32 v136, v31
	v_mov_b32_e32 v137, v31
	v_pk_fma_f32 v[180:181], v[30:31], v[72:73], v[34:35] op_sel:[1,0,1] op_sel_hi:[1,1,0] neg_lo:[0,0,1] neg_hi:[0,0,1]
	v_pk_fma_f32 v[30:31], v[30:31], v[72:73], v[34:35] op_sel:[1,0,1] op_sel_hi:[1,1,0]
	v_pk_fma_f32 v[206:207], v[74:75], v[72:73], v[76:77] op_sel:[0,0,1] op_sel_hi:[1,1,0] neg_lo:[0,0,1] neg_hi:[0,0,1]
	v_pk_fma_f32 v[72:73], v[8:9], v[72:73], v[76:77] op_sel:[0,0,1] op_sel_hi:[0,1,0]
	v_lshlrev_b32_e32 v152, 1, v122
	v_mov_b32_e32 v181, v31
	v_mov_b32_e32 v30, v32
	v_mov_b32_e32 v31, v32
	v_mov_b32_e32 v34, v36
	v_mov_b32_e32 v35, v36
	v_mov_b32_e32 v32, v33
	v_mov_b32_e32 v36, v37
	v_mov_b32_e32 v142, v22
	v_mov_b32_e32 v143, v22
	v_mov_b32_e32 v144, v26
	v_mov_b32_e32 v145, v26
	v_mov_b32_e32 v22, v23
	v_mov_b32_e32 v26, v27
	v_mov_b32_e32 v146, v24
	v_mov_b32_e32 v147, v24
	v_mov_b32_e32 v148, v28
	v_mov_b32_e32 v149, v28
	v_mov_b32_e32 v24, v25
	v_mov_b32_e32 v28, v29
	v_mov_b32_e32 v162, v14
	v_mov_b32_e32 v163, v14
	v_mov_b32_e32 v164, v18
	v_mov_b32_e32 v165, v18
	v_mov_b32_e32 v14, v15
	v_mov_b32_e32 v18, v19
	v_mov_b32_e32 v166, v16
	v_mov_b32_e32 v167, v16
	v_mov_b32_e32 v168, v20
	v_mov_b32_e32 v169, v20
	v_mov_b32_e32 v16, v17
	v_mov_b32_e32 v20, v21
	v_mov_b32_e32 v170, v6
	v_mov_b32_e32 v171, v6
	v_mov_b32_e32 v172, v10
	v_mov_b32_e32 v173, v10
	v_mov_b32_e32 v6, v7
	v_mov_b32_e32 v10, v11
	v_mov_b32_e32 v207, v73
	v_mov_b32_e32 v127, v126
	v_xor_b32_e32 v128, 0x80000000, v129
	v_add_u32_e32 v1, 0x2000, v152
	s_mov_b32 s0, 0
	s_add_i32 s1, s49, s0
	v_mov_b32_e32 v250, s1
	ds_read_b128 v[246:249], v250
	s_waitcnt lgkmcnt(0)
.LBB0_623:
	s_add_i32 s1, s49, s0
	v_mov_b32_e32 v2, s1
	ds_read_b128 v[76:79], v2 offset:16
	ds_read_b128 v[80:83], v2 offset:32
	ds_read_b128 v[84:87], v2 offset:48
	s_waitcnt lgkmcnt(5)
	v_pk_mul_f32 v[88:89], v[180:181], v[246:247] op_sel:[0,1]
	v_pk_fma_f32 v[72:73], v[178:179], v[246:247], v[88:89] op_sel_hi:[1,0,1]
	v_mov_b32_e32 v2, v249
	v_pk_fma_f32 v[72:73], v[182:183], v[248:249], v[72:73] op_sel_hi:[1,0,1]
	s_add_i32 s1, s49, s0
	s_add_i32 s1, s1, 64
	v_mov_b32_e32 v250, s1
	ds_read_b128 v[246:249], v250
	s_waitcnt lgkmcnt(2)
	v_pk_mul_f32 v[74:75], v[196:197], v[80:81] op_sel:[0,1]
	v_pk_fma_f32 v[72:73], v[184:185], v[2:3], v[72:73] op_sel_hi:[1,0,1]
	v_pk_fma_f32 v[72:73], v[186:187], v[76:77], v[72:73] op_sel_hi:[1,0,1]
	v_pk_fma_f32 v[74:75], v[194:195], v[80:81], v[74:75] op_sel_hi:[1,0,1]
	v_pk_fma_f32 v[72:73], v[188:189], v[76:77], v[72:73] op_sel:[0,1,0]
	v_pk_fma_f32 v[74:75], v[198:199], v[82:83], v[74:75] op_sel_hi:[1,0,1]
	v_pk_fma_f32 v[72:73], v[190:191], v[78:79], v[72:73] op_sel_hi:[1,0,1]
	v_pk_fma_f32 v[72:73], v[192:193], v[78:79], v[72:73] op_sel:[0,1,0]
	v_pk_fma_f32 v[74:75], v[200:201], v[82:83], v[74:75] op_sel:[0,1,0]
	s_waitcnt lgkmcnt(1)
	v_pk_fma_f32 v[74:75], v[202:203], v[84:85], v[74:75] op_sel_hi:[1,0,1]
	v_pk_fma_f32 v[74:75], v[204:205], v[84:85], v[74:75] op_sel:[0,1,0]
	v_pk_fma_f32 v[74:75], v[206:207], v[86:87], v[74:75] op_sel_hi:[1,0,1]
	v_pk_fma_f32 v[74:75], v[176:177], v[86:87], v[74:75] op_sel:[0,1,0]
	v_pk_add_f32 v[72:73], v[72:73], v[74:75]
	v_pk_fma_f32 v[72:73], v[128:129], v[174:175], v[72:73] op_sel:[0,1,0] op_sel_hi:[1,0,1]
	v_pk_fma_f32 v[174:175], v[126:127], v[174:175], v[72:73]
	v_add_u32_e32 v72, s49, v1
	v_cvt_pk_bf16_f32 v2, v174, s0
	v_cvt_pk_bf16_f32 v71, v175, s0
	s_add_i32 s0, s0, 64
	v_add_u32_e32 v1, 0x110, v1
	s_cmpk_lg_i32 s0, 0x800
	ds_write_b16 v72, v2
	ds_write_b16 v72, v71 offset:128
	s_cbranch_scc1 .LBB0_623
	v_and_b32_e32 v125, 15, v122
	v_mul_u32_u24_e32 v1, 0x110, v125
	v_lshlrev_b32_e32 v2, 1, v70
	v_add3_u32 v1, s49, v1, v2
	ds_read_b128 v[98:101], v1 offset:8192
	ds_read_b128 v[94:97], v1 offset:8256
	ds_read_b128 v[82:85], v1 offset:12544
	ds_read_b128 v[86:89], v1 offset:12608
	ds_read_b128 v[90:93], v1 offset:8320
	ds_read_b128 v[78:81], v1 offset:8384
	ds_read_b128 v[70:73], v1 offset:12672
	ds_read_b128 v[74:77], v1 offset:12736
	v_add_u32_e32 v2, s40, v152
	s_mov_b32 s0, 0
	v_mov_b32_e32 v102, v2
	s_add_i32 s1, s41, s0
	v_mov_b32_e32 v250, s1
	ds_read_b128 v[246:249], v250
	s_waitcnt lgkmcnt(0)
; #define LAS __attribute__((address_space(3)))
; DI unsigned pk2(float lo, float hi) { return pg8::cvt_pk_bf16(lo, hi); }
; DI f32x4 mfma16(bf16x8 a, bf16x8 b, f32x4 c) { return __builtin_amdgcn_mfma_f32_16x16x32_bf16(a, b, c, 0, 0, 0); }
; template <int DIRN, int SUB> DI void s5_subtile(const LAS float* UF, LAS bf16* XT, float lr, float li, const f32x2 (&bb)[16], f32x2& x,
;                                                 const bf16x8 (&bfr)[4], f32x4& acc0, f32x4& acc1, int lane) {
; #pragma unroll 1
;     for (int i = 0; i < 32; ++i) { const int r = DIRN ? 31 - i : i;
;         x = s5_step((const LAS f32x4*)(UF + (32 * SUB + r) * 16), bb, lr, li, x);
;         const unsigned pkd = pk2(x.x, x.y); XT[r * 136 + lane] = (bf16)(pkd & 0xffffu); XT[r * 136 + 64 + lane] = (bf16)(pkd >> 16); }
; #pragma unroll
;     for (int ks = 0; ks < 4; ++ks) { const bf16x8 a0 = *(const LAS bf16x8*)(XT + (lane & 15) * 136 + 32 * ks + 8 * (lane >> 4)), a1 = *(const LAS bf16x8*)(XT + (16 + (lane & 15)) * 136 + 32 * ks + 8 * (lane >> 4));
;         acc0 = mfma16(a0, bfr[ks], acc0); acc1 = mfma16(a1, bfr[ks], acc1); }
.LBB0_625:
	s_add_i32 s1, s41, s0
	v_mov_b32_e32 v103, s1
	ds_read_b128 v[108:111], v103 offset:16
	ds_read_b128 v[112:115], v103 offset:32
	ds_read_b128 v[116:119], v103 offset:48
	s_waitcnt lgkmcnt(5)
	v_pk_mul_f32 v[120:121], v[180:181], v[246:247] op_sel:[0,1]
	v_pk_fma_f32 v[104:105], v[178:179], v[246:247], v[120:121] op_sel_hi:[1,0,1]
	v_pk_fma_f32 v[104:105], v[182:183], v[248:249], v[104:105] op_sel_hi:[1,0,1]
	v_pk_fma_f32 v[104:105], v[184:185], v[248:249], v[104:105] op_sel:[0,1,0]
	s_add_i32 s1, s41, s0
	s_add_i32 s1, s1, 64
	v_mov_b32_e32 v250, s1
	ds_read_b128 v[246:249], v250
	s_waitcnt lgkmcnt(3)
	v_pk_fma_f32 v[104:105], v[186:187], v[108:109], v[104:105] op_sel_hi:[1,0,1]
	v_pk_fma_f32 v[104:105], v[188:189], v[108:109], v[104:105] op_sel:[0,1,0]
	s_waitcnt lgkmcnt(2)
	v_pk_fma_f32 v[104:105], v[190:191], v[110:111], v[104:105] op_sel_hi:[1,0,1]
	v_pk_fma_f32 v[104:105], v[192:193], v[110:111], v[104:105] op_sel:[0,1,0]
	v_pk_mul_f32 v[106:107], v[196:197], v[112:113] op_sel:[0,1]
	v_pk_fma_f32 v[106:107], v[194:195], v[112:113], v[106:107] op_sel_hi:[1,0,1]
	v_pk_fma_f32 v[106:107], v[198:199], v[114:115], v[106:107] op_sel_hi:[1,0,1]
	v_pk_fma_f32 v[106:107], v[200:201], v[114:115], v[106:107] op_sel:[0,1,0]
	s_waitcnt lgkmcnt(1)
	v_mov_b32_e32 v108, v119
	v_pk_fma_f32 v[106:107], v[202:203], v[116:117], v[106:107] op_sel_hi:[1,0,1]
	v_pk_fma_f32 v[106:107], v[204:205], v[116:117], v[106:107] op_sel:[0,1,0]
	v_pk_fma_f32 v[106:107], v[206:207], v[118:119], v[106:107] op_sel_hi:[1,0,1]
	v_pk_fma_f32 v[106:107], v[176:177], v[108:109], v[106:107] op_sel_hi:[1,0,1]
	v_pk_add_f32 v[104:105], v[104:105], v[106:107]
	v_pk_fma_f32 v[104:105], v[128:129], v[174:175], v[104:105] op_sel:[0,1,0] op_sel_hi:[1,0,1]
	v_pk_fma_f32 v[174:175], v[126:127], v[174:175], v[104:105]
	v_cvt_pk_bf16_f32 v103, v174, s0
	v_cvt_pk_bf16_f32 v104, v175, s0
	s_add_i32 s0, s0, 64
	ds_write_b16 v102, v103
	ds_write_b16 v102, v104 offset:128
	v_add_u32_e32 v102, 0x110, v102
	s_cmpk_lg_i32 s0, 0x800
	s_cbranch_scc1 .LBB0_625
	v_cvt_pk_bf16_f32 v46, v46, v47
	v_cvt_pk_bf16_f32 v47, v48, v49
	v_cvt_pk_bf16_f32 v48, v66, v67
	v_cvt_pk_bf16_f32 v49, v68, v69
	v_cvt_pk_bf16_f32 v54, v54, v55
	v_cvt_pk_bf16_f32 v55, v56, v57
	v_cvt_pk_bf16_f32 v57, v52, v53
	v_cvt_pk_bf16_f32 v52, -v58, -v59
	v_cvt_pk_bf16_f32 v53, -v60, -v61
	v_mfma_f32_16x16x32_bf16 v[58:61], v[98:101], v[46:49], 0
	v_cvt_pk_bf16_f32 v56, v50, v51
	v_cvt_pk_bf16_f32 v50, -v62, -v63
	v_cvt_pk_bf16_f32 v51, -v64, -v65
	v_mfma_f32_16x16x32_bf16 v[58:61], v[94:97], v[54:57], v[58:61]
	s_mov_b32 s0, 0
	v_mov_b32_e32 v110, v2
	v_mfma_f32_16x16x32_bf16 v[90:93], v[90:93], v[50:53], v[58:61]
	v_mfma_f32_16x16x32_bf16 v[58:61], v[82:85], v[46:49], 0
	v_mfma_f32_16x16x32_bf16 v[58:61], v[86:89], v[54:57], v[58:61]
	ds_read_b128 v[94:97], v1 offset:8192
	ds_read_b128 v[86:89], v1 offset:12544
	ds_read_b128 v[98:101], v1 offset:8256
	ds_read_b128 v[102:105], v1 offset:12608
	ds_read_b128 v[106:109], v1 offset:8320
	ds_read_b128 v[66:69], v1 offset:12672
	ds_read_b128 v[62:65], v1 offset:8384
	ds_read_b128 v[82:85], v1 offset:12736
	s_add_i32 s1, s42, s0
	v_mov_b32_e32 v250, s1
	ds_read_b128 v[246:249], v250
	s_waitcnt lgkmcnt(0)
.LBB0_627:
	s_add_i32 s1, s42, s0
	v_mov_b32_e32 v111, s1
	ds_read_b128 v[116:119], v111 offset:16
	ds_read_b128 v[230:233], v111 offset:32
	ds_read_b128 v[234:237], v111 offset:48
	s_waitcnt lgkmcnt(5)
	v_pk_mul_f32 v[120:121], v[180:181], v[246:247] op_sel:[0,1]
	v_pk_fma_f32 v[112:113], v[178:179], v[246:247], v[120:121] op_sel_hi:[1,0,1]
	v_pk_fma_f32 v[112:113], v[182:183], v[248:249], v[112:113] op_sel_hi:[1,0,1]
	v_pk_fma_f32 v[112:113], v[184:185], v[248:249], v[112:113] op_sel:[0,1,0]
	s_add_i32 s1, s42, s0
	s_add_i32 s1, s1, 64
	v_mov_b32_e32 v250, s1
	ds_read_b128 v[246:249], v250
	s_waitcnt lgkmcnt(3)
	v_pk_fma_f32 v[112:113], v[186:187], v[116:117], v[112:113] op_sel_hi:[1,0,1]
	v_pk_fma_f32 v[112:113], v[188:189], v[116:117], v[112:113] op_sel:[0,1,0]
	s_waitcnt lgkmcnt(2)
	v_pk_fma_f32 v[112:113], v[190:191], v[118:119], v[112:113] op_sel_hi:[1,0,1]
	v_pk_fma_f32 v[112:113], v[192:193], v[118:119], v[112:113] op_sel:[0,1,0]
	v_pk_mul_f32 v[114:115], v[196:197], v[230:231] op_sel:[0,1]
	v_pk_fma_f32 v[114:115], v[194:195], v[230:231], v[114:115] op_sel_hi:[1,0,1]
	v_pk_fma_f32 v[114:115], v[198:199], v[232:233], v[114:115] op_sel_hi:[1,0,1]
	v_pk_fma_f32 v[114:115], v[200:201], v[232:233], v[114:115] op_sel:[0,1,0]
	s_waitcnt lgkmcnt(1)
	v_mov_b32_e32 v116, v237
	v_pk_fma_f32 v[114:115], v[202:203], v[234:235], v[114:115] op_sel_hi:[1,0,1]
	v_pk_fma_f32 v[114:115], v[204:205], v[234:235], v[114:115] op_sel:[0,1,0]
	v_pk_fma_f32 v[114:115], v[206:207], v[236:237], v[114:115] op_sel_hi:[1,0,1]
	v_pk_fma_f32 v[114:115], v[176:177], v[116:117], v[114:115] op_sel_hi:[1,0,1]
	v_pk_add_f32 v[112:113], v[112:113], v[114:115]
	v_pk_fma_f32 v[112:113], v[128:129], v[174:175], v[112:113] op_sel:[0,1,0] op_sel_hi:[1,0,1]
	v_pk_fma_f32 v[174:175], v[126:127], v[174:175], v[112:113]
	v_cvt_pk_bf16_f32 v111, v174, s0
	v_cvt_pk_bf16_f32 v112, v175, s0
	s_add_i32 s0, s0, 64
	ds_write_b16 v110, v111
	ds_write_b16 v110, v112 offset:128
	v_add_u32_e32 v110, 0x110, v110
	s_cmpk_lg_i32 s0, 0x800
	s_cbranch_scc1 .LBB0_627
	v_cvt_pk_bf16_f32 v42, -v42, -v43
	v_cvt_pk_bf16_f32 v43, -v44, -v45
	v_cvt_pk_bf16_f32 v44, -v38, -v39
	v_cvt_pk_bf16_f32 v45, -v40, -v41
	v_mfma_f32_16x16x32_bf16 v[86:89], v[86:89], v[46:49], 0
	s_mov_b32 s0, 0
	v_mfma_f32_16x16x32_bf16 v[38:41], v[78:81], v[42:45], v[90:93]
	v_mfma_f32_16x16x32_bf16 v[78:81], v[94:97], v[46:49], 0
	v_mfma_f32_16x16x32_bf16 v[78:81], v[98:101], v[54:57], v[78:81]
	v_mfma_f32_16x16x32_bf16 v[78:81], v[106:109], v[50:53], v[78:81]
	v_mfma_f32_16x16x32_bf16 v[86:89], v[102:105], v[54:57], v[86:89]
	ds_read_b128 v[94:97], v1 offset:8192
	ds_read_b128 v[90:93], v1 offset:12544
	ds_read_b128 v[102:105], v1 offset:8256
	ds_read_b128 v[98:101], v1 offset:12608
	ds_read_b128 v[110:113], v1 offset:8320
	ds_read_b128 v[106:109], v1 offset:12672
	ds_read_b128 v[118:121], v1 offset:8384
	ds_read_b128 v[114:117], v1 offset:12736
	s_add_i32 s1, s43, s0
	v_mov_b32_e32 v250, s1
	ds_read_b128 v[246:249], v250
	s_waitcnt lgkmcnt(0)
; DI void s5_disc(const S5P& P, int dir, int g, int p, float& lr, float& li, f32x2 (&bb)[16]) {
;     const float dt = expf(P.log_dt[dir * 64 + g]); const float are = P.a_re[(dir * 64 + g) * 64 + p], aim = P.a_im[(dir * 64 + g) * 64 + p];
;     const float mag = expf(dt * are); lr = mag * cosf(dt * aim); li = mag * sinf(dt * aim);
.LBB0_629:
	s_add_i32 s1, s43, s0
	v_mov_b32_e32 v158, s1
	ds_read_b128 v[234:237], v158 offset:16
	ds_read_b128 v[238:241], v158 offset:32
	ds_read_b128 v[242:245], v158 offset:48
	s_waitcnt lgkmcnt(5)
	v_pk_mul_f32 v[158:159], v[180:181], v[246:247] op_sel:[0,1]
	v_pk_fma_f32 v[158:159], v[178:179], v[246:247], v[158:159] op_sel_hi:[1,0,1]
	v_pk_fma_f32 v[158:159], v[182:183], v[248:249], v[158:159] op_sel_hi:[1,0,1]
	s_waitcnt lgkmcnt(1)
	v_pk_fma_f32 v[158:159], v[184:185], v[248:249], v[158:159] op_sel:[0,1,0]
	s_add_i32 s1, s43, s0
	s_add_i32 s1, s1, 64
	v_mov_b32_e32 v250, s1
	ds_read_b128 v[246:249], v250
	v_pk_fma_f32 v[158:159], v[186:187], v[234:235], v[158:159] op_sel_hi:[1,0,1]
	v_pk_fma_f32 v[158:159], v[188:189], v[234:235], v[158:159] op_sel:[0,1,0]
	v_pk_fma_f32 v[158:159], v[190:191], v[236:237], v[158:159] op_sel_hi:[1,0,1]
	v_pk_fma_f32 v[158:159], v[192:193], v[236:237], v[158:159] op_sel:[0,1,0]
	v_pk_mul_f32 v[160:161], v[196:197], v[238:239] op_sel:[0,1]
	v_pk_fma_f32 v[160:161], v[194:195], v[238:239], v[160:161] op_sel_hi:[1,0,1]
	v_pk_fma_f32 v[160:161], v[198:199], v[240:241], v[160:161] op_sel_hi:[1,0,1]
	v_pk_fma_f32 v[160:161], v[200:201], v[240:241], v[160:161] op_sel:[0,1,0]
	s_waitcnt lgkmcnt(1)
	v_mov_b32_e32 v230, v245
	v_pk_fma_f32 v[160:161], v[202:203], v[242:243], v[160:161] op_sel_hi:[1,0,1]
	v_pk_fma_f32 v[160:161], v[204:205], v[242:243], v[160:161] op_sel:[0,1,0]
	v_pk_fma_f32 v[160:161], v[206:207], v[244:245], v[160:161] op_sel_hi:[1,0,1]
	v_pk_fma_f32 v[160:161], v[176:177], v[230:231], v[160:161] op_sel_hi:[1,0,1]
	v_pk_add_f32 v[158:159], v[158:159], v[160:161]
	v_pk_fma_f32 v[158:159], v[128:129], v[174:175], v[158:159] op_sel:[0,1,0] op_sel_hi:[1,0,1]
	v_pk_fma_f32 v[174:175], v[126:127], v[174:175], v[158:159]
	v_cvt_pk_bf16_f32 v158, v174, s0
	v_cvt_pk_bf16_f32 v159, v175, s0
	s_add_i32 s0, s0, 64
	ds_write_b16 v2, v158
	ds_write_b16 v2, v159 offset:128
	v_add_u32_e32 v2, 0x110, v2
	s_cmpk_eq_i32 s0, 0x800
	s_cbranch_scc0 .LBB0_629
	v_mfma_f32_16x16x32_bf16 v[58:61], v[70:73], v[50:53], v[58:61]
	v_readlane_b32 s72, v252, 4
	v_readlane_b32 s84, v252, 16
	v_readlane_b32 s85, v252, 17
	v_mfma_f32_16x16x32_bf16 v[66:69], v[66:69], v[50:53], v[86:89]
	v_readlane_b32 s82, v252, 14
	v_readlane_b32 s83, v252, 15
	s_mov_b32 s0, 0x3fb8aa3b
	v_mfma_f32_16x16x32_bf16 v[62:65], v[62:65], v[42:45], v[78:81]
	v_readlane_b32 s73, v252, 5
	v_readlane_b32 s74, v252, 6
	v_readlane_b32 s75, v252, 7
	v_mfma_f32_16x16x32_bf16 v[58:61], v[74:77], v[42:45], v[58:61]
	v_readlane_b32 s76, v252, 8
	v_readlane_b32 s77, v252, 9
	v_readlane_b32 s78, v252, 10
	v_mfma_f32_16x16x32_bf16 v[66:69], v[82:85], v[42:45], v[66:69]
	ds_read_b128 v[78:81], v1 offset:8192
	ds_read_b128 v[82:85], v1 offset:8256
	v_readlane_b32 s79, v252, 11
	v_readlane_b32 s80, v252, 12
	v_mfma_f32_16x16x32_bf16 v[74:77], v[90:93], v[46:49], 0
	ds_read_b128 v[86:89], v1 offset:12544
	ds_read_b128 v[90:93], v1 offset:12608
	global_load_dword v2, v3, s[22:23] offset:256
	v_readlane_b32 s81, v252, 13
	s_waitcnt lgkmcnt(1)
	v_mfma_f32_16x16x32_bf16 v[86:89], v[86:89], v[46:49], 0
	v_readlane_b32 s86, v252, 18
	v_readlane_b32 s87, v252, 19
	v_mfma_f32_16x16x32_bf16 v[70:73], v[94:97], v[46:49], 0
	ds_read_b128 v[94:97], v1 offset:8320
	v_mfma_f32_16x16x32_bf16 v[78:81], v[78:81], v[46:49], 0
	s_waitcnt lgkmcnt(1)
	v_mfma_f32_16x16x32_bf16 v[86:89], v[90:93], v[54:57], v[86:89]
	v_add_u32_e32 v90, 0x1000, v124
	v_ashrrev_i32_e32 v91, 31, v90
	v_lshlrev_b64 v[90:91], 2, v[90:91]
	v_lshl_add_u64 v[92:93], s[84:85], 0, v[90:91]
	v_mfma_f32_16x16x32_bf16 v[70:73], v[102:105], v[54:57], v[70:73]
	v_lshl_add_u64 v[90:91], s[82:83], 0, v[90:91]
	v_mfma_f32_16x16x32_bf16 v[74:77], v[98:101], v[54:57], v[74:77]
	v_mfma_f32_16x16x32_bf16 v[78:81], v[82:85], v[54:57], v[78:81]
	ds_read_b128 v[82:85], v1 offset:8384
	ds_read_b128 v[98:101], v1 offset:12672
	ds_read_b128 v[102:105], v1 offset:12736
	global_load_dword v93, v[92:93], off
	s_nop 0
	global_load_dword v92, v[90:91], off
	s_waitcnt lgkmcnt(3)
	v_mfma_f32_16x16x32_bf16 v[78:81], v[94:97], v[50:53], v[78:81]
	s_waitcnt lgkmcnt(2)
	v_mfma_f32_16x16x32_bf16 v[78:81], v[82:85], v[42:45], v[78:81]
	s_waitcnt vmcnt(2)
	v_mul_f32_e32 v82, 0x3fb8aa3b, v2
	v_fma_f32 v83, v2, s0, -v82
	v_rndne_f32_e32 v84, v82
	v_fmac_f32_e32 v83, 0x32a5705f, v2
	v_sub_f32_e32 v82, v82, v84
	v_add_f32_e32 v82, v82, v83
	s_waitcnt lgkmcnt(1)
	v_mfma_f32_16x16x32_bf16 v[86:89], v[98:101], v[50:53], v[86:89]
	v_cvt_i32_f32_e32 v90, v84
	v_exp_f32_e32 v91, v82
	s_mov_b32 s0, 0xc2ce8ed0
	v_mfma_f32_16x16x32_bf16 v[70:73], v[110:113], v[50:53], v[70:73]
	v_cmp_ngt_f32_e32 vcc, s0, v2
	s_mov_b32 s0, 0x42b17218
	v_mfma_f32_16x16x32_bf16 v[74:77], v[106:109], v[50:53], v[74:77]
	s_waitcnt lgkmcnt(0)
	v_mfma_f32_16x16x32_bf16 v[82:85], v[102:105], v[42:45], v[86:89]
	v_mfma_f32_16x16x32_bf16 v[70:73], v[118:121], v[42:45], v[70:73]
	s_nop 1
	v_ldexp_f32 v86, v91, v90
	v_cndmask_b32_e32 v86, 0, v86, vcc
	v_cmp_nlt_f32_e32 vcc, s0, v2
	v_mfma_f32_16x16x32_bf16 v[74:77], v[114:117], v[42:45], v[74:77]
	s_brev_b32 s0, 18
	v_cndmask_b32_e32 v86, v219, v86, vcc
	s_waitcnt vmcnt(1)
	v_mul_f32_e32 v87, v86, v93
	v_and_b32_e32 v88, 0x7fffffff, v87
	v_cmp_nlt_f32_e64 s[22:23], |v87|, s0
	s_and_saveexec_b64 s[0:1], s[22:23]
	s_xor_b64 s[24:25], exec, s[0:1]
	s_cbranch_execz .LBB0_632
; DI void s5_disc(const S5P& P, int dir, int g, int p, float& lr, float& li, f32x2 (&bb)[16]) {
;     const float dt = expf(P.log_dt[dir * 64 + g]); const float are = P.a_re[(dir * 64 + g) * 64 + p], aim = P.a_im[(dir * 64 + g) * 64 + p];
;     const float mag = expf(dt * are); lr = mag * cosf(dt * aim); li = mag * sinf(dt * aim);
	v_lshrrev_b32_e32 v2, 23, v88
	v_add_u32_e32 v2, 0xffffff88, v2
	v_cmp_lt_u32_e32 vcc, 63, v2
	s_mov_b32 s10, 0xfe5163ab
	s_nop 0
	v_cndmask_b32_e32 v89, 0, v220, vcc
	v_add_u32_e32 v2, v89, v2
	v_cmp_lt_u32_e64 s[0:1], 31, v2
	s_nop 1
	v_cndmask_b32_e64 v89, 0, v221, s[0:1]
	v_add_u32_e32 v2, v89, v2
	v_cmp_lt_u32_e64 s[8:9], 31, v2
	s_nop 1
	v_cndmask_b32_e64 v89, 0, v221, s[8:9]
	v_add_u32_e32 v89, v89, v2
	v_and_b32_e32 v2, 0x7fffff, v88
	v_or_b32_e32 v104, 0x800000, v2
	v_mad_u64_u32 v[90:91], s[10:11], v104, s10, 0
	v_mov_b32_e32 v2, v91
	s_mov_b32 s10, 0x3c439041
	v_mad_u64_u32 v[94:95], s[10:11], v104, s10, v[2:3]
	v_mov_b32_e32 v2, v95
	s_mov_b32 s10, 0xdb629599
	v_mad_u64_u32 v[96:97], s[10:11], v104, s10, v[2:3]
	v_mov_b32_e32 v2, v97
	s_mov_b32 s10, 0xf534ddc0
	v_mad_u64_u32 v[98:99], s[10:11], v104, s10, v[2:3]
	v_mov_b32_e32 v2, v99
	s_mov_b32 s10, 0xfc2757d1
	v_mad_u64_u32 v[100:101], s[10:11], v104, s10, v[2:3]
	v_mov_b32_e32 v2, v101
	s_mov_b32 s10, 0x4e441529
	v_mad_u64_u32 v[102:103], s[10:11], v104, s10, v[2:3]
	v_mov_b32_e32 v2, v103
	s_mov_b32 s10, 0xa2f9836e
	v_mad_u64_u32 v[104:105], s[10:11], v104, s10, v[2:3]
	v_cndmask_b32_e32 v91, v102, v98, vcc
	v_cndmask_b32_e32 v2, v104, v100, vcc
	v_cndmask_b32_e32 v97, v105, v102, vcc
	v_cndmask_b32_e64 v95, v2, v91, s[0:1]
	v_cndmask_b32_e64 v2, v97, v2, s[0:1]
	v_cndmask_b32_e32 v97, v100, v96, vcc
	v_cndmask_b32_e64 v91, v91, v97, s[0:1]
	v_sub_u32_e32 v99, 32, v89
	v_cmp_eq_u32_e64 s[10:11], 0, v89
	v_cndmask_b32_e32 v89, v98, v94, vcc
	v_cndmask_b32_e64 v2, v2, v95, s[8:9]
	v_cndmask_b32_e64 v95, v95, v91, s[8:9]
	v_cndmask_b32_e64 v94, v97, v89, s[0:1]
	v_alignbit_b32 v100, v2, v95, v99
	v_cndmask_b32_e64 v91, v91, v94, s[8:9]
	v_cndmask_b32_e64 v2, v100, v2, s[10:11]
	v_alignbit_b32 v97, v95, v91, v99
	v_cndmask_b32_e32 v90, v96, v90, vcc
	v_cndmask_b32_e64 v95, v97, v95, s[10:11]
	v_bfe_u32 v100, v2, 29, 1
	v_cndmask_b32_e64 v89, v89, v90, s[0:1]
	v_alignbit_b32 v97, v2, v95, 30
	v_sub_u32_e32 v101, 0, v100
	v_cndmask_b32_e64 v89, v94, v89, s[8:9]
	v_xor_b32_e32 v97, v97, v101
	v_alignbit_b32 v90, v91, v89, v99
	v_cndmask_b32_e64 v90, v90, v91, s[10:11]
	v_ffbh_u32_e32 v94, v97
	v_alignbit_b32 v91, v95, v90, 30
	v_min_u32_e32 v94, 32, v94
	v_alignbit_b32 v89, v90, v89, 30
	v_xor_b32_e32 v91, v91, v101
	v_sub_u32_e32 v95, 31, v94
	v_xor_b32_e32 v89, v89, v101
	v_alignbit_b32 v96, v97, v91, v95
	v_alignbit_b32 v89, v91, v89, v95
	v_alignbit_b32 v90, v96, v89, 9
	v_ffbh_u32_e32 v91, v90
	v_min_u32_e32 v91, 32, v91
	v_lshrrev_b32_e32 v98, 29, v2
	v_not_b32_e32 v95, v91
	v_alignbit_b32 v89, v90, v89, v95
	v_lshlrev_b32_e32 v90, 31, v98
	v_or_b32_e32 v95, 0x33000000, v90
	v_add_lshl_u32 v91, v91, v94, 23
	v_lshrrev_b32_e32 v89, 9, v89
	v_sub_u32_e32 v91, v95, v91
	v_or_b32_e32 v90, 0.5, v90
	v_lshlrev_b32_e32 v94, 23, v94
	v_or_b32_e32 v89, v91, v89
	v_lshrrev_b32_e32 v91, 9, v96
	v_sub_u32_e32 v90, v90, v94
	v_or_b32_e32 v90, v91, v90
	v_mul_f32_e32 v91, 0x3fc90fda, v90
	s_mov_b32 s0, 0x3fc90fda
	v_fma_f32 v94, v90, s0, -v91
	v_fmac_f32_e32 v94, 0x33a22168, v90
	v_fmac_f32_e32 v94, 0x3fc90fda, v89
	v_lshrrev_b32_e32 v2, 30, v2
	v_add_f32_e32 v90, v91, v94
	v_add_u32_e32 v89, v100, v2
	s_andn2_saveexec_b64 s[0:1], s[24:25]
	s_cbranch_execz .LBB0_634
	s_branch .LBB0_633

; DI void s5_disc(const S5P& P, int dir, int g, int p, float& lr, float& li, f32x2 (&bb)[16]) {
;     ...
;     const float den = are * are + aim * aim, nr = lr - 1.0f; const float cr = (nr * are + li * aim) / den, ci = (li * are - nr * aim) / den;
;     const f32x4* br = (const f32x4*)(P.b_re + (size_t)(g * 64 + p) * 16); const f32x4* bi = (const f32x4*)(P.b_im + (size_t)(g * 64 + p) * 16);
; #pragma unroll
;     for (int q = 0; q < 4; ++q) { const f32x4 r = br[q], i = bi[q];
; #pragma unroll
;         for (int e = 0; e < 4; ++e) bb[4 * q + e] = (f32x2){cr * r[e] - ci * i[e], cr * i[e] + ci * r[e]}; }
.LBB0_650:
	v_add_f32_e32 v88, -1.0, v86
	v_mov_b32_e32 v2, v93
	v_pk_mul_f32 v[94:95], v[92:93], v[92:93]
	v_pk_mul_f32 v[96:97], v[2:3], v[88:89] op_sel:[0,1] op_sel_hi:[0,0]
	v_pk_fma_f32 v[98:99], v[92:93], v[88:89], v[96:97]
	v_pk_fma_f32 v[92:93], v[92:93], v[88:89], v[96:97] op_sel_hi:[0,1,1] neg_lo:[0,0,1] neg_hi:[0,0,1]
	v_pk_add_f32 v[94:95], v[94:95], v[94:95] op_sel:[0,1] op_sel_hi:[0,1]
	v_div_scale_f32 v2, s[0:1], v95, v95, v93
	v_rcp_f32_e32 v87, v2
	s_nop 0
	v_fma_f32 v88, -v2, v87, 1.0
	v_fmac_f32_e32 v87, v88, v87
	v_div_scale_f32 v88, vcc, v93, v95, v93
	v_mul_f32_e32 v92, v88, v87
	v_fma_f32 v96, -v2, v92, v88
	v_fmac_f32_e32 v92, v96, v87
	v_fma_f32 v2, -v2, v92, v88
	v_div_fmas_f32 v2, v2, v87, v92
	v_div_fixup_f32 v117, v2, v95, v93
	v_div_scale_f32 v2, s[0:1], v94, v94, v98
	v_rcp_f32_e32 v87, v2
	s_mov_b32 s0, 0
	v_fma_f32 v88, -v2, v87, 1.0
	v_fmac_f32_e32 v87, v88, v87
	v_div_scale_f32 v88, vcc, v98, v94, v98
	v_mul_f32_e32 v92, v88, v87
	v_fma_f32 v93, -v2, v92, v88
	v_fmac_f32_e32 v92, v93, v87
	v_fma_f32 v2, -v2, v92, v88
	v_div_fmas_f32 v2, v2, v87, v92
	v_div_fixup_f32 v116, v2, v94, v98
	v_pk_mul_f32 v[94:95], v[134:135], v[116:117]
	v_pk_mul_f32 v[96:97], v[138:139], v[116:117]
	v_pk_fma_f32 v[92:93], v[130:131], v[116:117], v[94:95] op_sel:[0,0,1] op_sel_hi:[1,1,0] neg_lo:[0,0,1] neg_hi:[0,0,1]
	v_pk_fma_f32 v[94:95], v[130:131], v[116:117], v[94:95] op_sel:[0,0,1] op_sel_hi:[1,1,0]
	v_pk_mul_f32 v[98:99], v[140:141], v[116:117]
	v_mov_b32_e32 v93, v95
	v_pk_fma_f32 v[94:95], v[132:133], v[116:117], v[96:97] op_sel:[0,0,1] op_sel_hi:[1,1,0] neg_lo:[0,0,1] neg_hi:[0,0,1]
	v_pk_fma_f32 v[96:97], v[132:133], v[116:117], v[96:97] op_sel:[0,0,1] op_sel_hi:[1,1,0]
	v_pk_mul_f32 v[36:37], v[36:37], v[116:117]
	v_mov_b32_e32 v95, v97
	v_pk_fma_f32 v[96:97], v[136:137], v[116:117], v[98:99] op_sel:[0,0,1] op_sel_hi:[1,1,0] neg_lo:[0,0,1] neg_hi:[0,0,1]
	v_pk_fma_f32 v[98:99], v[136:137], v[116:117], v[98:99] op_sel:[0,0,1] op_sel_hi:[1,1,0]
	v_pk_mul_f32 v[26:27], v[26:27], v[116:117]
	v_mov_b32_e32 v97, v99
	v_pk_mul_f32 v[98:99], v[34:35], v[116:117]
	v_pk_mul_f32 v[18:19], v[18:19], v[116:117]
	v_pk_fma_f32 v[34:35], v[30:31], v[116:117], v[98:99] op_sel:[0,0,1] op_sel_hi:[1,1,0] neg_lo:[0,0,1] neg_hi:[0,0,1]
	v_pk_fma_f32 v[30:31], v[30:31], v[116:117], v[98:99] op_sel:[0,0,1] op_sel_hi:[1,1,0]
	v_pk_fma_f32 v[104:105], v[14:15], v[116:117], v[18:19] op_sel:[0,0,1] op_sel_hi:[1,1,0] neg_lo:[0,0,1] neg_hi:[0,0,1]
	v_mov_b32_e32 v35, v31
	v_pk_fma_f32 v[30:31], v[32:33], v[116:117], v[36:37] op_sel:[0,0,1] op_sel_hi:[1,1,0] neg_lo:[0,0,1] neg_hi:[0,0,1]
	v_pk_fma_f32 v[32:33], v[32:33], v[116:117], v[36:37] op_sel:[0,0,1] op_sel_hi:[1,1,0]
	v_pk_mul_f32 v[36:37], v[144:145], v[116:117]
	v_mov_b32_e32 v31, v33
	v_pk_fma_f32 v[32:33], v[142:143], v[116:117], v[36:37] op_sel:[0,0,1] op_sel_hi:[1,1,0] neg_lo:[0,0,1] neg_hi:[0,0,1]
	v_pk_fma_f32 v[36:37], v[142:143], v[116:117], v[36:37] op_sel:[0,0,1] op_sel_hi:[1,1,0]
	v_pk_fma_f32 v[14:15], v[14:15], v[116:117], v[18:19] op_sel:[0,0,1] op_sel_hi:[1,1,0]
	v_mov_b32_e32 v33, v37
	v_pk_fma_f32 v[36:37], v[22:23], v[116:117], v[26:27] op_sel:[0,0,1] op_sel_hi:[1,1,0] neg_lo:[0,0,1] neg_hi:[0,0,1]
	v_pk_fma_f32 v[22:23], v[22:23], v[116:117], v[26:27] op_sel:[0,0,1] op_sel_hi:[1,1,0]
	v_mov_b32_e32 v105, v15
	v_mov_b32_e32 v37, v23
	v_pk_mul_f32 v[22:23], v[148:149], v[116:117]
	v_pk_mul_f32 v[14:15], v[168:169], v[116:117]
	v_pk_fma_f32 v[98:99], v[146:147], v[116:117], v[22:23] op_sel:[0,0,1] op_sel_hi:[1,1,0] neg_lo:[0,0,1] neg_hi:[0,0,1]
	v_pk_fma_f32 v[22:23], v[146:147], v[116:117], v[22:23] op_sel:[0,0,1] op_sel_hi:[1,1,0]
	v_pk_fma_f32 v[106:107], v[166:167], v[116:117], v[14:15] op_sel:[0,0,1] op_sel_hi:[1,1,0] neg_lo:[0,0,1] neg_hi:[0,0,1]
	v_pk_fma_f32 v[14:15], v[166:167], v[116:117], v[14:15] op_sel:[0,0,1] op_sel_hi:[1,1,0]
	v_mov_b32_e32 v99, v23
	v_pk_mul_f32 v[22:23], v[28:29], v[116:117]
	v_mov_b32_e32 v107, v15
	v_pk_mul_f32 v[14:15], v[20:21], v[116:117]
	v_pk_mul_f32 v[10:11], v[10:11], v[116:117]
	v_pk_fma_f32 v[100:101], v[24:25], v[116:117], v[22:23] op_sel:[0,0,1] op_sel_hi:[1,1,0] neg_lo:[0,0,1] neg_hi:[0,0,1]
	v_pk_fma_f32 v[22:23], v[24:25], v[116:117], v[22:23] op_sel:[0,0,1] op_sel_hi:[1,1,0]
	v_pk_fma_f32 v[108:109], v[16:17], v[116:117], v[14:15] op_sel:[0,0,1] op_sel_hi:[1,1,0] neg_lo:[0,0,1] neg_hi:[0,0,1]
	v_pk_fma_f32 v[14:15], v[16:17], v[116:117], v[14:15] op_sel:[0,0,1] op_sel_hi:[1,1,0]
	v_pk_fma_f32 v[112:113], v[6:7], v[116:117], v[10:11] op_sel:[0,0,1] op_sel_hi:[1,1,0] neg_lo:[0,0,1] neg_hi:[0,0,1]
	v_pk_fma_f32 v[6:7], v[6:7], v[116:117], v[10:11] op_sel:[0,0,1] op_sel_hi:[1,1,0]
	v_mov_b32_e32 v101, v23
	v_pk_mul_f32 v[22:23], v[164:165], v[116:117]
	v_mov_b32_e32 v109, v15
	v_pk_mul_f32 v[14:15], v[172:173], v[116:117]
	v_mov_b32_e32 v113, v7
	v_pk_mul_f32 v[6:7], v[12:13], v[116:117]
	v_pk_fma_f32 v[102:103], v[162:163], v[116:117], v[22:23] op_sel:[0,0,1] op_sel_hi:[1,1,0] neg_lo:[0,0,1] neg_hi:[0,0,1]
	v_pk_fma_f32 v[22:23], v[162:163], v[116:117], v[22:23] op_sel:[0,0,1] op_sel_hi:[1,1,0]
	v_pk_fma_f32 v[110:111], v[170:171], v[116:117], v[14:15] op_sel:[0,0,1] op_sel_hi:[1,1,0] neg_lo:[0,0,1] neg_hi:[0,0,1]
	v_pk_fma_f32 v[14:15], v[170:171], v[116:117], v[14:15] op_sel:[0,0,1] op_sel_hi:[1,1,0]
	v_pk_fma_f32 v[114:115], v[8:9], v[116:117], v[6:7] op_sel:[0,0,1] op_sel_hi:[1,1,0] neg_lo:[0,0,1] neg_hi:[0,0,1]
	v_pk_fma_f32 v[6:7], v[8:9], v[116:117], v[6:7] op_sel:[0,0,1] op_sel_hi:[1,1,0]
	v_mov_b32_e32 v103, v23
	v_mov_b32_e32 v111, v15
	v_mov_b32_e32 v115, v7
	v_mov_b32_e32 v87, v86
	v_xor_b32_e32 v88, 0x80000000, v89
	v_add_u32_e32 v2, s66, v152
	s_add_i32 s1, s53, s0
	v_mov_b32_e32 v250, s1
	ds_read_b128 v[246:249], v250
	s_waitcnt lgkmcnt(0)
; #define LAS __attribute__((address_space(3)))
; DI unsigned pk2(float lo, float hi) { return pg8::cvt_pk_bf16(lo, hi); }
; DI f32x4 mfma16(bf16x8 a, bf16x8 b, f32x4 c) { return __builtin_amdgcn_mfma_f32_16x16x32_bf16(a, b, c, 0, 0, 0); }
; template <int DIRN, int SUB> DI void s5_subtile(const LAS float* UF, LAS bf16* XT, float lr, float li, const f32x2 (&bb)[16], f32x2& x,
;                                                 const bf16x8 (&bfr)[4], f32x4& acc0, f32x4& acc1, int lane) {
; #pragma unroll 1
;     for (int i = 0; i < 32; ++i) { const int r = DIRN ? 31 - i : i;
;         x = s5_step((const LAS f32x4*)(UF + (32 * SUB + r) * 16), bb, lr, li, x);
;         const unsigned pkd = pk2(x.x, x.y); XT[r * 136 + lane] = (bf16)(pkd & 0xffffu); XT[r * 136 + 64 + lane] = (bf16)(pkd >> 16); }
; #pragma unroll
;     for (int ks = 0; ks < 4; ++ks) { const bf16x8 a0 = *(const LAS bf16x8*)(XT + (lane & 15) * 136 + 32 * ks + 8 * (lane >> 4)), a1 = *(const LAS bf16x8*)(XT + (16 + (lane & 15)) * 136 + 32 * ks + 8 * (lane >> 4));
;         acc0 = mfma16(a0, bfr[ks], acc0); acc1 = mfma16(a1, bfr[ks], acc1); }
.LBB0_651:
	s_add_i32 s1, s53, s0
	v_mov_b32_e32 v18, s1
	ds_read_b128 v[10:13], v18 offset:16
	ds_read_b128 v[14:17], v18 offset:32
	ds_read_b128 v[18:21], v18 offset:48
	s_waitcnt lgkmcnt(5)
	v_pk_mul_f32 v[22:23], v[96:97], v[246:247] op_sel:[0,1]
	v_pk_fma_f32 v[6:7], v[94:95], v[246:247], v[22:23] op_sel_hi:[1,0,1]
	v_pk_fma_f32 v[6:7], v[34:35], v[248:249], v[6:7] op_sel_hi:[1,0,1]
	v_pk_fma_f32 v[6:7], v[30:31], v[248:249], v[6:7] op_sel:[0,1,0]
	s_add_i32 s1, s53, s0
	s_sub_i32 s1, s1, 64
	v_mov_b32_e32 v250, s1
	ds_read_b128 v[246:249], v250
	s_waitcnt lgkmcnt(3)
	v_pk_fma_f32 v[6:7], v[32:33], v[10:11], v[6:7] op_sel_hi:[1,0,1]
	v_pk_fma_f32 v[6:7], v[36:37], v[10:11], v[6:7] op_sel:[0,1,0]
	s_waitcnt lgkmcnt(2)
	v_pk_fma_f32 v[6:7], v[98:99], v[12:13], v[6:7] op_sel_hi:[1,0,1]
	v_pk_fma_f32 v[6:7], v[100:101], v[12:13], v[6:7] op_sel:[0,1,0]
	v_pk_mul_f32 v[8:9], v[104:105], v[14:15] op_sel:[0,1]
	v_pk_fma_f32 v[8:9], v[102:103], v[14:15], v[8:9] op_sel_hi:[1,0,1]
	v_pk_fma_f32 v[8:9], v[106:107], v[16:17], v[8:9] op_sel_hi:[1,0,1]
	v_pk_fma_f32 v[8:9], v[108:109], v[16:17], v[8:9] op_sel:[0,1,0]
	s_waitcnt lgkmcnt(1)
	v_mov_b32_e32 v10, v21
	v_pk_fma_f32 v[8:9], v[110:111], v[18:19], v[8:9] op_sel_hi:[1,0,1]
	v_pk_fma_f32 v[8:9], v[112:113], v[18:19], v[8:9] op_sel:[0,1,0]
	v_pk_fma_f32 v[8:9], v[114:115], v[20:21], v[8:9] op_sel_hi:[1,0,1]
	v_pk_fma_f32 v[8:9], v[92:93], v[10:11], v[8:9] op_sel_hi:[1,0,1]
	v_pk_add_f32 v[6:7], v[6:7], v[8:9]
	v_pk_fma_f32 v[6:7], v[88:89], v[90:91], v[6:7] op_sel:[0,1,0] op_sel_hi:[1,0,1]
	v_pk_fma_f32 v[90:91], v[86:87], v[90:91], v[6:7]
	v_cvt_pk_bf16_f32 v6, v90, s0
	v_cvt_pk_bf16_f32 v7, v91, s0
	s_sub_i32 s0, s0, 64
	ds_write_b16 v2, v6
	ds_write_b16 v2, v7 offset:128
	v_add_u32_e32 v2, 0xfffffef0, v2
	s_cmpk_lg_i32 s0, 0xf800
	s_cbranch_scc1 .LBB0_651
	ds_read_b128 v[6:9], v1 offset:8192
	ds_read_b128 v[10:13], v1 offset:12544
	ds_read_b128 v[14:17], v1 offset:8256
	ds_read_b128 v[18:21], v1 offset:12608
	v_add_u32_e32 v2, 0x40f0, v152
	s_movk_i32 s0, 0x17c0
	s_waitcnt lgkmcnt(3)
	v_mfma_f32_16x16x32_bf16 v[6:9], v[6:9], v[46:49], v[78:81]
	v_readlane_b32 s8, v253, 21
	v_readlane_b32 s9, v253, 22
	s_waitcnt lgkmcnt(2)
	v_mfma_f32_16x16x32_bf16 v[10:13], v[10:13], v[46:49], v[82:85]
	s_waitcnt lgkmcnt(1)
	v_mfma_f32_16x16x32_bf16 v[6:9], v[14:17], v[54:57], v[6:9]
	s_waitcnt lgkmcnt(0)
	v_mfma_f32_16x16x32_bf16 v[10:13], v[18:21], v[54:57], v[10:13]
	ds_read_b128 v[14:17], v1 offset:8320
	ds_read_b128 v[18:21], v1 offset:12672
	s_waitcnt lgkmcnt(1)
	v_mfma_f32_16x16x32_bf16 v[6:9], v[14:17], v[50:53], v[6:9]
	s_waitcnt lgkmcnt(0)
	v_mfma_f32_16x16x32_bf16 v[14:17], v[18:21], v[50:53], v[10:13]
	s_nop 2
	ds_read_b128 v[10:13], v1 offset:8384
	ds_read_b128 v[18:21], v1 offset:12736
	s_waitcnt lgkmcnt(1)
	v_mfma_f32_16x16x32_bf16 v[10:13], v[10:13], v[42:45], v[6:9]
	s_waitcnt lgkmcnt(0)
	v_mfma_f32_16x16x32_bf16 v[6:9], v[18:21], v[42:45], v[14:17]
	s_nop 2
	v_mov_b32_e32 v14, v2
	s_add_i32 s1, s49, s0
	v_mov_b32_e32 v250, s1
	ds_read_b128 v[246:249], v250
	s_waitcnt lgkmcnt(0)
.LBB0_653:
	s_add_i32 s1, s49, s0
	v_mov_b32_e32 v15, s1
	ds_read_b128 v[20:23], v15 offset:16
	ds_read_b128 v[24:27], v15 offset:32
	ds_read_b128 v[78:81], v15 offset:48
	s_waitcnt lgkmcnt(5)
	v_pk_mul_f32 v[28:29], v[96:97], v[246:247] op_sel:[0,1]
	v_pk_fma_f32 v[16:17], v[94:95], v[246:247], v[28:29] op_sel_hi:[1,0,1]
	v_pk_fma_f32 v[16:17], v[34:35], v[248:249], v[16:17] op_sel_hi:[1,0,1]
	v_pk_fma_f32 v[16:17], v[30:31], v[248:249], v[16:17] op_sel:[0,1,0]
	s_add_i32 s1, s49, s0
	s_sub_i32 s1, s1, 64
	v_mov_b32_e32 v250, s1
	ds_read_b128 v[246:249], v250
	s_waitcnt lgkmcnt(3)
	v_pk_fma_f32 v[16:17], v[32:33], v[20:21], v[16:17] op_sel_hi:[1,0,1]
	v_pk_fma_f32 v[16:17], v[36:37], v[20:21], v[16:17] op_sel:[0,1,0]
	s_waitcnt lgkmcnt(2)
	v_pk_fma_f32 v[16:17], v[98:99], v[22:23], v[16:17] op_sel_hi:[1,0,1]
	v_pk_fma_f32 v[16:17], v[100:101], v[22:23], v[16:17] op_sel:[0,1,0]
	v_pk_mul_f32 v[18:19], v[104:105], v[24:25] op_sel:[0,1]
	v_pk_fma_f32 v[18:19], v[102:103], v[24:25], v[18:19] op_sel_hi:[1,0,1]
	v_pk_fma_f32 v[18:19], v[106:107], v[26:27], v[18:19] op_sel_hi:[1,0,1]
	v_pk_fma_f32 v[18:19], v[108:109], v[26:27], v[18:19] op_sel:[0,1,0]
	s_waitcnt lgkmcnt(1)
	v_mov_b32_e32 v20, v81
	v_pk_fma_f32 v[18:19], v[110:111], v[78:79], v[18:19] op_sel_hi:[1,0,1]
	v_pk_fma_f32 v[18:19], v[112:113], v[78:79], v[18:19] op_sel:[0,1,0]
	v_pk_fma_f32 v[18:19], v[114:115], v[80:81], v[18:19] op_sel_hi:[1,0,1]
	v_pk_fma_f32 v[18:19], v[92:93], v[20:21], v[18:19] op_sel_hi:[1,0,1]
	v_pk_add_f32 v[16:17], v[16:17], v[18:19]
	v_pk_fma_f32 v[16:17], v[88:89], v[90:91], v[16:17] op_sel:[0,1,0] op_sel_hi:[1,0,1]
	v_pk_fma_f32 v[90:91], v[86:87], v[90:91], v[16:17]
	v_add_u32_e32 v17, s49, v14
	v_cvt_pk_bf16_f32 v15, v90, s0
	v_cvt_pk_bf16_f32 v16, v91, s0
	s_sub_i32 s0, s0, 64
	v_add_u32_e32 v14, 0xfffffef0, v14
	s_cmpk_lg_i32 s0, 0xfc0
	ds_write_b16 v17, v15
	ds_write_b16 v17, v16 offset:128
	s_cbranch_scc1 .LBB0_653
	ds_read_b128 v[14:17], v1 offset:8192
	ds_read_b128 v[22:25], v1 offset:8256
	ds_read_b128 v[18:21], v1 offset:12544
	s_movk_i32 s0, 0xfc0
	s_waitcnt lgkmcnt(2)
	v_mfma_f32_16x16x32_bf16 v[14:17], v[14:17], v[46:49], v[70:73]
	s_waitcnt lgkmcnt(1)
	v_mfma_f32_16x16x32_bf16 v[14:17], v[22:25], v[54:57], v[14:17]
	ds_read_b128 v[22:25], v1 offset:12608
	s_waitcnt lgkmcnt(1)
	v_mfma_f32_16x16x32_bf16 v[18:21], v[18:21], v[46:49], v[74:77]
	s_waitcnt lgkmcnt(0)
	v_mfma_f32_16x16x32_bf16 v[18:21], v[22:25], v[54:57], v[18:21]
	ds_read_b128 v[22:25], v1 offset:8320
	s_waitcnt lgkmcnt(0)
	v_mfma_f32_16x16x32_bf16 v[14:17], v[22:25], v[50:53], v[14:17]
	ds_read_b128 v[22:25], v1 offset:12672
	s_waitcnt lgkmcnt(0)
	v_mfma_f32_16x16x32_bf16 v[24:27], v[22:25], v[50:53], v[18:21]
	s_nop 2
	ds_read_b128 v[18:21], v1 offset:8384
	v_mov_b32_e32 v22, v2
	s_waitcnt lgkmcnt(0)
	v_mfma_f32_16x16x32_bf16 v[18:21], v[18:21], v[42:45], v[14:17]
	s_nop 2
	ds_read_b128 v[14:17], v1 offset:12736
	s_waitcnt lgkmcnt(0)
	v_mfma_f32_16x16x32_bf16 v[14:17], v[14:17], v[42:45], v[24:27]
	s_add_i32 s1, s49, s0
	v_mov_b32_e32 v250, s1
	ds_read_b128 v[246:249], v250
	s_waitcnt lgkmcnt(0)
; #define LAS __attribute__((address_space(3)))
; DI unsigned pk2(float lo, float hi) { return pg8::cvt_pk_bf16(lo, hi); }
; DI f32x4 mfma16(bf16x8 a, bf16x8 b, f32x4 c) { return __builtin_amdgcn_mfma_f32_16x16x32_bf16(a, b, c, 0, 0, 0); }
; template <int DIRN, int SUB> DI void s5_subtile(const LAS float* UF, LAS bf16* XT, float lr, float li, const f32x2 (&bb)[16], f32x2& x,
;                                                 const bf16x8 (&bfr)[4], f32x4& acc0, f32x4& acc1, int lane) {
; #pragma unroll 1
;     for (int i = 0; i < 32; ++i) { const int r = DIRN ? 31 - i : i;
;         x = s5_step((const LAS f32x4*)(UF + (32 * SUB + r) * 16), bb, lr, li, x);
;         const unsigned pkd = pk2(x.x, x.y); XT[r * 136 + lane] = (bf16)(pkd & 0xffffu); XT[r * 136 + 64 + lane] = (bf16)(pkd >> 16); }
; #pragma unroll
;     for (int ks = 0; ks < 4; ++ks) { const bf16x8 a0 = *(const LAS bf16x8*)(XT + (lane & 15) * 136 + 32 * ks + 8 * (lane >> 4)), a1 = *(const LAS bf16x8*)(XT + (16 + (lane & 15)) * 136 + 32 * ks + 8 * (lane >> 4));
;         acc0 = mfma16(a0, bfr[ks], acc0); acc1 = mfma16(a1, bfr[ks], acc1); }
.LBB0_655:
	s_add_i32 s1, s49, s0
	v_mov_b32_e32 v23, s1
	s_nop 0
	ds_read_b128 v[70:73], v23 offset:16
	ds_read_b128 v[74:77], v23 offset:32
	ds_read_b128 v[78:81], v23 offset:48
	s_waitcnt lgkmcnt(5)
	v_pk_mul_f32 v[28:29], v[96:97], v[246:247] op_sel:[0,1]
	v_pk_fma_f32 v[24:25], v[94:95], v[246:247], v[28:29] op_sel_hi:[1,0,1]
	s_waitcnt lgkmcnt(1)
	v_pk_fma_f32 v[24:25], v[34:35], v[248:249], v[24:25] op_sel_hi:[1,0,1]
	v_pk_fma_f32 v[24:25], v[30:31], v[248:249], v[24:25] op_sel:[0,1,0]
	s_add_i32 s1, s49, s0
	s_sub_i32 s1, s1, 64
	v_mov_b32_e32 v250, s1
	ds_read_b128 v[246:249], v250
	v_pk_fma_f32 v[24:25], v[32:33], v[70:71], v[24:25] op_sel_hi:[1,0,1]
	v_pk_fma_f32 v[24:25], v[36:37], v[70:71], v[24:25] op_sel:[0,1,0]
	v_pk_fma_f32 v[24:25], v[98:99], v[72:73], v[24:25] op_sel_hi:[1,0,1]
	v_pk_fma_f32 v[24:25], v[100:101], v[72:73], v[24:25] op_sel:[0,1,0]
	v_pk_mul_f32 v[26:27], v[104:105], v[74:75] op_sel:[0,1]
	v_pk_fma_f32 v[26:27], v[102:103], v[74:75], v[26:27] op_sel_hi:[1,0,1]
	v_pk_fma_f32 v[26:27], v[106:107], v[76:77], v[26:27] op_sel_hi:[1,0,1]
	v_pk_fma_f32 v[26:27], v[108:109], v[76:77], v[26:27] op_sel:[0,1,0]
	s_waitcnt lgkmcnt(1)
	v_mov_b32_e32 v28, v81
	v_pk_fma_f32 v[26:27], v[110:111], v[78:79], v[26:27] op_sel_hi:[1,0,1]
	v_pk_fma_f32 v[26:27], v[112:113], v[78:79], v[26:27] op_sel:[0,1,0]
	v_pk_fma_f32 v[26:27], v[114:115], v[80:81], v[26:27] op_sel_hi:[1,0,1]
	v_pk_fma_f32 v[26:27], v[92:93], v[28:29], v[26:27] op_sel_hi:[1,0,1]
	v_pk_add_f32 v[24:25], v[24:25], v[26:27]
	v_pk_fma_f32 v[24:25], v[88:89], v[90:91], v[24:25] op_sel:[0,1,0] op_sel_hi:[1,0,1]
	v_pk_fma_f32 v[90:91], v[86:87], v[90:91], v[24:25]
	v_add_u32_e32 v25, s49, v22
	v_cvt_pk_bf16_f32 v23, v90, s0
	v_cvt_pk_bf16_f32 v24, v91, s0
	s_sub_i32 s0, s0, 64
	v_add_u32_e32 v22, 0xfffffef0, v22
	s_cmpk_lg_i32 s0, 0x7c0
	ds_write_b16 v25, v23
	ds_write_b16 v25, v24 offset:128
	s_cbranch_scc1 .LBB0_655
	ds_read_b128 v[22:25], v1 offset:8192
	ds_read_b128 v[26:29], v1 offset:12544
	s_movk_i32 s0, 0x7c0
	s_waitcnt lgkmcnt(1)
	v_mfma_f32_16x16x32_bf16 v[22:25], v[22:25], v[46:49], v[62:65]
	s_nop 2
	ds_read_b128 v[62:65], v1 offset:8256
	s_waitcnt lgkmcnt(1)
	v_mfma_f32_16x16x32_bf16 v[26:29], v[26:29], v[46:49], v[66:69]
	s_waitcnt lgkmcnt(0)
	v_mfma_f32_16x16x32_bf16 v[22:25], v[62:65], v[54:57], v[22:25]
	ds_read_b128 v[62:65], v1 offset:12608
	s_waitcnt lgkmcnt(0)
	v_mfma_f32_16x16x32_bf16 v[26:29], v[62:65], v[54:57], v[26:29]
	ds_read_b128 v[62:65], v1 offset:8320
	s_waitcnt lgkmcnt(0)
	v_mfma_f32_16x16x32_bf16 v[22:25], v[62:65], v[50:53], v[22:25]
	ds_read_b128 v[62:65], v1 offset:12672
	s_waitcnt lgkmcnt(0)
	v_mfma_f32_16x16x32_bf16 v[62:65], v[62:65], v[50:53], v[26:29]
	s_nop 2
	ds_read_b128 v[26:29], v1 offset:8384
	s_waitcnt lgkmcnt(0)
	v_mfma_f32_16x16x32_bf16 v[26:29], v[26:29], v[42:45], v[22:25]
	s_nop 2
	ds_read_b128 v[22:25], v1 offset:12736
	s_waitcnt lgkmcnt(0)
	v_mfma_f32_16x16x32_bf16 v[22:25], v[22:25], v[42:45], v[62:65]
	s_add_i32 s1, s49, s0
	v_mov_b32_e32 v250, s1
	ds_read_b128 v[246:249], v250
	s_waitcnt lgkmcnt(0)
.LBB0_657:
	s_add_i32 s1, s49, s0
	v_mov_b32_e32 v74, s1
	s_nop 0
	ds_read_b128 v[66:69], v74 offset:16
	ds_read_b128 v[70:73], v74 offset:32
	ds_read_b128 v[74:77], v74 offset:48
	s_waitcnt lgkmcnt(5)
	v_pk_mul_f32 v[78:79], v[96:97], v[246:247] op_sel:[0,1]
	v_pk_fma_f32 v[62:63], v[94:95], v[246:247], v[78:79] op_sel_hi:[1,0,1]
	v_pk_fma_f32 v[62:63], v[34:35], v[248:249], v[62:63] op_sel_hi:[1,0,1]
	v_pk_fma_f32 v[62:63], v[30:31], v[248:249], v[62:63] op_sel:[0,1,0]
	s_add_i32 s1, s49, s0
	s_sub_i32 s1, s1, 64
	v_mov_b32_e32 v250, s1
	ds_read_b128 v[246:249], v250
	s_waitcnt lgkmcnt(3)
	v_pk_fma_f32 v[62:63], v[32:33], v[66:67], v[62:63] op_sel_hi:[1,0,1]
	v_pk_fma_f32 v[62:63], v[36:37], v[66:67], v[62:63] op_sel:[0,1,0]
	s_waitcnt lgkmcnt(2)
	v_pk_fma_f32 v[62:63], v[98:99], v[68:69], v[62:63] op_sel_hi:[1,0,1]
	v_pk_fma_f32 v[62:63], v[100:101], v[68:69], v[62:63] op_sel:[0,1,0]
	v_pk_mul_f32 v[64:65], v[104:105], v[70:71] op_sel:[0,1]
	v_pk_fma_f32 v[64:65], v[102:103], v[70:71], v[64:65] op_sel_hi:[1,0,1]
	v_pk_fma_f32 v[64:65], v[106:107], v[72:73], v[64:65] op_sel_hi:[1,0,1]
	v_pk_fma_f32 v[64:65], v[108:109], v[72:73], v[64:65] op_sel:[0,1,0]
	s_waitcnt lgkmcnt(1)
	v_mov_b32_e32 v66, v77
	v_pk_fma_f32 v[64:65], v[110:111], v[74:75], v[64:65] op_sel_hi:[1,0,1]
	v_pk_fma_f32 v[64:65], v[112:113], v[74:75], v[64:65] op_sel:[0,1,0]
	v_pk_fma_f32 v[64:65], v[114:115], v[76:77], v[64:65] op_sel_hi:[1,0,1]
	v_pk_fma_f32 v[64:65], v[92:93], v[66:67], v[64:65] op_sel_hi:[1,0,1]
	v_pk_add_f32 v[62:63], v[62:63], v[64:65]
	v_add_u32_e32 v64, s49, v2
	v_pk_fma_f32 v[62:63], v[88:89], v[90:91], v[62:63] op_sel:[0,1,0] op_sel_hi:[1,0,1]
	v_add_u32_e32 v2, 0xfffffef0, v2
	v_pk_fma_f32 v[90:91], v[86:87], v[90:91], v[62:63]
	v_cvt_pk_bf16_f32 v62, v90, s0
	v_cvt_pk_bf16_f32 v63, v91, s0
	s_sub_i32 s0, s0, 64
	s_cmpk_eq_i32 s0, 0xffc0
	ds_write_b16 v64, v62
	ds_write_b16 v64, v63 offset:128
	s_cbranch_scc0 .LBB0_657
; #define LAS __attribute__((address_space(3)))
; DI bf16 f2bf(float f) { return (bf16)(pk2(f, 0.f) & 0xffffu); }
; DI float gelu_tanh(float x) { const float u = 0.7978845608028654f * (x + 0.044715f * x * x * x); return x * sigm(2.0f * u); }
; DI f32x4 mfma16(bf16x8 a, bf16x8 b, f32x4 c) { return __builtin_amdgcn_mfma_f32_16x16x32_bf16(a, b, c, 0, 0, 0); }
; template <int DIRN, int SUB> DI void s5_subtile(const LAS float* UF, LAS bf16* XT, float lr, float li, const f32x2 (&bb)[16], f32x2& x,
;                                                 const bf16x8 (&bfr)[4], f32x4& acc0, f32x4& acc1, int lane) {
;     ...
; #pragma unroll
;     for (int ks = 0; ks < 4; ++ks) { const bf16x8 a0 = *(const LAS bf16x8*)(XT + (lane & 15) * 136 + 32 * ks + 8 * (lane >> 4)), a1 = *(const LAS bf16x8*)(XT + (16 + (lane & 15)) * 136 + 32 * ks + 8 * (lane >> 4));
;         acc0 = mfma16(a0, bfr[ks], acc0); acc1 = mfma16(a1, bfr[ks], acc1); }
; DI void s5_passC(const Ctx& C, const S5P& P, const bf16* PROJ, const f32x2* END, bf16* YG  , int item_lo, int item_hi) {
;     ...
;         const float dv = P.d[g * 16 + (lane & 15)];
; #pragma unroll
;         for (int r = 0; r < 8; ++r)
; #pragma unroll
;             for (int j = 0; j < 4; ++j) { const int t = 16 * r + (lane >> 4) * 4 + j; const float y = acc[r][j] + dv * UF[t * 16 + (lane & 15)]; YG[(tok0 + t) * 1024 + g * 16 + (lane & 15)] = f2bf(gelu_tanh(y)); }
	ds_read_b128 v[30:33], v1 offset:8192
	ds_read_b128 v[34:37], v1 offset:12544
	v_lshlrev_b32_e32 v2, 2, v125
	v_readlane_b32 s72, v252, 20
	v_readlane_b32 s80, v252, 28
	s_waitcnt lgkmcnt(1)
	v_mfma_f32_16x16x32_bf16 v[30:33], v[30:33], v[46:49], v[38:41]
	v_readlane_b32 s81, v252, 29
	s_lshl_b32 s0, s67, 5
	s_add_u32 s0, s47, s0
	s_waitcnt lgkmcnt(0)
	v_mfma_f32_16x16x32_bf16 v[34:37], v[34:37], v[46:49], v[58:61]
	ds_read_b128 v[38:41], v1 offset:8256
	ds_read_b128 v[46:49], v1 offset:12608
	s_addc_u32 s1, s48, 0
	s_add_i32 s31, s31, s8
	s_waitcnt lgkmcnt(1)
	v_mfma_f32_16x16x32_bf16 v[30:33], v[38:41], v[54:57], v[30:33]
	v_readlane_b32 s76, v252, 24
	v_readlane_b32 s77, v252, 25
	v_readlane_b32 s78, v252, 26
	s_waitcnt lgkmcnt(0)
	v_mfma_f32_16x16x32_bf16 v[34:37], v[46:49], v[54:57], v[34:37]
	ds_read_b128 v[38:41], v1 offset:8320
	ds_read_b128 v[46:49], v1 offset:12672
	v_readlane_b32 s79, v252, 27
	v_readlane_b32 s73, v252, 21
	s_waitcnt lgkmcnt(1)
	v_mfma_f32_16x16x32_bf16 v[30:33], v[38:41], v[50:53], v[30:33]
	v_readlane_b32 s74, v252, 22
	v_readlane_b32 s75, v252, 23
	v_readlane_b32 s82, v252, 30
	s_waitcnt lgkmcnt(0)
	v_mfma_f32_16x16x32_bf16 v[38:41], v[46:49], v[50:53], v[34:37]
	s_nop 2
	ds_read_b128 v[34:37], v1 offset:8384
	ds_read_b128 v[46:49], v1 offset:12736
	v_lshl_or_b32 v1, s67, 6, v2
	global_load_dword v1, v1, s[80:81]
	s_waitcnt lgkmcnt(1)
	v_mfma_f32_16x16x32_bf16 v[34:37], v[34:37], v[42:45], v[30:33]
	v_readlane_b32 s83, v252, 31
	v_readlane_b32 s84, v252, 32
	v_readlane_b32 s85, v252, 33
	s_waitcnt lgkmcnt(0)
	v_mfma_f32_16x16x32_bf16 v[30:33], v[46:49], v[42:45], v[38:41]
	v_ashrrev_i32_e32 v43, 2, v122
	v_add_u32_e32 v42, s49, v2
	v_lshlrev_b32_e32 v2, 1, v125
	v_and_b32_e32 v40, -4, v43
	v_lshl_add_u64 v[38:39], s[0:1], 0, v[2:3]
	v_lshl_add_u32 v2, v40, 6, v42
	ds_read_b32 v2, v2
	v_ashrrev_i32_e32 v41, 31, v40
	v_lshl_add_u64 v[44:45], s[12:13], 0, v[40:41]
	v_lshlrev_b64 v[44:45], 11, v[44:45]
	v_lshl_add_u64 v[44:45], v[38:39], 0, v[44:45]
	v_readlane_b32 s86, v252, 34
	v_readlane_b32 s87, v252, 35
	s_waitcnt vmcnt(0) lgkmcnt(0)
	v_fma_f32 v2, v1, v2, v34
	v_mul_f32_e32 v34, 0x3d372713, v2
	v_mul_f32_e32 v34, v2, v34
	v_fma_f32 v34, v2, v34, v2
	v_mul_f32_e32 v34, 0x3f4c422a, v34
	v_add_f32_e32 v34, v34, v34
	v_mul_f32_e32 v34, 0xbfb8aa3b, v34
	v_exp_f32_e32 v34, v34
	s_nop 0
	v_add_f32_e32 v34, 1.0, v34
	v_rcp_f32_e32 v34, v34
	s_nop 0
	v_mul_f32_e32 v2, v2, v34
	v_cvt_pk_bf16_f32 v2, v2, s0
	v_or_b32_e32 v34, 1, v40
	global_store_short v[44:45], v2, off
	v_lshl_add_u32 v2, v34, 6, v42
	ds_read_b32 v2, v2
	s_waitcnt lgkmcnt(0)
	v_fma_f32 v2, v1, v2, v35
	v_mul_f32_e32 v35, 0x3d372713, v2
	v_mul_f32_e32 v35, v2, v35
	v_fma_f32 v35, v2, v35, v2
	v_mul_f32_e32 v35, 0x3f4c422a, v35
	v_add_f32_e32 v35, v35, v35
	v_mul_f32_e32 v35, 0xbfb8aa3b, v35
	v_exp_f32_e32 v35, v35
	s_nop 0
	v_add_f32_e32 v35, 1.0, v35
	v_rcp_f32_e32 v35, v35
	s_nop 0
	v_mul_f32_e32 v2, v2, v35
	v_ashrrev_i32_e32 v35, 31, v34
	v_lshl_add_u64 v[34:35], s[12:13], 0, v[34:35]
	v_lshlrev_b64 v[34:35], 11, v[34:35]
	v_cvt_pk_bf16_f32 v2, v2, s0
	v_lshl_add_u64 v[34:35], v[38:39], 0, v[34:35]
	global_store_short v[34:35], v2, off
	v_or_b32_e32 v34, 2, v40
	v_lshl_add_u32 v2, v34, 6, v42
	ds_read_b32 v2, v2
	s_waitcnt lgkmcnt(0)
	v_fma_f32 v2, v1, v2, v36
	v_mul_f32_e32 v35, 0x3d372713, v2
	v_mul_f32_e32 v35, v2, v35
	v_fma_f32 v35, v2, v35, v2
	v_mul_f32_e32 v35, 0x3f4c422a, v35
	v_add_f32_e32 v35, v35, v35
	v_mul_f32_e32 v35, 0xbfb8aa3b, v35
	v_exp_f32_e32 v35, v35
	s_nop 0
	v_add_f32_e32 v35, 1.0, v35
	v_rcp_f32_e32 v35, v35
	s_nop 0
	v_mul_f32_e32 v2, v2, v35
	v_ashrrev_i32_e32 v35, 31, v34
	v_lshl_add_u64 v[34:35], s[12:13], 0, v[34:35]
	v_lshlrev_b64 v[34:35], 11, v[34:35]
	v_cvt_pk_bf16_f32 v2, v2, s0
	v_lshl_add_u64 v[34:35], v[38:39], 0, v[34:35]
	global_store_short v[34:35], v2, off
	v_or_b32_e32 v34, 3, v43
	v_lshl_add_u32 v2, v34, 6, v42
	ds_read_b32 v2, v2
	v_ashrrev_i32_e32 v35, 31, v34
	v_lshl_add_u64 v[34:35], s[12:13], 0, v[34:35]
	v_lshlrev_b64 v[34:35], 11, v[34:35]
	v_lshl_add_u64 v[34:35], v[38:39], 0, v[34:35]
	s_waitcnt lgkmcnt(0)
	v_fmac_f32_e32 v37, v1, v2
	v_mul_f32_e32 v2, 0x3d372713, v37
	v_mul_f32_e32 v2, v37, v2
	v_fma_f32 v2, v37, v2, v37
	v_mul_f32_e32 v2, 0x3f4c422a, v2
	v_add_f32_e32 v2, v2, v2
	v_mul_f32_e32 v2, 0xbfb8aa3b, v2
	v_exp_f32_e32 v2, v2
	s_nop 0
	v_add_f32_e32 v2, 1.0, v2
	v_rcp_f32_e32 v2, v2
	s_nop 0
	v_mul_f32_e32 v2, v37, v2
	v_cvt_pk_bf16_f32 v2, v2, s0
	global_store_short v[34:35], v2, off
	v_add_u32_e32 v34, 16, v40
	v_lshl_add_u32 v2, v34, 6, v42
	ds_read_b32 v2, v2
	v_ashrrev_i32_e32 v35, 31, v34
	v_lshl_add_u64 v[34:35], s[12:13], 0, v[34:35]
	v_lshlrev_b64 v[34:35], 11, v[34:35]
	v_lshl_add_u64 v[34:35], v[38:39], 0, v[34:35]
	s_waitcnt lgkmcnt(0)
	v_fma_f32 v2, v1, v2, v30
	v_mul_f32_e32 v30, 0x3d372713, v2
	v_mul_f32_e32 v30, v2, v30
	v_fma_f32 v30, v2, v30, v2
	v_mul_f32_e32 v30, 0x3f4c422a, v30
	v_add_f32_e32 v30, v30, v30
	v_mul_f32_e32 v30, 0xbfb8aa3b, v30
	v_exp_f32_e32 v30, v30
	s_nop 0
	v_add_f32_e32 v30, 1.0, v30
	v_rcp_f32_e32 v30, v30
	s_nop 0
	v_mul_f32_e32 v2, v2, v30
	v_cvt_pk_bf16_f32 v2, v2, s0
	v_add_u32_e32 v30, 17, v40
	global_store_short v[34:35], v2, off
	v_lshl_add_u32 v2, v30, 6, v42
	ds_read_b32 v2, v2
	s_waitcnt lgkmcnt(0)
; DI bf16 f2bf(float f) { return (bf16)(pk2(f, 0.f) & 0xffffu); }
; DI float gelu_tanh(float x) { const float u = 0.7978845608028654f * (x + 0.044715f * x * x * x); return x * sigm(2.0f * u); }
; DI void s5_passC(const Ctx& C, const S5P& P, const bf16* PROJ, const f32x2* END, bf16* YG  , int item_lo, int item_hi) {
;     ...
;         const float dv = P.d[g * 16 + (lane & 15)];
; #pragma unroll
;         for (int r = 0; r < 8; ++r)
; #pragma unroll
;             for (int j = 0; j < 4; ++j) { const int t = 16 * r + (lane >> 4) * 4 + j; const float y = acc[r][j] + dv * UF[t * 16 + (lane & 15)]; YG[(tok0 + t) * 1024 + g * 16 + (lane & 15)] = f2bf(gelu_tanh(y)); }
	v_fma_f32 v2, v1, v2, v31
	v_mul_f32_e32 v31, 0x3d372713, v2
	v_mul_f32_e32 v31, v2, v31
	v_fma_f32 v31, v2, v31, v2
	v_mul_f32_e32 v31, 0x3f4c422a, v31
	v_add_f32_e32 v31, v31, v31
	v_mul_f32_e32 v31, 0xbfb8aa3b, v31
	v_exp_f32_e32 v31, v31
	s_nop 0
	v_add_f32_e32 v31, 1.0, v31
	v_rcp_f32_e32 v31, v31
	s_nop 0
	v_mul_f32_e32 v2, v2, v31
	v_ashrrev_i32_e32 v31, 31, v30
	v_lshl_add_u64 v[30:31], s[12:13], 0, v[30:31]
	v_lshlrev_b64 v[30:31], 11, v[30:31]
	v_cvt_pk_bf16_f32 v2, v2, s0
	v_lshl_add_u64 v[30:31], v[38:39], 0, v[30:31]
	global_store_short v[30:31], v2, off
	v_add_u32_e32 v30, 18, v40
	v_lshl_add_u32 v2, v30, 6, v42
	ds_read_b32 v2, v2
	s_waitcnt lgkmcnt(0)
	v_fma_f32 v2, v1, v2, v32
	v_mul_f32_e32 v31, 0x3d372713, v2
	v_mul_f32_e32 v31, v2, v31
	v_fma_f32 v31, v2, v31, v2
	v_mul_f32_e32 v31, 0x3f4c422a, v31
	v_add_f32_e32 v31, v31, v31
	v_mul_f32_e32 v31, 0xbfb8aa3b, v31
	v_exp_f32_e32 v31, v31
	s_nop 0
	v_add_f32_e32 v31, 1.0, v31
	v_rcp_f32_e32 v31, v31
	s_nop 0
	v_mul_f32_e32 v2, v2, v31
	v_ashrrev_i32_e32 v31, 31, v30
	v_lshl_add_u64 v[30:31], s[12:13], 0, v[30:31]
	v_lshlrev_b64 v[30:31], 11, v[30:31]
	v_cvt_pk_bf16_f32 v2, v2, s0
	v_lshl_add_u64 v[30:31], v[38:39], 0, v[30:31]
	global_store_short v[30:31], v2, off
	v_add_u32_e32 v30, 19, v40
	v_lshl_add_u32 v2, v30, 6, v42
	ds_read_b32 v2, v2
	v_ashrrev_i32_e32 v31, 31, v30
	v_lshl_add_u64 v[30:31], s[12:13], 0, v[30:31]
	v_lshlrev_b64 v[30:31], 11, v[30:31]
	v_lshl_add_u64 v[30:31], v[38:39], 0, v[30:31]
	s_waitcnt lgkmcnt(0)
	v_fmac_f32_e32 v33, v1, v2
	v_mul_f32_e32 v2, 0x3d372713, v33
	v_mul_f32_e32 v2, v33, v2
	v_fma_f32 v2, v33, v2, v33
	v_mul_f32_e32 v2, 0x3f4c422a, v2
	v_add_f32_e32 v2, v2, v2
	v_mul_f32_e32 v2, 0xbfb8aa3b, v2
	v_exp_f32_e32 v2, v2
	s_nop 0
	v_add_f32_e32 v2, 1.0, v2
	v_rcp_f32_e32 v2, v2
	s_nop 0
	v_mul_f32_e32 v2, v33, v2
	v_cvt_pk_bf16_f32 v2, v2, s0
	global_store_short v[30:31], v2, off
	v_add_u32_e32 v30, 32, v40
	v_lshl_add_u32 v2, v30, 6, v42
	ds_read_b32 v2, v2
	v_ashrrev_i32_e32 v31, 31, v30
	v_lshl_add_u64 v[30:31], s[12:13], 0, v[30:31]
	v_lshlrev_b64 v[30:31], 11, v[30:31]
	v_lshl_add_u64 v[30:31], v[38:39], 0, v[30:31]
	s_waitcnt lgkmcnt(0)
	v_fma_f32 v2, v1, v2, v26
	v_mul_f32_e32 v26, 0x3d372713, v2
	v_mul_f32_e32 v26, v2, v26
	v_fma_f32 v26, v2, v26, v2
	v_mul_f32_e32 v26, 0x3f4c422a, v26
	v_add_f32_e32 v26, v26, v26
	v_mul_f32_e32 v26, 0xbfb8aa3b, v26
	v_exp_f32_e32 v26, v26
	s_nop 0
	v_add_f32_e32 v26, 1.0, v26
	v_rcp_f32_e32 v26, v26
	s_nop 0
	v_mul_f32_e32 v2, v2, v26
	v_cvt_pk_bf16_f32 v2, v2, s0
	v_add_u32_e32 v26, 33, v40
	global_store_short v[30:31], v2, off
	v_lshl_add_u32 v2, v26, 6, v42
	ds_read_b32 v2, v2
	s_waitcnt lgkmcnt(0)
	v_fma_f32 v2, v1, v2, v27
	v_mul_f32_e32 v27, 0x3d372713, v2
	v_mul_f32_e32 v27, v2, v27
	v_fma_f32 v27, v2, v27, v2
	v_mul_f32_e32 v27, 0x3f4c422a, v27
	v_add_f32_e32 v27, v27, v27
	v_mul_f32_e32 v27, 0xbfb8aa3b, v27
	v_exp_f32_e32 v27, v27
	s_nop 0
	v_add_f32_e32 v27, 1.0, v27
	v_rcp_f32_e32 v27, v27
	s_nop 0
	v_mul_f32_e32 v2, v2, v27
	v_ashrrev_i32_e32 v27, 31, v26
	v_lshl_add_u64 v[26:27], s[12:13], 0, v[26:27]
	v_lshlrev_b64 v[26:27], 11, v[26:27]
	v_cvt_pk_bf16_f32 v2, v2, s0
	v_lshl_add_u64 v[26:27], v[38:39], 0, v[26:27]
	global_store_short v[26:27], v2, off
	v_add_u32_e32 v26, 34, v40
	v_lshl_add_u32 v2, v26, 6, v42
	ds_read_b32 v2, v2
	s_waitcnt lgkmcnt(0)
	v_fma_f32 v2, v1, v2, v28
	v_mul_f32_e32 v27, 0x3d372713, v2
	v_mul_f32_e32 v27, v2, v27
	v_fma_f32 v27, v2, v27, v2
	v_mul_f32_e32 v27, 0x3f4c422a, v27
	v_add_f32_e32 v27, v27, v27
	v_mul_f32_e32 v27, 0xbfb8aa3b, v27
	v_exp_f32_e32 v27, v27
	s_nop 0
	v_add_f32_e32 v27, 1.0, v27
	v_rcp_f32_e32 v27, v27
	s_nop 0
	v_mul_f32_e32 v2, v2, v27
	v_ashrrev_i32_e32 v27, 31, v26
	v_lshl_add_u64 v[26:27], s[12:13], 0, v[26:27]
	v_lshlrev_b64 v[26:27], 11, v[26:27]
	v_cvt_pk_bf16_f32 v2, v2, s0
	v_lshl_add_u64 v[26:27], v[38:39], 0, v[26:27]
	global_store_short v[26:27], v2, off
	v_add_u32_e32 v26, 35, v40
	v_lshl_add_u32 v2, v26, 6, v42
	ds_read_b32 v2, v2
	v_ashrrev_i32_e32 v27, 31, v26
	v_lshl_add_u64 v[26:27], s[12:13], 0, v[26:27]
	v_lshlrev_b64 v[26:27], 11, v[26:27]
	v_lshl_add_u64 v[26:27], v[38:39], 0, v[26:27]
	s_waitcnt lgkmcnt(0)
	v_fmac_f32_e32 v29, v1, v2
	v_mul_f32_e32 v2, 0x3d372713, v29
	v_mul_f32_e32 v2, v29, v2
	v_fma_f32 v2, v29, v2, v29
	v_mul_f32_e32 v2, 0x3f4c422a, v2
	v_add_f32_e32 v2, v2, v2
	v_mul_f32_e32 v2, 0xbfb8aa3b, v2
	v_exp_f32_e32 v2, v2
	s_nop 0
	v_add_f32_e32 v2, 1.0, v2
	v_rcp_f32_e32 v2, v2
	s_nop 0
	v_mul_f32_e32 v2, v29, v2
	v_cvt_pk_bf16_f32 v2, v2, s0
	global_store_short v[26:27], v2, off
	v_add_u32_e32 v26, 48, v40
	v_lshl_add_u32 v2, v26, 6, v42
	ds_read_b32 v2, v2
	v_ashrrev_i32_e32 v27, 31, v26
	v_lshl_add_u64 v[26:27], s[12:13], 0, v[26:27]
	v_lshlrev_b64 v[26:27], 11, v[26:27]
	v_lshl_add_u64 v[26:27], v[38:39], 0, v[26:27]
	s_waitcnt lgkmcnt(0)
	v_fma_f32 v2, v1, v2, v22
	v_mul_f32_e32 v22, 0x3d372713, v2
	v_mul_f32_e32 v22, v2, v22
	v_fma_f32 v22, v2, v22, v2
	v_mul_f32_e32 v22, 0x3f4c422a, v22
	v_add_f32_e32 v22, v22, v22
	v_mul_f32_e32 v22, 0xbfb8aa3b, v22
	v_exp_f32_e32 v22, v22
	s_nop 0
	v_add_f32_e32 v22, 1.0, v22
	v_rcp_f32_e32 v22, v22
	s_nop 0
	v_mul_f32_e32 v2, v2, v22
	v_cvt_pk_bf16_f32 v2, v2, s0
	v_add_u32_e32 v22, 49, v40
	global_store_short v[26:27], v2, off
	v_lshl_add_u32 v2, v22, 6, v42
	ds_read_b32 v2, v2
	s_waitcnt lgkmcnt(0)
; DI bf16 f2bf(float f) { return (bf16)(pk2(f, 0.f) & 0xffffu); }
; DI float gelu_tanh(float x) { const float u = 0.7978845608028654f * (x + 0.044715f * x * x * x); return x * sigm(2.0f * u); }
; DI void s5_passC(const Ctx& C, const S5P& P, const bf16* PROJ, const f32x2* END, bf16* YG  , int item_lo, int item_hi) {
;     ...
;         const float dv = P.d[g * 16 + (lane & 15)];
; #pragma unroll
;         for (int r = 0; r < 8; ++r)
; #pragma unroll
;             for (int j = 0; j < 4; ++j) { const int t = 16 * r + (lane >> 4) * 4 + j; const float y = acc[r][j] + dv * UF[t * 16 + (lane & 15)]; YG[(tok0 + t) * 1024 + g * 16 + (lane & 15)] = f2bf(gelu_tanh(y)); }
	v_fma_f32 v2, v1, v2, v23
	v_mul_f32_e32 v23, 0x3d372713, v2
	v_mul_f32_e32 v23, v2, v23
	v_fma_f32 v23, v2, v23, v2
	v_mul_f32_e32 v23, 0x3f4c422a, v23
	v_add_f32_e32 v23, v23, v23
	v_mul_f32_e32 v23, 0xbfb8aa3b, v23
	v_exp_f32_e32 v23, v23
	s_nop 0
	v_add_f32_e32 v23, 1.0, v23
	v_rcp_f32_e32 v23, v23
	s_nop 0
	v_mul_f32_e32 v2, v2, v23
	v_ashrrev_i32_e32 v23, 31, v22
	v_lshl_add_u64 v[22:23], s[12:13], 0, v[22:23]
	v_lshlrev_b64 v[22:23], 11, v[22:23]
	v_cvt_pk_bf16_f32 v2, v2, s0
	v_lshl_add_u64 v[22:23], v[38:39], 0, v[22:23]
	global_store_short v[22:23], v2, off
	v_add_u32_e32 v22, 50, v40
	v_lshl_add_u32 v2, v22, 6, v42
	ds_read_b32 v2, v2
	s_waitcnt lgkmcnt(0)
	v_fma_f32 v2, v1, v2, v24
	v_mul_f32_e32 v23, 0x3d372713, v2
	v_mul_f32_e32 v23, v2, v23
	v_fma_f32 v23, v2, v23, v2
	v_mul_f32_e32 v23, 0x3f4c422a, v23
	v_add_f32_e32 v23, v23, v23
	v_mul_f32_e32 v23, 0xbfb8aa3b, v23
	v_exp_f32_e32 v23, v23
	s_nop 0
	v_add_f32_e32 v23, 1.0, v23
	v_rcp_f32_e32 v23, v23
	s_nop 0
	v_mul_f32_e32 v2, v2, v23
	v_ashrrev_i32_e32 v23, 31, v22
	v_lshl_add_u64 v[22:23], s[12:13], 0, v[22:23]
	v_lshlrev_b64 v[22:23], 11, v[22:23]
	v_cvt_pk_bf16_f32 v2, v2, s0
	v_lshl_add_u64 v[22:23], v[38:39], 0, v[22:23]
	global_store_short v[22:23], v2, off
	v_add_u32_e32 v22, 51, v40
	v_lshl_add_u32 v2, v22, 6, v42
	ds_read_b32 v2, v2
	v_ashrrev_i32_e32 v23, 31, v22
	v_lshl_add_u64 v[22:23], s[12:13], 0, v[22:23]
	v_lshlrev_b64 v[22:23], 11, v[22:23]
	v_lshl_add_u64 v[22:23], v[38:39], 0, v[22:23]
	s_waitcnt lgkmcnt(0)
	v_fmac_f32_e32 v25, v1, v2
	v_mul_f32_e32 v2, 0x3d372713, v25
	v_mul_f32_e32 v2, v25, v2
	v_fma_f32 v2, v25, v2, v25
	v_mul_f32_e32 v2, 0x3f4c422a, v2
	v_add_f32_e32 v2, v2, v2
	v_mul_f32_e32 v2, 0xbfb8aa3b, v2
	v_exp_f32_e32 v2, v2
	s_nop 0
	v_add_f32_e32 v2, 1.0, v2
	v_rcp_f32_e32 v2, v2
	s_nop 0
	v_mul_f32_e32 v2, v25, v2
	v_cvt_pk_bf16_f32 v2, v2, s0
	global_store_short v[22:23], v2, off
	v_add_u32_e32 v22, 64, v40
	v_lshl_add_u32 v2, v22, 6, v42
	ds_read_b32 v2, v2
	v_ashrrev_i32_e32 v23, 31, v22
	v_lshl_add_u64 v[22:23], s[12:13], 0, v[22:23]
	v_lshlrev_b64 v[22:23], 11, v[22:23]
	v_lshl_add_u64 v[22:23], v[38:39], 0, v[22:23]
	s_waitcnt lgkmcnt(0)
	v_fma_f32 v2, v1, v2, v18
	v_mul_f32_e32 v18, 0x3d372713, v2
	v_mul_f32_e32 v18, v2, v18
	v_fma_f32 v18, v2, v18, v2
	v_mul_f32_e32 v18, 0x3f4c422a, v18
	v_add_f32_e32 v18, v18, v18
	v_mul_f32_e32 v18, 0xbfb8aa3b, v18
	v_exp_f32_e32 v18, v18
	s_nop 0
	v_add_f32_e32 v18, 1.0, v18
	v_rcp_f32_e32 v18, v18
	s_nop 0
	v_mul_f32_e32 v2, v2, v18
	v_cvt_pk_bf16_f32 v2, v2, s0
	v_add_u32_e32 v18, 0x41, v40
	global_store_short v[22:23], v2, off
	v_lshl_add_u32 v2, v18, 6, v42
	ds_read_b32 v2, v2
	s_waitcnt lgkmcnt(0)
	v_fma_f32 v2, v1, v2, v19
	v_mul_f32_e32 v19, 0x3d372713, v2
	v_mul_f32_e32 v19, v2, v19
	v_fma_f32 v19, v2, v19, v2
	v_mul_f32_e32 v19, 0x3f4c422a, v19
	v_add_f32_e32 v19, v19, v19
	v_mul_f32_e32 v19, 0xbfb8aa3b, v19
	v_exp_f32_e32 v19, v19
	s_nop 0
	v_add_f32_e32 v19, 1.0, v19
	v_rcp_f32_e32 v19, v19
	s_nop 0
	v_mul_f32_e32 v2, v2, v19
	v_ashrrev_i32_e32 v19, 31, v18
	v_lshl_add_u64 v[18:19], s[12:13], 0, v[18:19]
	v_lshlrev_b64 v[18:19], 11, v[18:19]
	v_cvt_pk_bf16_f32 v2, v2, s0
	v_lshl_add_u64 v[18:19], v[38:39], 0, v[18:19]
	global_store_short v[18:19], v2, off
	v_add_u32_e32 v18, 0x42, v40
	v_lshl_add_u32 v2, v18, 6, v42
	ds_read_b32 v2, v2
	s_waitcnt lgkmcnt(0)
	v_fma_f32 v2, v1, v2, v20
	v_mul_f32_e32 v19, 0x3d372713, v2
	v_mul_f32_e32 v19, v2, v19
	v_fma_f32 v19, v2, v19, v2
	v_mul_f32_e32 v19, 0x3f4c422a, v19
	v_add_f32_e32 v19, v19, v19
	v_mul_f32_e32 v19, 0xbfb8aa3b, v19
	v_exp_f32_e32 v19, v19
	s_nop 0
	v_add_f32_e32 v19, 1.0, v19
	v_rcp_f32_e32 v19, v19
	s_nop 0
	v_mul_f32_e32 v2, v2, v19
	v_ashrrev_i32_e32 v19, 31, v18
	v_lshl_add_u64 v[18:19], s[12:13], 0, v[18:19]
	v_lshlrev_b64 v[18:19], 11, v[18:19]
	v_cvt_pk_bf16_f32 v2, v2, s0
	v_lshl_add_u64 v[18:19], v[38:39], 0, v[18:19]
	global_store_short v[18:19], v2, off
	v_add_u32_e32 v18, 0x43, v40
	v_lshl_add_u32 v2, v18, 6, v42
	ds_read_b32 v2, v2
	v_ashrrev_i32_e32 v19, 31, v18
	v_lshl_add_u64 v[18:19], s[12:13], 0, v[18:19]
	v_lshlrev_b64 v[18:19], 11, v[18:19]
	v_lshl_add_u64 v[18:19], v[38:39], 0, v[18:19]
	s_waitcnt lgkmcnt(0)
	v_fmac_f32_e32 v21, v1, v2
	v_mul_f32_e32 v2, 0x3d372713, v21
	v_mul_f32_e32 v2, v21, v2
	v_fma_f32 v2, v21, v2, v21
	v_mul_f32_e32 v2, 0x3f4c422a, v2
	v_add_f32_e32 v2, v2, v2
	v_mul_f32_e32 v2, 0xbfb8aa3b, v2
	v_exp_f32_e32 v2, v2
	s_nop 0
	v_add_f32_e32 v2, 1.0, v2
	v_rcp_f32_e32 v2, v2
	s_nop 0
	v_mul_f32_e32 v2, v21, v2
	v_cvt_pk_bf16_f32 v2, v2, s0
	global_store_short v[18:19], v2, off
	v_add_u32_e32 v18, 0x50, v40
	v_lshl_add_u32 v2, v18, 6, v42
	ds_read_b32 v2, v2
	v_ashrrev_i32_e32 v19, 31, v18
	v_lshl_add_u64 v[18:19], s[12:13], 0, v[18:19]
	v_lshlrev_b64 v[18:19], 11, v[18:19]
	v_lshl_add_u64 v[18:19], v[38:39], 0, v[18:19]
	s_waitcnt lgkmcnt(0)
	v_fma_f32 v2, v1, v2, v14
	v_mul_f32_e32 v14, 0x3d372713, v2
	v_mul_f32_e32 v14, v2, v14
	v_fma_f32 v14, v2, v14, v2
	v_mul_f32_e32 v14, 0x3f4c422a, v14
	v_add_f32_e32 v14, v14, v14
	v_mul_f32_e32 v14, 0xbfb8aa3b, v14
	v_exp_f32_e32 v14, v14
	s_nop 0
	v_add_f32_e32 v14, 1.0, v14
	v_rcp_f32_e32 v14, v14
	s_nop 0
	v_mul_f32_e32 v2, v2, v14
	v_cvt_pk_bf16_f32 v2, v2, s0
	v_add_u32_e32 v14, 0x51, v40
	global_store_short v[18:19], v2, off
	v_lshl_add_u32 v2, v14, 6, v42
	ds_read_b32 v2, v2
	s_waitcnt lgkmcnt(0)
; DI bf16 f2bf(float f) { return (bf16)(pk2(f, 0.f) & 0xffffu); }
; DI float gelu_tanh(float x) { const float u = 0.7978845608028654f * (x + 0.044715f * x * x * x); return x * sigm(2.0f * u); }
; DI void s5_passC(const Ctx& C, const S5P& P, const bf16* PROJ, const f32x2* END, bf16* YG  , int item_lo, int item_hi) {
;     ...
;         const float dv = P.d[g * 16 + (lane & 15)];
; #pragma unroll
;         for (int r = 0; r < 8; ++r)
; #pragma unroll
;             for (int j = 0; j < 4; ++j) { const int t = 16 * r + (lane >> 4) * 4 + j; const float y = acc[r][j] + dv * UF[t * 16 + (lane & 15)]; YG[(tok0 + t) * 1024 + g * 16 + (lane & 15)] = f2bf(gelu_tanh(y)); }
;         asm volatile("s_waitcnt lgkmcnt(0)" ::: "memory");
	v_fma_f32 v2, v1, v2, v15
	v_mul_f32_e32 v15, 0x3d372713, v2
	v_mul_f32_e32 v15, v2, v15
	v_fma_f32 v15, v2, v15, v2
	v_mul_f32_e32 v15, 0x3f4c422a, v15
	v_add_f32_e32 v15, v15, v15
	v_mul_f32_e32 v15, 0xbfb8aa3b, v15
	v_exp_f32_e32 v15, v15
	s_nop 0
	v_add_f32_e32 v15, 1.0, v15
	v_rcp_f32_e32 v15, v15
	s_nop 0
	v_mul_f32_e32 v2, v2, v15
	v_ashrrev_i32_e32 v15, 31, v14
	v_lshl_add_u64 v[14:15], s[12:13], 0, v[14:15]
	v_lshlrev_b64 v[14:15], 11, v[14:15]
	v_cvt_pk_bf16_f32 v2, v2, s0
	v_lshl_add_u64 v[14:15], v[38:39], 0, v[14:15]
	global_store_short v[14:15], v2, off
	v_add_u32_e32 v14, 0x52, v40
	v_lshl_add_u32 v2, v14, 6, v42
	ds_read_b32 v2, v2
	s_waitcnt lgkmcnt(0)
	v_fma_f32 v2, v1, v2, v16
	v_mul_f32_e32 v15, 0x3d372713, v2
	v_mul_f32_e32 v15, v2, v15
	v_fma_f32 v15, v2, v15, v2
	v_mul_f32_e32 v15, 0x3f4c422a, v15
	v_add_f32_e32 v15, v15, v15
	v_mul_f32_e32 v15, 0xbfb8aa3b, v15
	v_exp_f32_e32 v15, v15
	s_nop 0
	v_add_f32_e32 v15, 1.0, v15
	v_rcp_f32_e32 v15, v15
	s_nop 0
	v_mul_f32_e32 v2, v2, v15
	v_ashrrev_i32_e32 v15, 31, v14
	v_lshl_add_u64 v[14:15], s[12:13], 0, v[14:15]
	v_lshlrev_b64 v[14:15], 11, v[14:15]
	v_cvt_pk_bf16_f32 v2, v2, s0
	v_lshl_add_u64 v[14:15], v[38:39], 0, v[14:15]
	global_store_short v[14:15], v2, off
	v_add_u32_e32 v14, 0x53, v40
	v_lshl_add_u32 v2, v14, 6, v42
	ds_read_b32 v2, v2
	v_ashrrev_i32_e32 v15, 31, v14
	v_lshl_add_u64 v[14:15], s[12:13], 0, v[14:15]
	v_lshlrev_b64 v[14:15], 11, v[14:15]
	v_lshl_add_u64 v[14:15], v[38:39], 0, v[14:15]
	s_waitcnt lgkmcnt(0)
	v_fmac_f32_e32 v17, v1, v2
	v_mul_f32_e32 v2, 0x3d372713, v17
	v_mul_f32_e32 v2, v17, v2
	v_fma_f32 v2, v17, v2, v17
	v_mul_f32_e32 v2, 0x3f4c422a, v2
	v_add_f32_e32 v2, v2, v2
	v_mul_f32_e32 v2, 0xbfb8aa3b, v2
	v_exp_f32_e32 v2, v2
	s_nop 0
	v_add_f32_e32 v2, 1.0, v2
	v_rcp_f32_e32 v2, v2
	s_nop 0
	v_mul_f32_e32 v2, v17, v2
	v_cvt_pk_bf16_f32 v2, v2, s0
	global_store_short v[14:15], v2, off
	v_add_u32_e32 v14, 0x60, v40
	v_lshl_add_u32 v2, v14, 6, v42
	ds_read_b32 v2, v2
	v_ashrrev_i32_e32 v15, 31, v14
	v_lshl_add_u64 v[14:15], s[12:13], 0, v[14:15]
	v_lshlrev_b64 v[14:15], 11, v[14:15]
	v_lshl_add_u64 v[14:15], v[38:39], 0, v[14:15]
	s_waitcnt lgkmcnt(0)
	v_fma_f32 v2, v1, v2, v10
	v_mul_f32_e32 v10, 0x3d372713, v2
	v_mul_f32_e32 v10, v2, v10
	v_fma_f32 v10, v2, v10, v2
	v_mul_f32_e32 v10, 0x3f4c422a, v10
	v_add_f32_e32 v10, v10, v10
	v_mul_f32_e32 v10, 0xbfb8aa3b, v10
	v_exp_f32_e32 v10, v10
	s_nop 0
	v_add_f32_e32 v10, 1.0, v10
	v_rcp_f32_e32 v10, v10
	s_nop 0
	v_mul_f32_e32 v2, v2, v10
	v_cvt_pk_bf16_f32 v2, v2, s0
	v_add_u32_e32 v10, 0x61, v40
	global_store_short v[14:15], v2, off
	v_lshl_add_u32 v2, v10, 6, v42
	ds_read_b32 v2, v2
	s_waitcnt lgkmcnt(0)
	v_fma_f32 v2, v1, v2, v11
	v_mul_f32_e32 v11, 0x3d372713, v2
	v_mul_f32_e32 v11, v2, v11
	v_fma_f32 v11, v2, v11, v2
	v_mul_f32_e32 v11, 0x3f4c422a, v11
	v_add_f32_e32 v11, v11, v11
	v_mul_f32_e32 v11, 0xbfb8aa3b, v11
	v_exp_f32_e32 v11, v11
	s_nop 0
	v_add_f32_e32 v11, 1.0, v11
	v_rcp_f32_e32 v11, v11
	s_nop 0
	v_mul_f32_e32 v2, v2, v11
	v_ashrrev_i32_e32 v11, 31, v10
	v_lshl_add_u64 v[10:11], s[12:13], 0, v[10:11]
	v_lshlrev_b64 v[10:11], 11, v[10:11]
	v_cvt_pk_bf16_f32 v2, v2, s0
	v_lshl_add_u64 v[10:11], v[38:39], 0, v[10:11]
	global_store_short v[10:11], v2, off
	v_add_u32_e32 v10, 0x62, v40
	v_lshl_add_u32 v2, v10, 6, v42
	ds_read_b32 v2, v2
	s_waitcnt lgkmcnt(0)
; DI bf16 f2bf(float f) { return (bf16)(pk2(f, 0.f) & 0xffffu); }
; DI float gelu_tanh(float x) { const float u = 0.7978845608028654f * (x + 0.044715f * x * x * x); return x * sigm(2.0f * u); }
; DI void s5_passC(const Ctx& C, const S5P& P, const bf16* PROJ, const f32x2* END, bf16* YG  , int item_lo, int item_hi) {
;     ...
;         const float dv = P.d[g * 16 + (lane & 15)];
; #pragma unroll
;         for (int r = 0; r < 8; ++r)
; #pragma unroll
;             for (int j = 0; j < 4; ++j) { const int t = 16 * r + (lane >> 4) * 4 + j; const float y = acc[r][j] + dv * UF[t * 16 + (lane & 15)]; YG[(tok0 + t) * 1024 + g * 16 + (lane & 15)] = f2bf(gelu_tanh(y)); }
;         asm volatile("s_waitcnt lgkmcnt(0)" ::: "memory");
	v_fma_f32 v2, v1, v2, v12
	v_mul_f32_e32 v11, 0x3d372713, v2
	v_mul_f32_e32 v11, v2, v11
	v_fma_f32 v11, v2, v11, v2
	v_mul_f32_e32 v11, 0x3f4c422a, v11
	v_add_f32_e32 v11, v11, v11
	v_mul_f32_e32 v11, 0xbfb8aa3b, v11
	v_exp_f32_e32 v11, v11
	s_nop 0
	v_add_f32_e32 v11, 1.0, v11
	v_rcp_f32_e32 v11, v11
	s_nop 0
	v_mul_f32_e32 v2, v2, v11
	v_ashrrev_i32_e32 v11, 31, v10
	v_lshl_add_u64 v[10:11], s[12:13], 0, v[10:11]
	v_lshlrev_b64 v[10:11], 11, v[10:11]
	v_cvt_pk_bf16_f32 v2, v2, s0
	v_lshl_add_u64 v[10:11], v[38:39], 0, v[10:11]
	global_store_short v[10:11], v2, off
	v_add_u32_e32 v10, 0x63, v40
	v_lshl_add_u32 v2, v10, 6, v42
	ds_read_b32 v2, v2
	v_ashrrev_i32_e32 v11, 31, v10
	v_lshl_add_u64 v[10:11], s[12:13], 0, v[10:11]
	v_lshlrev_b64 v[10:11], 11, v[10:11]
	v_lshl_add_u64 v[10:11], v[38:39], 0, v[10:11]
	s_waitcnt lgkmcnt(0)
	v_fmac_f32_e32 v13, v1, v2
	v_mul_f32_e32 v2, 0x3d372713, v13
	v_mul_f32_e32 v2, v13, v2
	v_fma_f32 v2, v13, v2, v13
	v_mul_f32_e32 v2, 0x3f4c422a, v2
	v_add_f32_e32 v2, v2, v2
	v_mul_f32_e32 v2, 0xbfb8aa3b, v2
	v_exp_f32_e32 v2, v2
	s_nop 0
	v_add_f32_e32 v2, 1.0, v2
	v_rcp_f32_e32 v2, v2
	s_nop 0
	v_mul_f32_e32 v2, v13, v2
	v_cvt_pk_bf16_f32 v2, v2, s0
	global_store_short v[10:11], v2, off
	v_add_u32_e32 v10, 0x70, v40
	v_lshl_add_u32 v2, v10, 6, v42
	ds_read_b32 v2, v2
	v_ashrrev_i32_e32 v11, 31, v10
	v_lshl_add_u64 v[10:11], s[12:13], 0, v[10:11]
	v_lshlrev_b64 v[10:11], 11, v[10:11]
	v_lshl_add_u64 v[10:11], v[38:39], 0, v[10:11]
	s_waitcnt lgkmcnt(0)
	v_fma_f32 v2, v1, v2, v6
	v_mul_f32_e32 v6, 0x3d372713, v2
	v_mul_f32_e32 v6, v2, v6
	v_fma_f32 v6, v2, v6, v2
	v_mul_f32_e32 v6, 0x3f4c422a, v6
	v_add_f32_e32 v6, v6, v6
	v_mul_f32_e32 v6, 0xbfb8aa3b, v6
	v_exp_f32_e32 v6, v6
	s_nop 0
	v_add_f32_e32 v6, 1.0, v6
	v_rcp_f32_e32 v6, v6
	s_nop 0
	v_mul_f32_e32 v2, v2, v6
	v_cvt_pk_bf16_f32 v2, v2, s0
	v_add_u32_e32 v6, 0x71, v40
	global_store_short v[10:11], v2, off
	v_lshl_add_u32 v2, v6, 6, v42
	ds_read_b32 v2, v2
	s_waitcnt lgkmcnt(0)
	v_fma_f32 v2, v1, v2, v7
	v_mul_f32_e32 v7, 0x3d372713, v2
	v_mul_f32_e32 v7, v2, v7
	v_fma_f32 v7, v2, v7, v2
	v_mul_f32_e32 v7, 0x3f4c422a, v7
	v_add_f32_e32 v7, v7, v7
	v_mul_f32_e32 v7, 0xbfb8aa3b, v7
	v_exp_f32_e32 v7, v7
	s_nop 0
	v_add_f32_e32 v7, 1.0, v7
	v_rcp_f32_e32 v7, v7
	s_nop 0
	v_mul_f32_e32 v2, v2, v7
	v_ashrrev_i32_e32 v7, 31, v6
	v_lshl_add_u64 v[6:7], s[12:13], 0, v[6:7]
	v_lshlrev_b64 v[6:7], 11, v[6:7]
	v_cvt_pk_bf16_f32 v2, v2, s0
	v_lshl_add_u64 v[6:7], v[38:39], 0, v[6:7]
	global_store_short v[6:7], v2, off
	v_add_u32_e32 v6, 0x72, v40
	v_lshl_add_u32 v2, v6, 6, v42
	ds_read_b32 v2, v2
	s_waitcnt lgkmcnt(0)
	v_fma_f32 v2, v1, v2, v8
	v_mul_f32_e32 v7, 0x3d372713, v2
	v_mul_f32_e32 v7, v2, v7
	v_fma_f32 v7, v2, v7, v2
	v_mul_f32_e32 v7, 0x3f4c422a, v7
	v_add_f32_e32 v7, v7, v7
	v_mul_f32_e32 v7, 0xbfb8aa3b, v7
	v_exp_f32_e32 v7, v7
	s_nop 0
	v_add_f32_e32 v7, 1.0, v7
	v_rcp_f32_e32 v7, v7
	s_nop 0
	v_mul_f32_e32 v2, v2, v7
	v_ashrrev_i32_e32 v7, 31, v6
	v_lshl_add_u64 v[6:7], s[12:13], 0, v[6:7]
	v_lshlrev_b64 v[6:7], 11, v[6:7]
	v_cvt_pk_bf16_f32 v2, v2, s0
	v_lshl_add_u64 v[6:7], v[38:39], 0, v[6:7]
	global_store_short v[6:7], v2, off
	v_add_u32_e32 v6, 0x73, v40
	v_lshl_add_u32 v2, v6, 6, v42
	ds_read_b32 v2, v2
	v_ashrrev_i32_e32 v7, 31, v6
	v_lshl_add_u64 v[6:7], s[12:13], 0, v[6:7]
	v_lshlrev_b64 v[6:7], 11, v[6:7]
	v_lshl_add_u64 v[6:7], v[38:39], 0, v[6:7]
	s_waitcnt lgkmcnt(0)
	v_fmac_f32_e32 v9, v1, v2
	v_mul_f32_e32 v1, 0x3d372713, v9
	v_mul_f32_e32 v1, v9, v1
	v_fma_f32 v1, v9, v1, v9
	v_mul_f32_e32 v1, 0x3f4c422a, v1
	v_add_f32_e32 v1, v1, v1
	v_mul_f32_e32 v1, 0xbfb8aa3b, v1
	v_exp_f32_e32 v1, v1
	s_nop 0
	v_add_f32_e32 v1, 1.0, v1
	v_rcp_f32_e32 v1, v1
	s_nop 0
	v_mul_f32_e32 v1, v9, v1
	v_cvt_pk_bf16_f32 v1, v1, s0
	global_store_short v[6:7], v1, off
	s_waitcnt lgkmcnt(0)
	v_readlane_b32 s0, v255, 52
	s_add_i32 s30, s30, s0
	s_cmpk_lt_i32 s30, 0x1800
	s_cbranch_scc1 .LBB0_606

; DI void s5_disc(const S5P& P, int dir, int g, int p, float& lr, float& li, f32x2 (&bb)[16]) {
;     const float dt = expf(P.log_dt[dir * 64 + g]); const float are = P.a_re[(dir * 64 + g) * 64 + p], aim = P.a_im[(dir * 64 + g) * 64 + p];
;     const float mag = expf(dt * are); lr = mag * cosf(dt * aim); li = mag * sinf(dt * aim);
;     const float den = are * are + aim * aim, nr = lr - 1.0f; const float cr = (nr * are + li * aim) / den, ci = (li * are - nr * aim) / den;
;     const f32x4* br = (const f32x4*)(P.b_re + (size_t)(g * 64 + p) * 16); const f32x4* bi = (const f32x4*)(P.b_im + (size_t)(g * 64 + p) * 16);
; #pragma unroll
;     for (int q = 0; q < 4; ++q) { const f32x4 r = br[q], i = bi[q];
; #pragma unroll
;         for (int e = 0; e < 4; ++e) bb[4 * q + e] = (f32x2){cr * r[e] - ci * i[e], cr * i[e] + ci * r[e]}; }
.LBB0_696:
	v_add_f32_e32 v140, -1.0, v136
	v_mov_b32_e32 v2, v73
	v_pk_mul_f32 v[74:75], v[72:73], v[72:73]
	v_pk_mul_f32 v[76:77], v[2:3], v[140:141] op_sel:[0,1] op_sel_hi:[0,0]
	v_pk_fma_f32 v[78:79], v[72:73], v[140:141], v[76:77]
	v_pk_fma_f32 v[72:73], v[72:73], v[140:141], v[76:77] op_sel_hi:[0,1,1] neg_lo:[0,0,1] neg_hi:[0,0,1]
	v_pk_add_f32 v[74:75], v[74:75], v[74:75] op_sel:[0,1] op_sel_hi:[0,1]
	v_div_scale_f32 v2, s[0:1], v75, v75, v73
	v_rcp_f32_e32 v71, v2
	s_waitcnt vmcnt(3)
	v_mov_b32_e32 v128, v13
	v_mov_b32_e32 v129, v13
	v_mov_b32_e32 v124, v9
	v_fma_f32 v72, -v2, v71, 1.0
	v_fmac_f32_e32 v71, v72, v71
	v_div_scale_f32 v72, vcc, v73, v75, v73
	v_mul_f32_e32 v76, v72, v71
	v_fma_f32 v77, -v2, v76, v72
	v_fmac_f32_e32 v76, v77, v71
	v_fma_f32 v2, -v2, v76, v72
	v_div_fmas_f32 v2, v2, v71, v76
	v_div_fixup_f32 v73, v2, v75, v73
	v_div_scale_f32 v2, s[0:1], v74, v74, v78
	v_rcp_f32_e32 v71, v2
	v_mov_b32_e32 v125, v9
	s_waitcnt vmcnt(0)
	v_mov_b32_e32 v132, v34
	v_mov_b32_e32 v133, v34
	v_fma_f32 v72, -v2, v71, 1.0
	v_fmac_f32_e32 v71, v72, v71
	v_div_scale_f32 v72, vcc, v78, v74, v78
	v_mul_f32_e32 v75, v72, v71
	v_fma_f32 v76, -v2, v75, v72
	v_fmac_f32_e32 v75, v76, v71
	v_fma_f32 v2, -v2, v75, v72
	v_div_fmas_f32 v2, v2, v71, v75
	v_div_fixup_f32 v72, v2, v74, v78
	v_mov_b32_e32 v76, v13
	v_mov_b32_e32 v2, v9
	v_pk_mul_f32 v[76:77], v[76:77], v[72:73] op_sel_hi:[0,1]
	v_pk_fma_f32 v[174:175], v[2:3], v[72:73], v[76:77] op_sel:[0,0,1] op_sel_hi:[0,1,0] neg_lo:[0,0,1] neg_hi:[0,0,1]
	v_pk_fma_f32 v[76:77], v[2:3], v[72:73], v[76:77] op_sel:[0,0,1] op_sel_hi:[0,1,0]
	v_mov_b32_e32 v175, v77
	v_pk_mul_f32 v[76:77], v[34:35], v[72:73] op_sel_hi:[0,1]
	v_pk_fma_f32 v[176:177], v[30:31], v[72:73], v[76:77] op_sel:[0,0,1] op_sel_hi:[1,1,0] neg_lo:[0,0,1] neg_hi:[0,0,1]
	v_pk_fma_f32 v[76:77], v[30:31], v[72:73], v[76:77] op_sel:[0,0,1] op_sel_hi:[0,1,0]
	v_mov_b32_e32 v177, v77
	v_pk_mul_f32 v[76:77], v[36:37], v[72:73] op_sel_hi:[0,1]
	v_pk_fma_f32 v[180:181], v[32:33], v[72:73], v[76:77] op_sel:[0,0,1] op_sel_hi:[1,1,0] neg_lo:[0,0,1] neg_hi:[0,0,1]
	v_pk_fma_f32 v[76:77], v[32:33], v[72:73], v[76:77] op_sel:[0,0,1] op_sel_hi:[0,1,0]
	v_mov_b32_e32 v76, v37
	v_mov_b32_e32 v181, v77
	v_mov_b32_e32 v2, v33
	v_pk_mul_f32 v[76:77], v[76:77], v[72:73] op_sel_hi:[0,1]
	v_pk_fma_f32 v[182:183], v[2:3], v[72:73], v[76:77] op_sel:[0,0,1] op_sel_hi:[0,1,0] neg_lo:[0,0,1] neg_hi:[0,0,1]
	v_pk_fma_f32 v[76:77], v[2:3], v[72:73], v[76:77] op_sel:[0,0,1] op_sel_hi:[0,1,0]
	v_mov_b32_e32 v183, v77
	v_pk_mul_f32 v[76:77], v[26:27], v[72:73] op_sel_hi:[0,1]
	v_pk_fma_f32 v[184:185], v[22:23], v[72:73], v[76:77] op_sel:[0,0,1] op_sel_hi:[1,1,0] neg_lo:[0,0,1] neg_hi:[0,0,1]
	v_pk_fma_f32 v[76:77], v[22:23], v[72:73], v[76:77] op_sel:[0,0,1] op_sel_hi:[0,1,0]
	v_mov_b32_e32 v76, v27
	v_mov_b32_e32 v185, v77
	v_mov_b32_e32 v2, v23
	v_pk_mul_f32 v[76:77], v[76:77], v[72:73] op_sel_hi:[0,1]
	v_pk_fma_f32 v[186:187], v[2:3], v[72:73], v[76:77] op_sel:[0,0,1] op_sel_hi:[0,1,0] neg_lo:[0,0,1] neg_hi:[0,0,1]
	v_pk_fma_f32 v[76:77], v[2:3], v[72:73], v[76:77] op_sel:[0,0,1] op_sel_hi:[0,1,0]
	v_mov_b32_e32 v187, v77
	v_pk_mul_f32 v[76:77], v[28:29], v[72:73] op_sel_hi:[0,1]
	v_pk_fma_f32 v[188:189], v[24:25], v[72:73], v[76:77] op_sel:[0,0,1] op_sel_hi:[1,1,0] neg_lo:[0,0,1] neg_hi:[0,0,1]
	v_pk_fma_f32 v[76:77], v[24:25], v[72:73], v[76:77] op_sel:[0,0,1] op_sel_hi:[0,1,0]
	v_mov_b32_e32 v76, v29
	v_mov_b32_e32 v189, v77
	v_mov_b32_e32 v2, v25
	v_pk_mul_f32 v[76:77], v[76:77], v[72:73] op_sel_hi:[0,1]
	v_pk_fma_f32 v[190:191], v[2:3], v[72:73], v[76:77] op_sel:[0,0,1] op_sel_hi:[0,1,0] neg_lo:[0,0,1] neg_hi:[0,0,1]
	v_pk_fma_f32 v[76:77], v[2:3], v[72:73], v[76:77] op_sel:[0,0,1] op_sel_hi:[0,1,0]
	v_mov_b32_e32 v191, v77
	v_pk_mul_f32 v[76:77], v[18:19], v[72:73] op_sel_hi:[0,1]
	v_pk_fma_f32 v[192:193], v[14:15], v[72:73], v[76:77] op_sel:[0,0,1] op_sel_hi:[1,1,0] neg_lo:[0,0,1] neg_hi:[0,0,1]
	v_pk_fma_f32 v[76:77], v[14:15], v[72:73], v[76:77] op_sel:[0,0,1] op_sel_hi:[0,1,0]
	v_mov_b32_e32 v76, v19
	v_mov_b32_e32 v193, v77
	v_mov_b32_e32 v2, v15
	v_pk_mul_f32 v[76:77], v[76:77], v[72:73] op_sel_hi:[0,1]
	v_pk_fma_f32 v[194:195], v[2:3], v[72:73], v[76:77] op_sel:[0,0,1] op_sel_hi:[0,1,0] neg_lo:[0,0,1] neg_hi:[0,0,1]
	v_pk_fma_f32 v[76:77], v[2:3], v[72:73], v[76:77] op_sel:[0,0,1] op_sel_hi:[0,1,0]
	v_mov_b32_e32 v195, v77
	v_pk_mul_f32 v[76:77], v[20:21], v[72:73] op_sel_hi:[0,1]
	v_pk_fma_f32 v[196:197], v[16:17], v[72:73], v[76:77] op_sel:[0,0,1] op_sel_hi:[1,1,0] neg_lo:[0,0,1] neg_hi:[0,0,1]
	v_pk_fma_f32 v[76:77], v[16:17], v[72:73], v[76:77] op_sel:[0,0,1] op_sel_hi:[0,1,0]
	v_mov_b32_e32 v76, v21
	v_mov_b32_e32 v197, v77
	v_mov_b32_e32 v2, v17
	v_pk_mul_f32 v[76:77], v[76:77], v[72:73] op_sel_hi:[0,1]
	v_pk_fma_f32 v[198:199], v[2:3], v[72:73], v[76:77] op_sel:[0,0,1] op_sel_hi:[0,1,0] neg_lo:[0,0,1] neg_hi:[0,0,1]
	v_pk_fma_f32 v[76:77], v[2:3], v[72:73], v[76:77] op_sel:[0,0,1] op_sel_hi:[0,1,0]
	v_mov_b32_e32 v199, v77
	v_pk_mul_f32 v[76:77], v[10:11], v[72:73] op_sel_hi:[0,1]
	v_pk_fma_f32 v[200:201], v[6:7], v[72:73], v[76:77] op_sel:[0,0,1] op_sel_hi:[1,1,0] neg_lo:[0,0,1] neg_hi:[0,0,1]
	v_pk_fma_f32 v[76:77], v[6:7], v[72:73], v[76:77] op_sel:[0,0,1] op_sel_hi:[0,1,0]
	v_mov_b32_e32 v76, v11
	v_mov_b32_e32 v201, v77
	v_mov_b32_e32 v2, v7
	v_pk_mul_f32 v[76:77], v[76:77], v[72:73] op_sel_hi:[0,1]
	v_pk_fma_f32 v[202:203], v[2:3], v[72:73], v[76:77] op_sel:[0,0,1] op_sel_hi:[0,1,0] neg_lo:[0,0,1] neg_hi:[0,0,1]
	v_pk_fma_f32 v[76:77], v[2:3], v[72:73], v[76:77] op_sel:[0,0,1] op_sel_hi:[0,1,0]
	v_mov_b32_e32 v13, v12
; #define LAS __attribute__((address_space(3)))
; DI unsigned pk2(float lo, float hi) { return pg8::cvt_pk_bf16(lo, hi); }
; template <int DIRN, int SUB> DI void s5_subtile(const LAS float* UF, LAS bf16* XT, float lr, float li, const f32x2 (&bb)[16], f32x2& x,
;                                                 const bf16x8 (&bfr)[4], f32x4& acc0, f32x4& acc1, int lane) {
;     ...
;     for (int i = 0; i < 32; ++i) { const int r = DIRN ? 31 - i : i;
;         x = s5_step((const LAS f32x4*)(UF + (32 * SUB + r) * 16), bb, lr, li, x);
;         const unsigned pkd = pk2(x.x, x.y); XT[r * 136 + lane] = (bf16)(pkd & 0xffffu); XT[r * 136 + 64 + lane] = (bf16)(pkd >> 16); }
	v_mov_b32_e32 v74, v8
	v_mov_b32_e32 v75, v9
	v_mov_b32_e32 v134, v35
	v_mov_b32_e32 v135, v35
	v_pk_mul_f32 v[34:35], v[34:35], v[72:73] op_sel:[1,0]
	v_mov_b32_e32 v203, v77
	v_mov_b32_e32 v9, v8
	v_pk_mul_f32 v[76:77], v[12:13], v[72:73] op_sel_hi:[0,1]
	v_mov_b32_e32 v126, v30
	v_mov_b32_e32 v127, v30
	v_mov_b32_e32 v130, v31
	v_mov_b32_e32 v131, v31
	v_pk_fma_f32 v[178:179], v[30:31], v[72:73], v[34:35] op_sel:[1,0,1] op_sel_hi:[1,1,0] neg_lo:[0,0,1] neg_hi:[0,0,1]
	v_pk_fma_f32 v[30:31], v[30:31], v[72:73], v[34:35] op_sel:[1,0,1] op_sel_hi:[1,1,0]
	v_pk_fma_f32 v[204:205], v[74:75], v[72:73], v[76:77] op_sel:[0,0,1] op_sel_hi:[1,1,0] neg_lo:[0,0,1] neg_hi:[0,0,1]
	v_pk_fma_f32 v[72:73], v[8:9], v[72:73], v[76:77] op_sel:[0,0,1] op_sel_hi:[0,1,0]
	v_lshlrev_b32_e32 v206, 1, v0
	v_mov_b32_e32 v179, v31
	v_mov_b32_e32 v30, v32
	v_mov_b32_e32 v31, v32
	v_mov_b32_e32 v34, v36
	v_mov_b32_e32 v35, v36
	v_mov_b32_e32 v32, v33
	v_mov_b32_e32 v36, v37
	v_mov_b32_e32 v138, v22
	v_mov_b32_e32 v139, v22
	v_mov_b32_e32 v142, v26
	v_mov_b32_e32 v143, v26
	v_mov_b32_e32 v22, v23
	v_mov_b32_e32 v26, v27
	v_mov_b32_e32 v144, v24
	v_mov_b32_e32 v145, v24
	v_mov_b32_e32 v146, v28
	v_mov_b32_e32 v147, v28
	v_mov_b32_e32 v24, v25
	v_mov_b32_e32 v28, v29
	v_mov_b32_e32 v148, v14
	v_mov_b32_e32 v149, v14
	v_mov_b32_e32 v162, v18
	v_mov_b32_e32 v163, v18
	v_mov_b32_e32 v14, v15
	v_mov_b32_e32 v18, v19
	v_mov_b32_e32 v164, v16
	v_mov_b32_e32 v165, v16
	v_mov_b32_e32 v166, v20
	v_mov_b32_e32 v167, v20
	v_mov_b32_e32 v16, v17
	v_mov_b32_e32 v20, v21
	v_mov_b32_e32 v168, v6
	v_mov_b32_e32 v169, v6
	v_mov_b32_e32 v170, v10
	v_mov_b32_e32 v171, v10
	v_mov_b32_e32 v6, v7
	v_mov_b32_e32 v10, v11
	v_mov_b32_e32 v205, v73
	v_mov_b32_e32 v137, v136
	v_xor_b32_e32 v140, 0x80000000, v141
	v_add_u32_e32 v2, 0x2000, v206
	s_mov_b32 s0, 0
	s_add_i32 s1, s49, s0
	v_mov_b32_e32 v250, s1
	ds_read_b128 v[246:249], v250
	s_waitcnt lgkmcnt(0)
.LBB0_697:
	s_add_i32 s1, s49, s0
	v_mov_b32_e32 v71, s1
	ds_read_b128 v[76:79], v71 offset:16
	ds_read_b128 v[80:83], v71 offset:32
	ds_read_b128 v[84:87], v71 offset:48
	s_waitcnt lgkmcnt(5)
	v_pk_mul_f32 v[88:89], v[178:179], v[246:247] op_sel:[0,1]
	v_pk_fma_f32 v[72:73], v[176:177], v[246:247], v[88:89] op_sel_hi:[1,0,1]
	v_pk_fma_f32 v[72:73], v[180:181], v[248:249], v[72:73] op_sel_hi:[1,0,1]
	v_pk_fma_f32 v[72:73], v[182:183], v[248:249], v[72:73] op_sel:[0,1,0]
	s_add_i32 s1, s49, s0
	s_add_i32 s1, s1, 64
	v_mov_b32_e32 v250, s1
	ds_read_b128 v[246:249], v250
	s_waitcnt lgkmcnt(3)
	v_pk_fma_f32 v[72:73], v[184:185], v[76:77], v[72:73] op_sel_hi:[1,0,1]
	v_pk_fma_f32 v[72:73], v[186:187], v[76:77], v[72:73] op_sel:[0,1,0]
	s_waitcnt lgkmcnt(2)
	v_pk_fma_f32 v[72:73], v[188:189], v[78:79], v[72:73] op_sel_hi:[1,0,1]
	v_pk_fma_f32 v[72:73], v[190:191], v[78:79], v[72:73] op_sel:[0,1,0]
	v_pk_mul_f32 v[74:75], v[194:195], v[80:81] op_sel:[0,1]
	v_pk_fma_f32 v[74:75], v[192:193], v[80:81], v[74:75] op_sel_hi:[1,0,1]
	v_pk_fma_f32 v[74:75], v[196:197], v[82:83], v[74:75] op_sel_hi:[1,0,1]
	v_pk_fma_f32 v[74:75], v[198:199], v[82:83], v[74:75] op_sel:[0,1,0]
	s_waitcnt lgkmcnt(1)
	v_mov_b32_e32 v76, v87
	v_pk_fma_f32 v[74:75], v[200:201], v[84:85], v[74:75] op_sel_hi:[1,0,1]
	v_pk_fma_f32 v[74:75], v[202:203], v[84:85], v[74:75] op_sel:[0,1,0]
	v_pk_fma_f32 v[74:75], v[204:205], v[86:87], v[74:75] op_sel_hi:[1,0,1]
	v_pk_fma_f32 v[74:75], v[174:175], v[76:77], v[74:75] op_sel_hi:[1,0,1]
	v_pk_add_f32 v[72:73], v[72:73], v[74:75]
	v_pk_fma_f32 v[72:73], v[140:141], v[172:173], v[72:73] op_sel:[0,1,0] op_sel_hi:[1,0,1]
	v_pk_fma_f32 v[172:173], v[136:137], v[172:173], v[72:73]
	v_add_u32_e32 v73, s49, v2
	v_cvt_pk_bf16_f32 v71, v172, s0
	v_cvt_pk_bf16_f32 v72, v173, s0
	s_add_i32 s0, s0, 64
	v_add_u32_e32 v2, 0x110, v2
	s_cmpk_lg_i32 s0, 0x800
	ds_write_b16 v73, v71
	ds_write_b16 v73, v72 offset:128
	s_cbranch_scc1 .LBB0_697
	v_and_b32_e32 v123, 15, v0
	v_mul_u32_u24_e32 v2, 0x110, v123
	v_lshlrev_b32_e32 v70, 1, v70
	v_add3_u32 v152, s49, v2, v70
	ds_read_b128 v[98:101], v152 offset:8192
	ds_read_b128 v[94:97], v152 offset:8256
	ds_read_b128 v[82:85], v152 offset:12544
	ds_read_b128 v[86:89], v152 offset:12608
	ds_read_b128 v[90:93], v152 offset:8320
	ds_read_b128 v[78:81], v152 offset:8384
	ds_read_b128 v[70:73], v152 offset:12672
	ds_read_b128 v[74:77], v152 offset:12736
	v_add_u32_e32 v2, s35, v206
	s_mov_b32 s0, 0
	v_mov_b32_e32 v102, v2
	s_add_i32 s1, s40, s0
	v_mov_b32_e32 v250, s1
	ds_read_b128 v[246:249], v250
	s_waitcnt lgkmcnt(0)
; #define LAS __attribute__((address_space(3)))
; DI unsigned pk2(float lo, float hi) { return pg8::cvt_pk_bf16(lo, hi); }
; DI f32x4 mfma16(bf16x8 a, bf16x8 b, f32x4 c) { return __builtin_amdgcn_mfma_f32_16x16x32_bf16(a, b, c, 0, 0, 0); }
; template <int DIRN, int SUB> DI void s5_subtile(const LAS float* UF, LAS bf16* XT, float lr, float li, const f32x2 (&bb)[16], f32x2& x,
;                                                 const bf16x8 (&bfr)[4], f32x4& acc0, f32x4& acc1, int lane) {
;     ...
;     for (int i = 0; i < 32; ++i) { const int r = DIRN ? 31 - i : i;
;         x = s5_step((const LAS f32x4*)(UF + (32 * SUB + r) * 16), bb, lr, li, x);
;         const unsigned pkd = pk2(x.x, x.y); XT[r * 136 + lane] = (bf16)(pkd & 0xffffu); XT[r * 136 + 64 + lane] = (bf16)(pkd >> 16); }
; #pragma unroll
;     for (int ks = 0; ks < 4; ++ks) { const bf16x8 a0 = *(const LAS bf16x8*)(XT + (lane & 15) * 136 + 32 * ks + 8 * (lane >> 4)), a1 = *(const LAS bf16x8*)(XT + (16 + (lane & 15)) * 136 + 32 * ks + 8 * (lane >> 4));
;         acc0 = mfma16(a0, bfr[ks], acc0); acc1 = mfma16(a1, bfr[ks], acc1); }
.LBB0_699:
	s_add_i32 s1, s40, s0
	v_mov_b32_e32 v103, s1
	ds_read_b128 v[108:111], v103 offset:16
	ds_read_b128 v[112:115], v103 offset:32
	ds_read_b128 v[116:119], v103 offset:48
	s_waitcnt lgkmcnt(5)
	v_pk_mul_f32 v[120:121], v[178:179], v[246:247] op_sel:[0,1]
	v_pk_fma_f32 v[104:105], v[176:177], v[246:247], v[120:121] op_sel_hi:[1,0,1]
	v_pk_fma_f32 v[104:105], v[180:181], v[248:249], v[104:105] op_sel_hi:[1,0,1]
	v_pk_fma_f32 v[104:105], v[182:183], v[248:249], v[104:105] op_sel:[0,1,0]
	s_add_i32 s1, s40, s0
	s_add_i32 s1, s1, 64
	v_mov_b32_e32 v250, s1
	ds_read_b128 v[246:249], v250
	s_waitcnt lgkmcnt(3)
	v_pk_fma_f32 v[104:105], v[184:185], v[108:109], v[104:105] op_sel_hi:[1,0,1]
	v_pk_fma_f32 v[104:105], v[186:187], v[108:109], v[104:105] op_sel:[0,1,0]
	s_waitcnt lgkmcnt(2)
	v_pk_fma_f32 v[104:105], v[188:189], v[110:111], v[104:105] op_sel_hi:[1,0,1]
	v_pk_fma_f32 v[104:105], v[190:191], v[110:111], v[104:105] op_sel:[0,1,0]
	v_pk_mul_f32 v[106:107], v[194:195], v[112:113] op_sel:[0,1]
	v_pk_fma_f32 v[106:107], v[192:193], v[112:113], v[106:107] op_sel_hi:[1,0,1]
	v_pk_fma_f32 v[106:107], v[196:197], v[114:115], v[106:107] op_sel_hi:[1,0,1]
	v_pk_fma_f32 v[106:107], v[198:199], v[114:115], v[106:107] op_sel:[0,1,0]
	s_waitcnt lgkmcnt(1)
	v_mov_b32_e32 v108, v119
	v_pk_fma_f32 v[106:107], v[200:201], v[116:117], v[106:107] op_sel_hi:[1,0,1]
	v_pk_fma_f32 v[106:107], v[202:203], v[116:117], v[106:107] op_sel:[0,1,0]
	v_pk_fma_f32 v[106:107], v[204:205], v[118:119], v[106:107] op_sel_hi:[1,0,1]
	v_pk_fma_f32 v[106:107], v[174:175], v[108:109], v[106:107] op_sel_hi:[1,0,1]
	v_pk_add_f32 v[104:105], v[104:105], v[106:107]
	v_pk_fma_f32 v[104:105], v[140:141], v[172:173], v[104:105] op_sel:[0,1,0] op_sel_hi:[1,0,1]
	v_pk_fma_f32 v[172:173], v[136:137], v[172:173], v[104:105]
	v_cvt_pk_bf16_f32 v103, v172, s0
	v_cvt_pk_bf16_f32 v104, v173, s0
	s_add_i32 s0, s0, 64
	ds_write_b16 v102, v103
	ds_write_b16 v102, v104 offset:128
	v_add_u32_e32 v102, 0x110, v102
	s_cmpk_lg_i32 s0, 0x800
	s_cbranch_scc1 .LBB0_699
	v_cvt_pk_bf16_f32 v38, v38, v39
	v_cvt_pk_bf16_f32 v39, v40, v41
	v_cvt_pk_bf16_f32 v40, v66, v67
	v_cvt_pk_bf16_f32 v41, v68, v69
	v_cvt_pk_bf16_f32 v46, v46, v47
	v_cvt_pk_bf16_f32 v47, v48, v49
	v_cvt_pk_bf16_f32 v49, v44, v45
	v_cvt_pk_bf16_f32 v44, -v58, -v59
	v_cvt_pk_bf16_f32 v45, -v60, -v61
	v_mfma_f32_16x16x32_bf16 v[58:61], v[98:101], v[38:41], 0
	v_cvt_pk_bf16_f32 v48, v42, v43
	v_cvt_pk_bf16_f32 v42, -v62, -v63
	v_cvt_pk_bf16_f32 v43, -v64, -v65
	v_mfma_f32_16x16x32_bf16 v[58:61], v[94:97], v[46:49], v[58:61]
	s_mov_b32 s0, 0
	v_mov_b32_e32 v110, v2
	v_mfma_f32_16x16x32_bf16 v[90:93], v[90:93], v[42:45], v[58:61]
	v_mfma_f32_16x16x32_bf16 v[58:61], v[82:85], v[38:41], 0
	v_mfma_f32_16x16x32_bf16 v[58:61], v[86:89], v[46:49], v[58:61]
	ds_read_b128 v[94:97], v152 offset:8192
	ds_read_b128 v[86:89], v152 offset:12544
	ds_read_b128 v[98:101], v152 offset:8256
	ds_read_b128 v[102:105], v152 offset:12608
	ds_read_b128 v[106:109], v152 offset:8320
	ds_read_b128 v[66:69], v152 offset:12672
	ds_read_b128 v[62:65], v152 offset:8384
	ds_read_b128 v[82:85], v152 offset:12736
	s_add_i32 s1, s41, s0
	v_mov_b32_e32 v250, s1
	ds_read_b128 v[246:249], v250
	s_waitcnt lgkmcnt(0)
.LBB0_701:
	s_add_i32 s1, s41, s0
	v_mov_b32_e32 v111, s1
	ds_read_b128 v[116:119], v111 offset:16
	ds_read_b128 v[230:233], v111 offset:32
	ds_read_b128 v[234:237], v111 offset:48
	s_waitcnt lgkmcnt(5)
	v_pk_mul_f32 v[120:121], v[178:179], v[246:247] op_sel:[0,1]
	v_pk_fma_f32 v[112:113], v[176:177], v[246:247], v[120:121] op_sel_hi:[1,0,1]
	v_pk_fma_f32 v[112:113], v[180:181], v[248:249], v[112:113] op_sel_hi:[1,0,1]
	v_pk_fma_f32 v[112:113], v[182:183], v[248:249], v[112:113] op_sel:[0,1,0]
	s_add_i32 s1, s41, s0
	s_add_i32 s1, s1, 64
	v_mov_b32_e32 v250, s1
	ds_read_b128 v[246:249], v250
	s_waitcnt lgkmcnt(3)
	v_pk_fma_f32 v[112:113], v[184:185], v[116:117], v[112:113] op_sel_hi:[1,0,1]
	v_pk_fma_f32 v[112:113], v[186:187], v[116:117], v[112:113] op_sel:[0,1,0]
	s_waitcnt lgkmcnt(2)
	v_pk_fma_f32 v[112:113], v[188:189], v[118:119], v[112:113] op_sel_hi:[1,0,1]
	v_pk_fma_f32 v[112:113], v[190:191], v[118:119], v[112:113] op_sel:[0,1,0]
	v_pk_mul_f32 v[114:115], v[194:195], v[230:231] op_sel:[0,1]
	v_pk_fma_f32 v[114:115], v[192:193], v[230:231], v[114:115] op_sel_hi:[1,0,1]
	v_pk_fma_f32 v[114:115], v[196:197], v[232:233], v[114:115] op_sel_hi:[1,0,1]
	v_pk_fma_f32 v[114:115], v[198:199], v[232:233], v[114:115] op_sel:[0,1,0]
	s_waitcnt lgkmcnt(1)
	v_mov_b32_e32 v116, v237
	v_pk_fma_f32 v[114:115], v[200:201], v[234:235], v[114:115] op_sel_hi:[1,0,1]
	v_pk_fma_f32 v[114:115], v[202:203], v[234:235], v[114:115] op_sel:[0,1,0]
	v_pk_fma_f32 v[114:115], v[204:205], v[236:237], v[114:115] op_sel_hi:[1,0,1]
	v_pk_fma_f32 v[114:115], v[174:175], v[116:117], v[114:115] op_sel_hi:[1,0,1]
	v_pk_add_f32 v[112:113], v[112:113], v[114:115]
	v_pk_fma_f32 v[112:113], v[140:141], v[172:173], v[112:113] op_sel:[0,1,0] op_sel_hi:[1,0,1]
	v_pk_fma_f32 v[172:173], v[136:137], v[172:173], v[112:113]
	v_cvt_pk_bf16_f32 v111, v172, s0
	v_cvt_pk_bf16_f32 v112, v173, s0
	s_add_i32 s0, s0, 64
	ds_write_b16 v110, v111
	ds_write_b16 v110, v112 offset:128
	v_add_u32_e32 v110, 0x110, v110
	s_cmpk_lg_i32 s0, 0x800
	s_cbranch_scc1 .LBB0_701
	v_cvt_pk_bf16_f32 v54, -v54, -v55
	v_cvt_pk_bf16_f32 v55, -v56, -v57
	v_cvt_pk_bf16_f32 v56, -v50, -v51
	v_cvt_pk_bf16_f32 v57, -v52, -v53
	v_mfma_f32_16x16x32_bf16 v[86:89], v[86:89], v[38:41], 0
	s_mov_b32 s0, 0
	v_mfma_f32_16x16x32_bf16 v[50:53], v[78:81], v[54:57], v[90:93]
	v_mfma_f32_16x16x32_bf16 v[78:81], v[94:97], v[38:41], 0
	v_mfma_f32_16x16x32_bf16 v[78:81], v[98:101], v[46:49], v[78:81]
	v_mfma_f32_16x16x32_bf16 v[78:81], v[106:109], v[42:45], v[78:81]
	v_mfma_f32_16x16x32_bf16 v[86:89], v[102:105], v[46:49], v[86:89]
	ds_read_b128 v[94:97], v152 offset:8192
	ds_read_b128 v[90:93], v152 offset:12544
	ds_read_b128 v[102:105], v152 offset:8256
	ds_read_b128 v[98:101], v152 offset:12608
	ds_read_b128 v[110:113], v152 offset:8320
	ds_read_b128 v[106:109], v152 offset:12672
	ds_read_b128 v[118:121], v152 offset:8384
	ds_read_b128 v[114:117], v152 offset:12736
	s_add_i32 s1, s42, s0
	v_mov_b32_e32 v250, s1
	ds_read_b128 v[246:249], v250
	s_waitcnt lgkmcnt(0)
; #define LAS __attribute__((address_space(3)))
; DI unsigned pk2(float lo, float hi) { return pg8::cvt_pk_bf16(lo, hi); }
; DI f32x4 mfma16(bf16x8 a, bf16x8 b, f32x4 c) { return __builtin_amdgcn_mfma_f32_16x16x32_bf16(a, b, c, 0, 0, 0); }
; template <int DIRN, int SUB> DI void s5_subtile(const LAS float* UF, LAS bf16* XT, float lr, float li, const f32x2 (&bb)[16], f32x2& x,
;                                                 const bf16x8 (&bfr)[4], f32x4& acc0, f32x4& acc1, int lane) {
;     ...
;     for (int i = 0; i < 32; ++i) { const int r = DIRN ? 31 - i : i;
;         x = s5_step((const LAS f32x4*)(UF + (32 * SUB + r) * 16), bb, lr, li, x);
;         const unsigned pkd = pk2(x.x, x.y); XT[r * 136 + lane] = (bf16)(pkd & 0xffffu); XT[r * 136 + 64 + lane] = (bf16)(pkd >> 16); }
; #pragma unroll
;     for (int ks = 0; ks < 4; ++ks) { const bf16x8 a0 = *(const LAS bf16x8*)(XT + (lane & 15) * 136 + 32 * ks + 8 * (lane >> 4)), a1 = *(const LAS bf16x8*)(XT + (16 + (lane & 15)) * 136 + 32 * ks + 8 * (lane >> 4));
;         acc0 = mfma16(a0, bfr[ks], acc0); acc1 = mfma16(a1, bfr[ks], acc1); }
.LBB0_703:
	s_add_i32 s1, s42, s0
	v_mov_b32_e32 v158, s1
	ds_read_b128 v[234:237], v158 offset:16
	ds_read_b128 v[238:241], v158 offset:32
	ds_read_b128 v[242:245], v158 offset:48
	s_waitcnt lgkmcnt(5)
	v_pk_mul_f32 v[158:159], v[178:179], v[246:247] op_sel:[0,1]
	v_pk_fma_f32 v[158:159], v[176:177], v[246:247], v[158:159] op_sel_hi:[1,0,1]
	v_pk_fma_f32 v[158:159], v[180:181], v[248:249], v[158:159] op_sel_hi:[1,0,1]
	s_waitcnt lgkmcnt(1)
	v_pk_fma_f32 v[158:159], v[182:183], v[248:249], v[158:159] op_sel:[0,1,0]
	s_add_i32 s1, s42, s0
	s_add_i32 s1, s1, 64
	v_mov_b32_e32 v250, s1
	ds_read_b128 v[246:249], v250
	v_pk_fma_f32 v[158:159], v[184:185], v[234:235], v[158:159] op_sel_hi:[1,0,1]
	v_pk_fma_f32 v[158:159], v[186:187], v[234:235], v[158:159] op_sel:[0,1,0]
	v_pk_fma_f32 v[158:159], v[188:189], v[236:237], v[158:159] op_sel_hi:[1,0,1]
	v_pk_fma_f32 v[158:159], v[190:191], v[236:237], v[158:159] op_sel:[0,1,0]
	v_pk_mul_f32 v[160:161], v[194:195], v[238:239] op_sel:[0,1]
	v_pk_fma_f32 v[160:161], v[192:193], v[238:239], v[160:161] op_sel_hi:[1,0,1]
	v_pk_fma_f32 v[160:161], v[196:197], v[240:241], v[160:161] op_sel_hi:[1,0,1]
	v_pk_fma_f32 v[160:161], v[198:199], v[240:241], v[160:161] op_sel:[0,1,0]
	s_waitcnt lgkmcnt(1)
	v_mov_b32_e32 v230, v245
	v_pk_fma_f32 v[160:161], v[200:201], v[242:243], v[160:161] op_sel_hi:[1,0,1]
	v_pk_fma_f32 v[160:161], v[202:203], v[242:243], v[160:161] op_sel:[0,1,0]
	v_pk_fma_f32 v[160:161], v[204:205], v[244:245], v[160:161] op_sel_hi:[1,0,1]
	v_pk_fma_f32 v[160:161], v[174:175], v[230:231], v[160:161] op_sel_hi:[1,0,1]
	v_pk_add_f32 v[158:159], v[158:159], v[160:161]
	v_pk_fma_f32 v[158:159], v[140:141], v[172:173], v[158:159] op_sel:[0,1,0] op_sel_hi:[1,0,1]
	v_pk_fma_f32 v[172:173], v[136:137], v[172:173], v[158:159]
	v_cvt_pk_bf16_f32 v158, v172, s0
	v_cvt_pk_bf16_f32 v159, v173, s0
	s_add_i32 s0, s0, 64
	ds_write_b16 v2, v158
	ds_write_b16 v2, v159 offset:128
	v_add_u32_e32 v2, 0x110, v2
	s_cmpk_eq_i32 s0, 0x800
	s_cbranch_scc0 .LBB0_703
	v_mfma_f32_16x16x32_bf16 v[58:61], v[70:73], v[42:45], v[58:61]
	v_readlane_b32 s16, v252, 4
	v_readlane_b32 s28, v252, 16
	v_readlane_b32 s29, v252, 17
	v_mfma_f32_16x16x32_bf16 v[66:69], v[66:69], v[42:45], v[86:89]
	v_readlane_b32 s26, v252, 14
	v_readlane_b32 s27, v252, 15
	s_mov_b32 s0, 0x3fb8aa3b
	v_mfma_f32_16x16x32_bf16 v[62:65], v[62:65], v[54:57], v[78:81]
	v_readlane_b32 s20, v252, 8
	v_readlane_b32 s21, v252, 9
	v_readlane_b32 s22, v252, 10
	v_mfma_f32_16x16x32_bf16 v[58:61], v[74:77], v[54:57], v[58:61]
	v_readlane_b32 s23, v252, 11
	v_readlane_b32 s17, v252, 5
	v_readlane_b32 s18, v252, 6
	v_mfma_f32_16x16x32_bf16 v[66:69], v[82:85], v[54:57], v[66:69]
	ds_read_b128 v[78:81], v152 offset:8192
	ds_read_b128 v[82:85], v152 offset:8256
	v_readlane_b32 s19, v252, 7
	v_readlane_b32 s24, v252, 12
	v_mfma_f32_16x16x32_bf16 v[74:77], v[90:93], v[38:41], 0
	ds_read_b128 v[86:89], v152 offset:12544
	ds_read_b128 v[90:93], v152 offset:12608
	global_load_dword v2, v3, s[70:71] offset:256
	v_readlane_b32 s25, v252, 13
	s_waitcnt lgkmcnt(1)
	v_mfma_f32_16x16x32_bf16 v[86:89], v[86:89], v[38:41], 0
	v_readlane_b32 s30, v252, 18
	v_readlane_b32 s31, v252, 19
	v_mfma_f32_16x16x32_bf16 v[70:73], v[94:97], v[38:41], 0
	ds_read_b128 v[94:97], v152 offset:8320
	v_mfma_f32_16x16x32_bf16 v[78:81], v[78:81], v[38:41], 0
	s_waitcnt lgkmcnt(1)
	v_mfma_f32_16x16x32_bf16 v[86:89], v[90:93], v[46:49], v[86:89]
	v_add_u32_e32 v90, 0x1000, v122
	v_ashrrev_i32_e32 v91, 31, v90
	v_lshlrev_b64 v[90:91], 2, v[90:91]
	v_lshl_add_u64 v[92:93], s[28:29], 0, v[90:91]
	v_mfma_f32_16x16x32_bf16 v[70:73], v[102:105], v[46:49], v[70:73]
	v_lshl_add_u64 v[90:91], s[26:27], 0, v[90:91]
	v_mfma_f32_16x16x32_bf16 v[74:77], v[98:101], v[46:49], v[74:77]
	v_mfma_f32_16x16x32_bf16 v[78:81], v[82:85], v[46:49], v[78:81]
	ds_read_b128 v[82:85], v152 offset:8384
	ds_read_b128 v[98:101], v152 offset:12672
	ds_read_b128 v[102:105], v152 offset:12736
	global_load_dword v93, v[92:93], off
	s_nop 0
	global_load_dword v92, v[90:91], off
	s_waitcnt lgkmcnt(3)
	v_mfma_f32_16x16x32_bf16 v[78:81], v[94:97], v[42:45], v[78:81]
	s_waitcnt lgkmcnt(2)
	v_mfma_f32_16x16x32_bf16 v[78:81], v[82:85], v[54:57], v[78:81]
	s_waitcnt vmcnt(2)
	v_mul_f32_e32 v82, 0x3fb8aa3b, v2
	v_fma_f32 v83, v2, s0, -v82
	v_rndne_f32_e32 v84, v82
	v_fmac_f32_e32 v83, 0x32a5705f, v2
	v_sub_f32_e32 v82, v82, v84
	v_add_f32_e32 v82, v82, v83
	s_waitcnt lgkmcnt(1)
	v_mfma_f32_16x16x32_bf16 v[86:89], v[98:101], v[42:45], v[86:89]
	v_cvt_i32_f32_e32 v90, v84
	v_exp_f32_e32 v91, v82
	s_mov_b32 s0, 0xc2ce8ed0
	v_mfma_f32_16x16x32_bf16 v[70:73], v[110:113], v[42:45], v[70:73]
	v_cmp_ngt_f32_e32 vcc, s0, v2
	s_mov_b32 s0, 0x42b17218
	v_mfma_f32_16x16x32_bf16 v[74:77], v[106:109], v[42:45], v[74:77]
	s_waitcnt lgkmcnt(0)
	v_mfma_f32_16x16x32_bf16 v[82:85], v[102:105], v[54:57], v[86:89]
	v_mfma_f32_16x16x32_bf16 v[70:73], v[118:121], v[54:57], v[70:73]
	s_nop 1
	v_ldexp_f32 v86, v91, v90
	v_cndmask_b32_e32 v86, 0, v86, vcc
	v_cmp_nlt_f32_e32 vcc, s0, v2
	v_mfma_f32_16x16x32_bf16 v[74:77], v[114:117], v[54:57], v[74:77]
	s_brev_b32 s0, 18
	v_cndmask_b32_e32 v86, v219, v86, vcc
	s_waitcnt vmcnt(1)
	v_mul_f32_e32 v87, v86, v93
	v_and_b32_e32 v88, 0x7fffffff, v87
	v_cmp_nlt_f32_e64 s[20:21], |v87|, s0
	s_and_saveexec_b64 s[0:1], s[20:21]
	s_xor_b64 s[22:23], exec, s[0:1]
	s_cbranch_execz .LBB0_706
; DI void s5_disc(const S5P& P, int dir, int g, int p, float& lr, float& li, f32x2 (&bb)[16]) {
;     ...
;     const float mag = expf(dt * are); lr = mag * cosf(dt * aim); li = mag * sinf(dt * aim);
	v_lshrrev_b32_e32 v2, 23, v88
	v_add_u32_e32 v2, 0xffffff88, v2
	v_cmp_lt_u32_e32 vcc, 63, v2
	s_mov_b32 s10, 0xfe5163ab
	s_nop 0
	v_cndmask_b32_e32 v89, 0, v220, vcc
	v_add_u32_e32 v2, v89, v2
	v_cmp_lt_u32_e64 s[0:1], 31, v2
	s_nop 1
	v_cndmask_b32_e64 v89, 0, v221, s[0:1]
	v_add_u32_e32 v2, v89, v2
	v_cmp_lt_u32_e64 s[8:9], 31, v2
	s_nop 1
	v_cndmask_b32_e64 v89, 0, v221, s[8:9]
	v_add_u32_e32 v89, v89, v2
	v_and_b32_e32 v2, 0x7fffff, v88
	v_or_b32_e32 v104, 0x800000, v2
	v_mad_u64_u32 v[90:91], s[10:11], v104, s10, 0
	v_mov_b32_e32 v2, v91
	s_mov_b32 s10, 0x3c439041
	v_mad_u64_u32 v[94:95], s[10:11], v104, s10, v[2:3]
	v_mov_b32_e32 v2, v95
	s_mov_b32 s10, 0xdb629599
	v_mad_u64_u32 v[96:97], s[10:11], v104, s10, v[2:3]
	v_mov_b32_e32 v2, v97
	s_mov_b32 s10, 0xf534ddc0
	v_mad_u64_u32 v[98:99], s[10:11], v104, s10, v[2:3]
	v_mov_b32_e32 v2, v99
	s_mov_b32 s10, 0xfc2757d1
	v_mad_u64_u32 v[100:101], s[10:11], v104, s10, v[2:3]
	v_mov_b32_e32 v2, v101
	s_mov_b32 s10, 0x4e441529
	v_mad_u64_u32 v[102:103], s[10:11], v104, s10, v[2:3]
	v_mov_b32_e32 v2, v103
	s_mov_b32 s10, 0xa2f9836e
	v_mad_u64_u32 v[104:105], s[10:11], v104, s10, v[2:3]
	v_cndmask_b32_e32 v91, v102, v98, vcc
	v_cndmask_b32_e32 v2, v104, v100, vcc
	v_cndmask_b32_e32 v97, v105, v102, vcc
	v_cndmask_b32_e64 v95, v2, v91, s[0:1]
	v_cndmask_b32_e64 v2, v97, v2, s[0:1]
	v_cndmask_b32_e32 v97, v100, v96, vcc
	v_cndmask_b32_e64 v91, v91, v97, s[0:1]
	v_sub_u32_e32 v99, 32, v89
	v_cmp_eq_u32_e64 s[10:11], 0, v89
	v_cndmask_b32_e32 v89, v98, v94, vcc
	v_cndmask_b32_e64 v2, v2, v95, s[8:9]
	v_cndmask_b32_e64 v95, v95, v91, s[8:9]
	v_cndmask_b32_e64 v94, v97, v89, s[0:1]
	v_alignbit_b32 v100, v2, v95, v99
	v_cndmask_b32_e64 v91, v91, v94, s[8:9]
	v_cndmask_b32_e64 v2, v100, v2, s[10:11]
	v_alignbit_b32 v97, v95, v91, v99
	v_cndmask_b32_e32 v90, v96, v90, vcc
	v_cndmask_b32_e64 v95, v97, v95, s[10:11]
	v_bfe_u32 v100, v2, 29, 1
	v_cndmask_b32_e64 v89, v89, v90, s[0:1]
	v_alignbit_b32 v97, v2, v95, 30
	v_sub_u32_e32 v101, 0, v100
	v_cndmask_b32_e64 v89, v94, v89, s[8:9]
	v_xor_b32_e32 v97, v97, v101
	v_alignbit_b32 v90, v91, v89, v99
	v_cndmask_b32_e64 v90, v90, v91, s[10:11]
	v_ffbh_u32_e32 v94, v97
	v_alignbit_b32 v91, v95, v90, 30
	v_min_u32_e32 v94, 32, v94
	v_alignbit_b32 v89, v90, v89, 30
	v_xor_b32_e32 v91, v91, v101
	v_sub_u32_e32 v95, 31, v94
	v_xor_b32_e32 v89, v89, v101
	v_alignbit_b32 v96, v97, v91, v95
	v_alignbit_b32 v89, v91, v89, v95
	v_alignbit_b32 v90, v96, v89, 9
	v_ffbh_u32_e32 v91, v90
	v_min_u32_e32 v91, 32, v91
	v_lshrrev_b32_e32 v98, 29, v2
	v_not_b32_e32 v95, v91
	v_alignbit_b32 v89, v90, v89, v95
	v_lshlrev_b32_e32 v90, 31, v98
	v_or_b32_e32 v95, 0x33000000, v90
	v_add_lshl_u32 v91, v91, v94, 23
	v_lshrrev_b32_e32 v89, 9, v89
	v_sub_u32_e32 v91, v95, v91
	v_or_b32_e32 v90, 0.5, v90
	v_lshlrev_b32_e32 v94, 23, v94
	v_or_b32_e32 v89, v91, v89
	v_lshrrev_b32_e32 v91, 9, v96
	v_sub_u32_e32 v90, v90, v94
	v_or_b32_e32 v90, v91, v90
	v_mul_f32_e32 v91, 0x3fc90fda, v90
	s_mov_b32 s0, 0x3fc90fda
	v_fma_f32 v94, v90, s0, -v91
	v_fmac_f32_e32 v94, 0x33a22168, v90
	v_fmac_f32_e32 v94, 0x3fc90fda, v89
	v_lshrrev_b32_e32 v2, 30, v2
	v_add_f32_e32 v90, v91, v94
	v_add_u32_e32 v89, v100, v2

; DI void s5_disc(const S5P& P, int dir, int g, int p, float& lr, float& li, f32x2 (&bb)[16]) {
;     ...
;     const float den = are * are + aim * aim, nr = lr - 1.0f; const float cr = (nr * are + li * aim) / den, ci = (li * are - nr * aim) / den;
;     const f32x4* br = (const f32x4*)(P.b_re + (size_t)(g * 64 + p) * 16); const f32x4* bi = (const f32x4*)(P.b_im + (size_t)(g * 64 + p) * 16);
; #pragma unroll
;     for (int q = 0; q < 4; ++q) { const f32x4 r = br[q], i = bi[q];
; #pragma unroll
;         for (int e = 0; e < 4; ++e) bb[4 * q + e] = (f32x2){cr * r[e] - ci * i[e], cr * i[e] + ci * r[e]}; }
.LBB0_724:
	v_add_f32_e32 v88, -1.0, v86
	v_mov_b32_e32 v2, v93
	v_pk_mul_f32 v[94:95], v[92:93], v[92:93]
	v_pk_mul_f32 v[96:97], v[2:3], v[88:89] op_sel:[0,1] op_sel_hi:[0,0]
	v_pk_fma_f32 v[98:99], v[92:93], v[88:89], v[96:97]
	v_pk_fma_f32 v[92:93], v[92:93], v[88:89], v[96:97] op_sel_hi:[0,1,1] neg_lo:[0,0,1] neg_hi:[0,0,1]
	v_pk_add_f32 v[94:95], v[94:95], v[94:95] op_sel:[0,1] op_sel_hi:[0,1]
	v_div_scale_f32 v1, s[0:1], v95, v95, v93
	v_rcp_f32_e32 v2, v1
	s_nop 0
	v_fma_f32 v87, -v1, v2, 1.0
	v_fmac_f32_e32 v2, v87, v2
	v_div_scale_f32 v87, vcc, v93, v95, v93
	v_mul_f32_e32 v88, v87, v2
	v_fma_f32 v92, -v1, v88, v87
	v_fmac_f32_e32 v88, v92, v2
	v_fma_f32 v1, -v1, v88, v87
	v_div_fmas_f32 v1, v1, v2, v88
	v_div_fixup_f32 v117, v1, v95, v93
	v_div_scale_f32 v1, s[0:1], v94, v94, v98
	v_rcp_f32_e32 v2, v1
	s_mov_b32 s0, 0
	v_fma_f32 v87, -v1, v2, 1.0
	v_fmac_f32_e32 v2, v87, v2
	v_div_scale_f32 v87, vcc, v98, v94, v98
	v_mul_f32_e32 v88, v87, v2
	v_fma_f32 v92, -v1, v88, v87
	v_fmac_f32_e32 v88, v92, v2
	v_fma_f32 v1, -v1, v88, v87
	v_div_fmas_f32 v1, v1, v2, v88
	v_div_fixup_f32 v116, v1, v94, v98
	v_pk_mul_f32 v[94:95], v[128:129], v[116:117]
	v_pk_mul_f32 v[96:97], v[132:133], v[116:117]
	v_pk_fma_f32 v[92:93], v[124:125], v[116:117], v[94:95] op_sel:[0,0,1] op_sel_hi:[1,1,0] neg_lo:[0,0,1] neg_hi:[0,0,1]
	v_pk_fma_f32 v[94:95], v[124:125], v[116:117], v[94:95] op_sel:[0,0,1] op_sel_hi:[1,1,0]
	v_pk_mul_f32 v[98:99], v[134:135], v[116:117]
	v_mov_b32_e32 v93, v95
	v_pk_fma_f32 v[94:95], v[126:127], v[116:117], v[96:97] op_sel:[0,0,1] op_sel_hi:[1,1,0] neg_lo:[0,0,1] neg_hi:[0,0,1]
	v_pk_fma_f32 v[96:97], v[126:127], v[116:117], v[96:97] op_sel:[0,0,1] op_sel_hi:[1,1,0]
	v_pk_mul_f32 v[36:37], v[36:37], v[116:117]
	v_mov_b32_e32 v95, v97
	v_pk_fma_f32 v[96:97], v[130:131], v[116:117], v[98:99] op_sel:[0,0,1] op_sel_hi:[1,1,0] neg_lo:[0,0,1] neg_hi:[0,0,1]
	v_pk_fma_f32 v[98:99], v[130:131], v[116:117], v[98:99] op_sel:[0,0,1] op_sel_hi:[1,1,0]
	v_pk_mul_f32 v[26:27], v[26:27], v[116:117]
	v_mov_b32_e32 v97, v99
	v_pk_mul_f32 v[98:99], v[34:35], v[116:117]
	v_pk_mul_f32 v[18:19], v[18:19], v[116:117]
	v_pk_fma_f32 v[34:35], v[30:31], v[116:117], v[98:99] op_sel:[0,0,1] op_sel_hi:[1,1,0] neg_lo:[0,0,1] neg_hi:[0,0,1]
	v_pk_fma_f32 v[30:31], v[30:31], v[116:117], v[98:99] op_sel:[0,0,1] op_sel_hi:[1,1,0]
	v_pk_fma_f32 v[104:105], v[14:15], v[116:117], v[18:19] op_sel:[0,0,1] op_sel_hi:[1,1,0] neg_lo:[0,0,1] neg_hi:[0,0,1]
	v_mov_b32_e32 v35, v31
	v_pk_fma_f32 v[30:31], v[32:33], v[116:117], v[36:37] op_sel:[0,0,1] op_sel_hi:[1,1,0] neg_lo:[0,0,1] neg_hi:[0,0,1]
	v_pk_fma_f32 v[32:33], v[32:33], v[116:117], v[36:37] op_sel:[0,0,1] op_sel_hi:[1,1,0]
	v_pk_mul_f32 v[36:37], v[142:143], v[116:117]
	v_mov_b32_e32 v31, v33
	v_pk_fma_f32 v[32:33], v[138:139], v[116:117], v[36:37] op_sel:[0,0,1] op_sel_hi:[1,1,0] neg_lo:[0,0,1] neg_hi:[0,0,1]
	v_pk_fma_f32 v[36:37], v[138:139], v[116:117], v[36:37] op_sel:[0,0,1] op_sel_hi:[1,1,0]
	v_pk_fma_f32 v[14:15], v[14:15], v[116:117], v[18:19] op_sel:[0,0,1] op_sel_hi:[1,1,0]
	v_mov_b32_e32 v33, v37
	v_pk_fma_f32 v[36:37], v[22:23], v[116:117], v[26:27] op_sel:[0,0,1] op_sel_hi:[1,1,0] neg_lo:[0,0,1] neg_hi:[0,0,1]
	v_pk_fma_f32 v[22:23], v[22:23], v[116:117], v[26:27] op_sel:[0,0,1] op_sel_hi:[1,1,0]
	v_mov_b32_e32 v105, v15
	v_mov_b32_e32 v37, v23
	v_pk_mul_f32 v[22:23], v[146:147], v[116:117]
	v_pk_mul_f32 v[14:15], v[166:167], v[116:117]
	v_pk_fma_f32 v[98:99], v[144:145], v[116:117], v[22:23] op_sel:[0,0,1] op_sel_hi:[1,1,0] neg_lo:[0,0,1] neg_hi:[0,0,1]
	v_pk_fma_f32 v[22:23], v[144:145], v[116:117], v[22:23] op_sel:[0,0,1] op_sel_hi:[1,1,0]
	v_pk_fma_f32 v[106:107], v[164:165], v[116:117], v[14:15] op_sel:[0,0,1] op_sel_hi:[1,1,0] neg_lo:[0,0,1] neg_hi:[0,0,1]
	v_pk_fma_f32 v[14:15], v[164:165], v[116:117], v[14:15] op_sel:[0,0,1] op_sel_hi:[1,1,0]
	v_mov_b32_e32 v99, v23
	v_pk_mul_f32 v[22:23], v[28:29], v[116:117]
	v_mov_b32_e32 v107, v15
	v_pk_mul_f32 v[14:15], v[20:21], v[116:117]
	v_pk_mul_f32 v[10:11], v[10:11], v[116:117]
	v_pk_fma_f32 v[100:101], v[24:25], v[116:117], v[22:23] op_sel:[0,0,1] op_sel_hi:[1,1,0] neg_lo:[0,0,1] neg_hi:[0,0,1]
	v_pk_fma_f32 v[22:23], v[24:25], v[116:117], v[22:23] op_sel:[0,0,1] op_sel_hi:[1,1,0]
	v_pk_fma_f32 v[108:109], v[16:17], v[116:117], v[14:15] op_sel:[0,0,1] op_sel_hi:[1,1,0] neg_lo:[0,0,1] neg_hi:[0,0,1]
	v_pk_fma_f32 v[14:15], v[16:17], v[116:117], v[14:15] op_sel:[0,0,1] op_sel_hi:[1,1,0]
	v_pk_fma_f32 v[112:113], v[6:7], v[116:117], v[10:11] op_sel:[0,0,1] op_sel_hi:[1,1,0] neg_lo:[0,0,1] neg_hi:[0,0,1]
	v_pk_fma_f32 v[6:7], v[6:7], v[116:117], v[10:11] op_sel:[0,0,1] op_sel_hi:[1,1,0]
	v_mov_b32_e32 v101, v23
	v_pk_mul_f32 v[22:23], v[162:163], v[116:117]
	v_mov_b32_e32 v109, v15
	v_pk_mul_f32 v[14:15], v[170:171], v[116:117]
	v_mov_b32_e32 v113, v7
	v_pk_mul_f32 v[6:7], v[12:13], v[116:117]
	v_pk_fma_f32 v[102:103], v[148:149], v[116:117], v[22:23] op_sel:[0,0,1] op_sel_hi:[1,1,0] neg_lo:[0,0,1] neg_hi:[0,0,1]
	v_pk_fma_f32 v[22:23], v[148:149], v[116:117], v[22:23] op_sel:[0,0,1] op_sel_hi:[1,1,0]
	v_pk_fma_f32 v[110:111], v[168:169], v[116:117], v[14:15] op_sel:[0,0,1] op_sel_hi:[1,1,0] neg_lo:[0,0,1] neg_hi:[0,0,1]
	v_pk_fma_f32 v[14:15], v[168:169], v[116:117], v[14:15] op_sel:[0,0,1] op_sel_hi:[1,1,0]
	v_pk_fma_f32 v[114:115], v[8:9], v[116:117], v[6:7] op_sel:[0,0,1] op_sel_hi:[1,1,0] neg_lo:[0,0,1] neg_hi:[0,0,1]
	v_pk_fma_f32 v[6:7], v[8:9], v[116:117], v[6:7] op_sel:[0,0,1] op_sel_hi:[1,1,0]
	v_mov_b32_e32 v103, v23
	v_mov_b32_e32 v111, v15
	v_mov_b32_e32 v115, v7
	v_mov_b32_e32 v87, v86
	v_xor_b32_e32 v88, 0x80000000, v89
	v_add_u32_e32 v1, s51, v206
	s_add_i32 s1, s43, s0
	v_mov_b32_e32 v250, s1
	ds_read_b128 v[246:249], v250
	s_waitcnt lgkmcnt(0)
; #define LAS __attribute__((address_space(3)))
; DI unsigned pk2(float lo, float hi) { return pg8::cvt_pk_bf16(lo, hi); }
; DI f32x4 mfma16(bf16x8 a, bf16x8 b, f32x4 c) { return __builtin_amdgcn_mfma_f32_16x16x32_bf16(a, b, c, 0, 0, 0); }
; template <int DIRN, int SUB> DI void s5_subtile(const LAS float* UF, LAS bf16* XT, float lr, float li, const f32x2 (&bb)[16], f32x2& x,
;                                                 const bf16x8 (&bfr)[4], f32x4& acc0, f32x4& acc1, int lane) {
;     ...
;     for (int i = 0; i < 32; ++i) { const int r = DIRN ? 31 - i : i;
;         x = s5_step((const LAS f32x4*)(UF + (32 * SUB + r) * 16), bb, lr, li, x);
;         const unsigned pkd = pk2(x.x, x.y); XT[r * 136 + lane] = (bf16)(pkd & 0xffffu); XT[r * 136 + 64 + lane] = (bf16)(pkd >> 16); }
; #pragma unroll
;     for (int ks = 0; ks < 4; ++ks) { const bf16x8 a0 = *(const LAS bf16x8*)(XT + (lane & 15) * 136 + 32 * ks + 8 * (lane >> 4)), a1 = *(const LAS bf16x8*)(XT + (16 + (lane & 15)) * 136 + 32 * ks + 8 * (lane >> 4));
;         acc0 = mfma16(a0, bfr[ks], acc0); acc1 = mfma16(a1, bfr[ks], acc1); }
.LBB0_725:
	s_add_i32 s1, s43, s0
	v_mov_b32_e32 v2, s1
	ds_read_b128 v[10:13], v2 offset:16
	ds_read_b128 v[14:17], v2 offset:32
	ds_read_b128 v[18:21], v2 offset:48
	s_waitcnt lgkmcnt(5)
	v_pk_mul_f32 v[22:23], v[96:97], v[246:247] op_sel:[0,1]
	v_pk_fma_f32 v[6:7], v[94:95], v[246:247], v[22:23] op_sel_hi:[1,0,1]
	v_mov_b32_e32 v2, v249
	v_pk_fma_f32 v[6:7], v[34:35], v[248:249], v[6:7] op_sel_hi:[1,0,1]
	s_add_i32 s1, s43, s0
	s_sub_i32 s1, s1, 64
	v_mov_b32_e32 v250, s1
	ds_read_b128 v[246:249], v250
	s_waitcnt lgkmcnt(2)
	v_pk_mul_f32 v[8:9], v[104:105], v[14:15] op_sel:[0,1]
	v_pk_fma_f32 v[6:7], v[30:31], v[2:3], v[6:7] op_sel_hi:[1,0,1]
	v_pk_fma_f32 v[6:7], v[32:33], v[10:11], v[6:7] op_sel_hi:[1,0,1]
	v_pk_fma_f32 v[8:9], v[102:103], v[14:15], v[8:9] op_sel_hi:[1,0,1]
	v_pk_fma_f32 v[6:7], v[36:37], v[10:11], v[6:7] op_sel:[0,1,0]
	v_pk_fma_f32 v[8:9], v[106:107], v[16:17], v[8:9] op_sel_hi:[1,0,1]
	v_pk_fma_f32 v[6:7], v[98:99], v[12:13], v[6:7] op_sel_hi:[1,0,1]
	v_pk_fma_f32 v[6:7], v[100:101], v[12:13], v[6:7] op_sel:[0,1,0]
	v_pk_fma_f32 v[8:9], v[108:109], v[16:17], v[8:9] op_sel:[0,1,0]
	s_waitcnt lgkmcnt(1)
	v_pk_fma_f32 v[8:9], v[110:111], v[18:19], v[8:9] op_sel_hi:[1,0,1]
	v_pk_fma_f32 v[8:9], v[112:113], v[18:19], v[8:9] op_sel:[0,1,0]
	v_pk_fma_f32 v[8:9], v[114:115], v[20:21], v[8:9] op_sel_hi:[1,0,1]
	v_pk_fma_f32 v[8:9], v[92:93], v[20:21], v[8:9] op_sel:[0,1,0]
	v_pk_add_f32 v[6:7], v[6:7], v[8:9]
	v_pk_fma_f32 v[6:7], v[88:89], v[90:91], v[6:7] op_sel:[0,1,0] op_sel_hi:[1,0,1]
	v_pk_fma_f32 v[90:91], v[86:87], v[90:91], v[6:7]
	v_cvt_pk_bf16_f32 v2, v90, s0
	v_cvt_pk_bf16_f32 v6, v91, s0
	s_sub_i32 s0, s0, 64
	ds_write_b16 v1, v2
	ds_write_b16 v1, v6 offset:128
	v_add_u32_e32 v1, 0xfffffef0, v1
	s_cmpk_lg_i32 s0, 0xf800
	s_cbranch_scc1 .LBB0_725
	ds_read_b128 v[6:9], v152 offset:8192
	ds_read_b128 v[10:13], v152 offset:12544
	ds_read_b128 v[14:17], v152 offset:8256
	ds_read_b128 v[18:21], v152 offset:12608
	v_add_u32_e32 v1, 0x40f0, v206
	s_movk_i32 s0, 0x17c0
	s_waitcnt lgkmcnt(3)
	v_mfma_f32_16x16x32_bf16 v[6:9], v[6:9], v[38:41], v[78:81]
	v_mov_b32_e32 v2, v1
	s_waitcnt lgkmcnt(2)
	v_mfma_f32_16x16x32_bf16 v[10:13], v[10:13], v[38:41], v[82:85]
	s_waitcnt lgkmcnt(1)
	v_mfma_f32_16x16x32_bf16 v[6:9], v[14:17], v[46:49], v[6:9]
	s_waitcnt lgkmcnt(0)
	v_mfma_f32_16x16x32_bf16 v[10:13], v[18:21], v[46:49], v[10:13]
	ds_read_b128 v[14:17], v152 offset:8320
	ds_read_b128 v[18:21], v152 offset:12672
	s_waitcnt lgkmcnt(1)
	v_mfma_f32_16x16x32_bf16 v[6:9], v[14:17], v[42:45], v[6:9]
	s_waitcnt lgkmcnt(0)
	v_mfma_f32_16x16x32_bf16 v[14:17], v[18:21], v[42:45], v[10:13]
	s_nop 2
	ds_read_b128 v[10:13], v152 offset:8384
	ds_read_b128 v[18:21], v152 offset:12736
	s_waitcnt lgkmcnt(1)
	v_mfma_f32_16x16x32_bf16 v[10:13], v[10:13], v[54:57], v[6:9]
	s_waitcnt lgkmcnt(0)
	v_mfma_f32_16x16x32_bf16 v[6:9], v[18:21], v[54:57], v[14:17]
	s_add_i32 s1, s49, s0
	v_mov_b32_e32 v250, s1
	ds_read_b128 v[246:249], v250
	s_waitcnt lgkmcnt(0)
.LBB0_727:
	s_add_i32 s1, s49, s0
	v_mov_b32_e32 v26, s1
	s_nop 0
	ds_read_b128 v[18:21], v26 offset:16
	ds_read_b128 v[22:25], v26 offset:32
	ds_read_b128 v[26:29], v26 offset:48
	s_waitcnt lgkmcnt(5)
	v_pk_mul_f32 v[78:79], v[96:97], v[246:247] op_sel:[0,1]
	v_pk_fma_f32 v[14:15], v[94:95], v[246:247], v[78:79] op_sel_hi:[1,0,1]
	v_pk_fma_f32 v[14:15], v[34:35], v[248:249], v[14:15] op_sel_hi:[1,0,1]
	v_pk_fma_f32 v[14:15], v[30:31], v[248:249], v[14:15] op_sel:[0,1,0]
	s_add_i32 s1, s49, s0
	s_sub_i32 s1, s1, 64
	v_mov_b32_e32 v250, s1
	ds_read_b128 v[246:249], v250
	s_waitcnt lgkmcnt(3)
	v_pk_fma_f32 v[14:15], v[32:33], v[18:19], v[14:15] op_sel_hi:[1,0,1]
	v_pk_fma_f32 v[14:15], v[36:37], v[18:19], v[14:15] op_sel:[0,1,0]
	s_waitcnt lgkmcnt(2)
	v_pk_fma_f32 v[14:15], v[98:99], v[20:21], v[14:15] op_sel_hi:[1,0,1]
	v_pk_fma_f32 v[14:15], v[100:101], v[20:21], v[14:15] op_sel:[0,1,0]
	v_pk_mul_f32 v[16:17], v[104:105], v[22:23] op_sel:[0,1]
	v_pk_fma_f32 v[16:17], v[102:103], v[22:23], v[16:17] op_sel_hi:[1,0,1]
	v_pk_fma_f32 v[16:17], v[106:107], v[24:25], v[16:17] op_sel_hi:[1,0,1]
	v_pk_fma_f32 v[16:17], v[108:109], v[24:25], v[16:17] op_sel:[0,1,0]
	s_waitcnt lgkmcnt(1)
	v_mov_b32_e32 v18, v29
	v_pk_fma_f32 v[16:17], v[110:111], v[26:27], v[16:17] op_sel_hi:[1,0,1]
	v_pk_fma_f32 v[16:17], v[112:113], v[26:27], v[16:17] op_sel:[0,1,0]
	v_pk_fma_f32 v[16:17], v[114:115], v[28:29], v[16:17] op_sel_hi:[1,0,1]
	v_pk_fma_f32 v[16:17], v[92:93], v[18:19], v[16:17] op_sel_hi:[1,0,1]
	v_pk_add_f32 v[14:15], v[14:15], v[16:17]
	v_add_u32_e32 v16, s49, v2
	v_pk_fma_f32 v[14:15], v[88:89], v[90:91], v[14:15] op_sel:[0,1,0] op_sel_hi:[1,0,1]
	v_add_u32_e32 v2, 0xfffffef0, v2
	v_pk_fma_f32 v[90:91], v[86:87], v[90:91], v[14:15]
	v_cvt_pk_bf16_f32 v14, v90, s0
	v_cvt_pk_bf16_f32 v15, v91, s0
	s_sub_i32 s0, s0, 64
	s_cmpk_lg_i32 s0, 0xfc0
	ds_write_b16 v16, v14
	ds_write_b16 v16, v15 offset:128
	s_cbranch_scc1 .LBB0_727
	ds_read_b128 v[14:17], v152 offset:8192
	ds_read_b128 v[22:25], v152 offset:8256
	ds_read_b128 v[18:21], v152 offset:12544
	s_movk_i32 s0, 0xfc0
	v_mov_b32_e32 v2, v1
	s_waitcnt lgkmcnt(2)
	v_mfma_f32_16x16x32_bf16 v[14:17], v[14:17], v[38:41], v[70:73]
	s_waitcnt lgkmcnt(1)
	v_mfma_f32_16x16x32_bf16 v[14:17], v[22:25], v[46:49], v[14:17]
	ds_read_b128 v[22:25], v152 offset:12608
	s_waitcnt lgkmcnt(1)
	v_mfma_f32_16x16x32_bf16 v[18:21], v[18:21], v[38:41], v[74:77]
	s_waitcnt lgkmcnt(0)
	v_mfma_f32_16x16x32_bf16 v[18:21], v[22:25], v[46:49], v[18:21]
	ds_read_b128 v[22:25], v152 offset:8320
	s_waitcnt lgkmcnt(0)
	v_mfma_f32_16x16x32_bf16 v[14:17], v[22:25], v[42:45], v[14:17]
	ds_read_b128 v[22:25], v152 offset:12672
	s_waitcnt lgkmcnt(0)
	v_mfma_f32_16x16x32_bf16 v[22:25], v[22:25], v[42:45], v[18:21]
	s_nop 2
	ds_read_b128 v[18:21], v152 offset:8384
	s_waitcnt lgkmcnt(0)
	v_mfma_f32_16x16x32_bf16 v[18:21], v[18:21], v[54:57], v[14:17]
	s_nop 2
	ds_read_b128 v[14:17], v152 offset:12736
	s_waitcnt lgkmcnt(0)
	v_mfma_f32_16x16x32_bf16 v[14:17], v[14:17], v[54:57], v[22:25]
	s_add_i32 s1, s49, s0
	v_mov_b32_e32 v250, s1
	ds_read_b128 v[246:249], v250
	s_waitcnt lgkmcnt(0)
; #define LAS __attribute__((address_space(3)))
; DI unsigned pk2(float lo, float hi) { return pg8::cvt_pk_bf16(lo, hi); }
; DI f32x4 mfma16(bf16x8 a, bf16x8 b, f32x4 c) { return __builtin_amdgcn_mfma_f32_16x16x32_bf16(a, b, c, 0, 0, 0); }
; template <int DIRN, int SUB> DI void s5_subtile(const LAS float* UF, LAS bf16* XT, float lr, float li, const f32x2 (&bb)[16], f32x2& x,
;                                                 const bf16x8 (&bfr)[4], f32x4& acc0, f32x4& acc1, int lane) {
;     ...
;     for (int i = 0; i < 32; ++i) { const int r = DIRN ? 31 - i : i;
;         x = s5_step((const LAS f32x4*)(UF + (32 * SUB + r) * 16), bb, lr, li, x);
;         const unsigned pkd = pk2(x.x, x.y); XT[r * 136 + lane] = (bf16)(pkd & 0xffffu); XT[r * 136 + 64 + lane] = (bf16)(pkd >> 16); }
; #pragma unroll
;     for (int ks = 0; ks < 4; ++ks) { const bf16x8 a0 = *(const LAS bf16x8*)(XT + (lane & 15) * 136 + 32 * ks + 8 * (lane >> 4)), a1 = *(const LAS bf16x8*)(XT + (16 + (lane & 15)) * 136 + 32 * ks + 8 * (lane >> 4));
;         acc0 = mfma16(a0, bfr[ks], acc0); acc1 = mfma16(a1, bfr[ks], acc1); }
.LBB0_729:
	s_add_i32 s1, s49, s0
	v_mov_b32_e32 v74, s1
	s_nop 0
	ds_read_b128 v[26:29], v74 offset:16
	ds_read_b128 v[70:73], v74 offset:32
	ds_read_b128 v[74:77], v74 offset:48
	s_waitcnt lgkmcnt(5)
	v_pk_mul_f32 v[78:79], v[96:97], v[246:247] op_sel:[0,1]
	v_pk_fma_f32 v[22:23], v[94:95], v[246:247], v[78:79] op_sel_hi:[1,0,1]
	v_pk_fma_f32 v[22:23], v[34:35], v[248:249], v[22:23] op_sel_hi:[1,0,1]
	v_pk_fma_f32 v[22:23], v[30:31], v[248:249], v[22:23] op_sel:[0,1,0]
	s_add_i32 s1, s49, s0
	s_sub_i32 s1, s1, 64
	v_mov_b32_e32 v250, s1
	ds_read_b128 v[246:249], v250
	s_waitcnt lgkmcnt(3)
	v_pk_fma_f32 v[22:23], v[32:33], v[26:27], v[22:23] op_sel_hi:[1,0,1]
	v_pk_fma_f32 v[22:23], v[36:37], v[26:27], v[22:23] op_sel:[0,1,0]
	s_waitcnt lgkmcnt(2)
	v_pk_fma_f32 v[22:23], v[98:99], v[28:29], v[22:23] op_sel_hi:[1,0,1]
	v_pk_fma_f32 v[22:23], v[100:101], v[28:29], v[22:23] op_sel:[0,1,0]
	v_pk_mul_f32 v[24:25], v[104:105], v[70:71] op_sel:[0,1]
	v_pk_fma_f32 v[24:25], v[102:103], v[70:71], v[24:25] op_sel_hi:[1,0,1]
	v_pk_fma_f32 v[24:25], v[106:107], v[72:73], v[24:25] op_sel_hi:[1,0,1]
	v_pk_fma_f32 v[24:25], v[108:109], v[72:73], v[24:25] op_sel:[0,1,0]
	s_waitcnt lgkmcnt(1)
	v_mov_b32_e32 v26, v77
	v_pk_fma_f32 v[24:25], v[110:111], v[74:75], v[24:25] op_sel_hi:[1,0,1]
	v_pk_fma_f32 v[24:25], v[112:113], v[74:75], v[24:25] op_sel:[0,1,0]
	v_pk_fma_f32 v[24:25], v[114:115], v[76:77], v[24:25] op_sel_hi:[1,0,1]
	v_pk_fma_f32 v[24:25], v[92:93], v[26:27], v[24:25] op_sel_hi:[1,0,1]
	v_pk_add_f32 v[22:23], v[22:23], v[24:25]
	v_add_u32_e32 v24, s49, v2
	v_pk_fma_f32 v[22:23], v[88:89], v[90:91], v[22:23] op_sel:[0,1,0] op_sel_hi:[1,0,1]
	v_add_u32_e32 v2, 0xfffffef0, v2
	v_pk_fma_f32 v[90:91], v[86:87], v[90:91], v[22:23]
	v_cvt_pk_bf16_f32 v22, v90, s0
	v_cvt_pk_bf16_f32 v23, v91, s0
	s_sub_i32 s0, s0, 64
	s_cmpk_lg_i32 s0, 0x7c0
	ds_write_b16 v24, v22
	ds_write_b16 v24, v23 offset:128
	s_cbranch_scc1 .LBB0_729
	ds_read_b128 v[22:25], v152 offset:8192
	ds_read_b128 v[26:29], v152 offset:12544
	s_movk_i32 s0, 0x7c0
	s_waitcnt lgkmcnt(1)
	v_mfma_f32_16x16x32_bf16 v[22:25], v[22:25], v[38:41], v[62:65]
	s_nop 2
	ds_read_b128 v[62:65], v152 offset:8256
	s_waitcnt lgkmcnt(1)
	v_mfma_f32_16x16x32_bf16 v[26:29], v[26:29], v[38:41], v[66:69]
	s_waitcnt lgkmcnt(0)
	v_mfma_f32_16x16x32_bf16 v[22:25], v[62:65], v[46:49], v[22:25]
	ds_read_b128 v[62:65], v152 offset:12608
	s_waitcnt lgkmcnt(0)
	v_mfma_f32_16x16x32_bf16 v[26:29], v[62:65], v[46:49], v[26:29]
	ds_read_b128 v[62:65], v152 offset:8320
	s_waitcnt lgkmcnt(0)
	v_mfma_f32_16x16x32_bf16 v[22:25], v[62:65], v[42:45], v[22:25]
	ds_read_b128 v[62:65], v152 offset:12672
	s_waitcnt lgkmcnt(0)
	v_mfma_f32_16x16x32_bf16 v[62:65], v[62:65], v[42:45], v[26:29]
	s_nop 2
	ds_read_b128 v[26:29], v152 offset:8384
	s_waitcnt lgkmcnt(0)
	v_mfma_f32_16x16x32_bf16 v[26:29], v[26:29], v[54:57], v[22:25]
	s_nop 2
	ds_read_b128 v[22:25], v152 offset:12736
	s_waitcnt lgkmcnt(0)
	v_mfma_f32_16x16x32_bf16 v[22:25], v[22:25], v[54:57], v[62:65]
	s_add_i32 s1, s49, s0
	v_mov_b32_e32 v250, s1
	ds_read_b128 v[246:249], v250
	s_waitcnt lgkmcnt(0)
.LBB0_731:
	s_add_i32 s1, s49, s0
	v_mov_b32_e32 v2, s1
	s_nop 0
	ds_read_b128 v[66:69], v2 offset:16
	ds_read_b128 v[70:73], v2 offset:32
	ds_read_b128 v[74:77], v2 offset:48
	s_waitcnt lgkmcnt(5)
	v_pk_mul_f32 v[78:79], v[96:97], v[246:247] op_sel:[0,1]
	v_pk_fma_f32 v[62:63], v[94:95], v[246:247], v[78:79] op_sel_hi:[1,0,1]
	v_mov_b32_e32 v2, v249
	v_pk_fma_f32 v[62:63], v[34:35], v[248:249], v[62:63] op_sel_hi:[1,0,1]
	s_add_i32 s1, s49, s0
	s_sub_i32 s1, s1, 64
	v_mov_b32_e32 v250, s1
	ds_read_b128 v[246:249], v250
	s_waitcnt lgkmcnt(2)
	v_pk_mul_f32 v[64:65], v[104:105], v[70:71] op_sel:[0,1]
	v_pk_fma_f32 v[62:63], v[30:31], v[2:3], v[62:63] op_sel_hi:[1,0,1]
	v_pk_fma_f32 v[62:63], v[32:33], v[66:67], v[62:63] op_sel_hi:[1,0,1]
	v_pk_fma_f32 v[64:65], v[102:103], v[70:71], v[64:65] op_sel_hi:[1,0,1]
	v_pk_fma_f32 v[62:63], v[36:37], v[66:67], v[62:63] op_sel:[0,1,0]
	v_pk_fma_f32 v[64:65], v[106:107], v[72:73], v[64:65] op_sel_hi:[1,0,1]
	v_pk_fma_f32 v[62:63], v[98:99], v[68:69], v[62:63] op_sel_hi:[1,0,1]
	v_pk_fma_f32 v[62:63], v[100:101], v[68:69], v[62:63] op_sel:[0,1,0]
	v_pk_fma_f32 v[64:65], v[108:109], v[72:73], v[64:65] op_sel:[0,1,0]
	s_waitcnt lgkmcnt(1)
	v_pk_fma_f32 v[64:65], v[110:111], v[74:75], v[64:65] op_sel_hi:[1,0,1]
	v_pk_fma_f32 v[64:65], v[112:113], v[74:75], v[64:65] op_sel:[0,1,0]
	v_pk_fma_f32 v[64:65], v[114:115], v[76:77], v[64:65] op_sel_hi:[1,0,1]
	v_pk_fma_f32 v[64:65], v[92:93], v[76:77], v[64:65] op_sel:[0,1,0]
	v_pk_add_f32 v[62:63], v[62:63], v[64:65]
	v_pk_fma_f32 v[62:63], v[88:89], v[90:91], v[62:63] op_sel:[0,1,0] op_sel_hi:[1,0,1]
	v_pk_fma_f32 v[90:91], v[86:87], v[90:91], v[62:63]
	v_add_u32_e32 v63, s49, v1
	v_cvt_pk_bf16_f32 v2, v90, s0
	v_cvt_pk_bf16_f32 v62, v91, s0
	s_sub_i32 s0, s0, 64
	v_add_u32_e32 v1, 0xfffffef0, v1
	s_cmpk_eq_i32 s0, 0xffc0
	ds_write_b16 v63, v2
	ds_write_b16 v63, v62 offset:128
	s_cbranch_scc0 .LBB0_731
; #define LAS __attribute__((address_space(3)))
; DI bf16 f2bf(float f) { return (bf16)(pk2(f, 0.f) & 0xffffu); }
; DI float gelu_tanh(float x) { const float u = 0.7978845608028654f * (x + 0.044715f * x * x * x); return x * sigm(2.0f * u); }
; DI f32x4 mfma16(bf16x8 a, bf16x8 b, f32x4 c) { return __builtin_amdgcn_mfma_f32_16x16x32_bf16(a, b, c, 0, 0, 0); }
; template <int DIRN, int SUB> DI void s5_subtile(const LAS float* UF, LAS bf16* XT, float lr, float li, const f32x2 (&bb)[16], f32x2& x,
;                                                 const bf16x8 (&bfr)[4], f32x4& acc0, f32x4& acc1, int lane) {
;     ...
;     for (int ks = 0; ks < 4; ++ks) { const bf16x8 a0 = *(const LAS bf16x8*)(XT + (lane & 15) * 136 + 32 * ks + 8 * (lane >> 4)), a1 = *(const LAS bf16x8*)(XT + (16 + (lane & 15)) * 136 + 32 * ks + 8 * (lane >> 4));
;         acc0 = mfma16(a0, bfr[ks], acc0); acc1 = mfma16(a1, bfr[ks], acc1); }
; DI void s5_passC(const Ctx& C, const S5P& P, const bf16* PROJ, const f32x2* END, bf16* YG  , int item_lo, int item_hi) {
;     ...
;         const float dv = P.d[g * 16 + (lane & 15)];
; #pragma unroll
;         for (int r = 0; r < 8; ++r)
; #pragma unroll
;             for (int j = 0; j < 4; ++j) { const int t = 16 * r + (lane >> 4) * 4 + j; const float y = acc[r][j] + dv * UF[t * 16 + (lane & 15)]; YG[(tok0 + t) * 1024 + g * 16 + (lane & 15)] = f2bf(gelu_tanh(y)); }
	ds_read_b128 v[30:33], v152 offset:8192
	ds_read_b128 v[34:37], v152 offset:12544
	v_lshlrev_b32_e32 v1, 2, v123
	v_readlane_b32 s16, v252, 20
	v_lshl_or_b32 v2, s52, 6, v1
	s_waitcnt lgkmcnt(1)
	v_mfma_f32_16x16x32_bf16 v[30:33], v[30:33], v[38:41], v[50:53]
	v_readlane_b32 s24, v252, 28
	v_readlane_b32 s25, v252, 29
	s_lshl_b32 s0, s52, 5
	s_waitcnt lgkmcnt(0)
	v_mfma_f32_16x16x32_bf16 v[34:37], v[34:37], v[38:41], v[58:61]
	ds_read_b128 v[38:41], v152 offset:8256
	ds_read_b128 v[50:53], v152 offset:12608
	s_add_u32 s0, s47, s0
	s_addc_u32 s1, s48, 0
	s_waitcnt lgkmcnt(1)
	v_mfma_f32_16x16x32_bf16 v[30:33], v[38:41], v[46:49], v[30:33]
	v_readlane_b32 s17, v252, 21
	v_readlane_b32 s18, v252, 22
	v_readlane_b32 s19, v252, 23
	s_waitcnt lgkmcnt(0)
	v_mfma_f32_16x16x32_bf16 v[34:37], v[50:53], v[46:49], v[34:37]
	ds_read_b128 v[38:41], v152 offset:8320
	ds_read_b128 v[46:49], v152 offset:12672
	v_readlane_b32 s20, v252, 24
	v_readlane_b32 s21, v252, 25
	s_waitcnt lgkmcnt(1)
	v_mfma_f32_16x16x32_bf16 v[30:33], v[38:41], v[42:45], v[30:33]
	v_readlane_b32 s22, v252, 26
	v_readlane_b32 s23, v252, 27
	v_readlane_b32 s26, v252, 30
	s_waitcnt lgkmcnt(0)
	v_mfma_f32_16x16x32_bf16 v[38:41], v[46:49], v[42:45], v[34:37]
	s_nop 2
	ds_read_b128 v[34:37], v152 offset:8384
	ds_read_b128 v[42:45], v152 offset:12736
	v_readlane_b32 s27, v252, 31
	v_readlane_b32 s28, v252, 32
	s_waitcnt lgkmcnt(1)
	v_mfma_f32_16x16x32_bf16 v[34:37], v[34:37], v[54:57], v[30:33]
	v_readlane_b32 s29, v252, 33
	v_readlane_b32 s30, v252, 34
	v_readlane_b32 s31, v252, 35
	s_waitcnt lgkmcnt(0)
	v_mfma_f32_16x16x32_bf16 v[30:33], v[42:45], v[54:57], v[38:41]
	v_ashrrev_i32_e32 v44, 2, v0
	s_nop 1
	global_load_dword v40, v2, s[24:25]
	v_and_b32_e32 v38, -4, v44
	v_add_u32_e32 v41, s49, v1
	v_lshlrev_b32_e32 v2, 1, v123
	v_lshl_add_u64 v[0:1], s[0:1], 0, v[2:3]
	v_lshl_add_u32 v2, v38, 6, v41
	ds_read_b32 v2, v2
	v_ashrrev_i32_e32 v39, 31, v38
	v_lshl_add_u64 v[42:43], s[12:13], 0, v[38:39]
	v_lshlrev_b64 v[42:43], 11, v[42:43]
	v_lshl_add_u64 v[42:43], v[0:1], 0, v[42:43]
	s_waitcnt vmcnt(0) lgkmcnt(0)
	v_fma_f32 v2, v40, v2, v34
	v_mul_f32_e32 v34, 0x3d372713, v2
	v_mul_f32_e32 v34, v2, v34
	v_fma_f32 v34, v2, v34, v2
	v_mul_f32_e32 v34, 0x3f4c422a, v34
	v_add_f32_e32 v34, v34, v34
	v_mul_f32_e32 v34, 0xbfb8aa3b, v34
	v_exp_f32_e32 v34, v34
	s_nop 0
	v_add_f32_e32 v34, 1.0, v34
	v_rcp_f32_e32 v34, v34
	s_nop 0
	v_mul_f32_e32 v2, v2, v34
	v_cvt_pk_bf16_f32 v2, v2, s0
	v_or_b32_e32 v34, 1, v38
	global_store_short v[42:43], v2, off
	v_lshl_add_u32 v2, v34, 6, v41
	ds_read_b32 v2, v2
	s_waitcnt lgkmcnt(0)
	v_fma_f32 v2, v40, v2, v35
	v_mul_f32_e32 v35, 0x3d372713, v2
	v_mul_f32_e32 v35, v2, v35
	v_fma_f32 v35, v2, v35, v2
	v_mul_f32_e32 v35, 0x3f4c422a, v35
	v_add_f32_e32 v35, v35, v35
	v_mul_f32_e32 v35, 0xbfb8aa3b, v35
	v_exp_f32_e32 v35, v35
	s_nop 0
	v_add_f32_e32 v35, 1.0, v35
	v_rcp_f32_e32 v35, v35
	s_nop 0
	v_mul_f32_e32 v2, v2, v35
	v_ashrrev_i32_e32 v35, 31, v34
	v_lshl_add_u64 v[34:35], s[12:13], 0, v[34:35]
	v_lshlrev_b64 v[34:35], 11, v[34:35]
	v_cvt_pk_bf16_f32 v2, v2, s0
	v_lshl_add_u64 v[34:35], v[0:1], 0, v[34:35]
	global_store_short v[34:35], v2, off
	v_or_b32_e32 v34, 2, v38
	v_lshl_add_u32 v2, v34, 6, v41
	ds_read_b32 v2, v2
	s_waitcnt lgkmcnt(0)
	v_fma_f32 v2, v40, v2, v36
	v_mul_f32_e32 v35, 0x3d372713, v2
	v_mul_f32_e32 v35, v2, v35
	v_fma_f32 v35, v2, v35, v2
	v_mul_f32_e32 v35, 0x3f4c422a, v35
	v_add_f32_e32 v35, v35, v35
	v_mul_f32_e32 v35, 0xbfb8aa3b, v35
	v_exp_f32_e32 v35, v35
	s_nop 0
	v_add_f32_e32 v35, 1.0, v35
	v_rcp_f32_e32 v35, v35
	s_nop 0
	v_mul_f32_e32 v2, v2, v35
	v_ashrrev_i32_e32 v35, 31, v34
	v_lshl_add_u64 v[34:35], s[12:13], 0, v[34:35]
	v_lshlrev_b64 v[34:35], 11, v[34:35]
	v_cvt_pk_bf16_f32 v2, v2, s0
	v_lshl_add_u64 v[34:35], v[0:1], 0, v[34:35]
	global_store_short v[34:35], v2, off
	v_or_b32_e32 v34, 3, v44
	v_lshl_add_u32 v2, v34, 6, v41
	ds_read_b32 v2, v2
	v_ashrrev_i32_e32 v35, 31, v34
	v_lshl_add_u64 v[34:35], s[12:13], 0, v[34:35]
	v_lshlrev_b64 v[34:35], 11, v[34:35]
	v_lshl_add_u64 v[34:35], v[0:1], 0, v[34:35]
	s_waitcnt lgkmcnt(0)
	v_fmac_f32_e32 v37, v40, v2
	v_mul_f32_e32 v2, 0x3d372713, v37
	v_mul_f32_e32 v2, v37, v2
	v_fma_f32 v2, v37, v2, v37
	v_mul_f32_e32 v2, 0x3f4c422a, v2
	v_add_f32_e32 v2, v2, v2
	v_mul_f32_e32 v2, 0xbfb8aa3b, v2
	v_exp_f32_e32 v2, v2
	s_nop 0
	v_add_f32_e32 v2, 1.0, v2
	v_rcp_f32_e32 v2, v2
	s_nop 0
	v_mul_f32_e32 v2, v37, v2
	v_cvt_pk_bf16_f32 v2, v2, s0
	global_store_short v[34:35], v2, off
	v_add_u32_e32 v34, 16, v38
	v_lshl_add_u32 v2, v34, 6, v41
	ds_read_b32 v2, v2
	v_ashrrev_i32_e32 v35, 31, v34
	v_lshl_add_u64 v[34:35], s[12:13], 0, v[34:35]
	v_lshlrev_b64 v[34:35], 11, v[34:35]
	v_lshl_add_u64 v[34:35], v[0:1], 0, v[34:35]
	s_waitcnt lgkmcnt(0)
	v_fma_f32 v2, v40, v2, v30
	v_mul_f32_e32 v30, 0x3d372713, v2
	v_mul_f32_e32 v30, v2, v30
	v_fma_f32 v30, v2, v30, v2
	v_mul_f32_e32 v30, 0x3f4c422a, v30
	v_add_f32_e32 v30, v30, v30
	v_mul_f32_e32 v30, 0xbfb8aa3b, v30
	v_exp_f32_e32 v30, v30
	s_nop 0
	v_add_f32_e32 v30, 1.0, v30
	v_rcp_f32_e32 v30, v30
	s_nop 0
	v_mul_f32_e32 v2, v2, v30
	v_cvt_pk_bf16_f32 v2, v2, s0
	v_add_u32_e32 v30, 17, v38
	global_store_short v[34:35], v2, off
	v_lshl_add_u32 v2, v30, 6, v41
	ds_read_b32 v2, v2
	s_waitcnt lgkmcnt(0)
	v_fma_f32 v2, v40, v2, v31
	v_mul_f32_e32 v31, 0x3d372713, v2
	v_mul_f32_e32 v31, v2, v31
	v_fma_f32 v31, v2, v31, v2
	v_mul_f32_e32 v31, 0x3f4c422a, v31
	v_add_f32_e32 v31, v31, v31
	v_mul_f32_e32 v31, 0xbfb8aa3b, v31
	v_exp_f32_e32 v31, v31
	s_nop 0
	v_add_f32_e32 v31, 1.0, v31
	v_rcp_f32_e32 v31, v31
	s_nop 0
	v_mul_f32_e32 v2, v2, v31
	v_ashrrev_i32_e32 v31, 31, v30
	v_lshl_add_u64 v[30:31], s[12:13], 0, v[30:31]
	v_lshlrev_b64 v[30:31], 11, v[30:31]
	v_cvt_pk_bf16_f32 v2, v2, s0
	v_lshl_add_u64 v[30:31], v[0:1], 0, v[30:31]
	global_store_short v[30:31], v2, off
	v_add_u32_e32 v30, 18, v38
	v_lshl_add_u32 v2, v30, 6, v41
	ds_read_b32 v2, v2
	s_waitcnt lgkmcnt(0)
; DI bf16 f2bf(float f) { return (bf16)(pk2(f, 0.f) & 0xffffu); }
; DI float gelu_tanh(float x) { const float u = 0.7978845608028654f * (x + 0.044715f * x * x * x); return x * sigm(2.0f * u); }
; DI void s5_passC(const Ctx& C, const S5P& P, const bf16* PROJ, const f32x2* END, bf16* YG  , int item_lo, int item_hi) {
;     ...
;         const float dv = P.d[g * 16 + (lane & 15)];
; #pragma unroll
;         for (int r = 0; r < 8; ++r)
; #pragma unroll
;             for (int j = 0; j < 4; ++j) { const int t = 16 * r + (lane >> 4) * 4 + j; const float y = acc[r][j] + dv * UF[t * 16 + (lane & 15)]; YG[(tok0 + t) * 1024 + g * 16 + (lane & 15)] = f2bf(gelu_tanh(y)); }
	v_fma_f32 v2, v40, v2, v32
	v_mul_f32_e32 v31, 0x3d372713, v2
	v_mul_f32_e32 v31, v2, v31
	v_fma_f32 v31, v2, v31, v2
	v_mul_f32_e32 v31, 0x3f4c422a, v31
	v_add_f32_e32 v31, v31, v31
	v_mul_f32_e32 v31, 0xbfb8aa3b, v31
	v_exp_f32_e32 v31, v31
	s_nop 0
	v_add_f32_e32 v31, 1.0, v31
	v_rcp_f32_e32 v31, v31
	s_nop 0
	v_mul_f32_e32 v2, v2, v31
	v_ashrrev_i32_e32 v31, 31, v30
	v_lshl_add_u64 v[30:31], s[12:13], 0, v[30:31]
	v_lshlrev_b64 v[30:31], 11, v[30:31]
	v_cvt_pk_bf16_f32 v2, v2, s0
	v_lshl_add_u64 v[30:31], v[0:1], 0, v[30:31]
	global_store_short v[30:31], v2, off
	v_add_u32_e32 v30, 19, v38
	v_lshl_add_u32 v2, v30, 6, v41
	ds_read_b32 v2, v2
	v_ashrrev_i32_e32 v31, 31, v30
	v_lshl_add_u64 v[30:31], s[12:13], 0, v[30:31]
	v_lshlrev_b64 v[30:31], 11, v[30:31]
	v_lshl_add_u64 v[30:31], v[0:1], 0, v[30:31]
	s_waitcnt lgkmcnt(0)
	v_fmac_f32_e32 v33, v40, v2
	v_mul_f32_e32 v2, 0x3d372713, v33
	v_mul_f32_e32 v2, v33, v2
	v_fma_f32 v2, v33, v2, v33
	v_mul_f32_e32 v2, 0x3f4c422a, v2
	v_add_f32_e32 v2, v2, v2
	v_mul_f32_e32 v2, 0xbfb8aa3b, v2
	v_exp_f32_e32 v2, v2
	s_nop 0
	v_add_f32_e32 v2, 1.0, v2
	v_rcp_f32_e32 v2, v2
	s_nop 0
	v_mul_f32_e32 v2, v33, v2
	v_cvt_pk_bf16_f32 v2, v2, s0
	global_store_short v[30:31], v2, off
	v_add_u32_e32 v30, 32, v38
	v_lshl_add_u32 v2, v30, 6, v41
	ds_read_b32 v2, v2
	v_ashrrev_i32_e32 v31, 31, v30
	v_lshl_add_u64 v[30:31], s[12:13], 0, v[30:31]
	v_lshlrev_b64 v[30:31], 11, v[30:31]
	v_lshl_add_u64 v[30:31], v[0:1], 0, v[30:31]
	s_waitcnt lgkmcnt(0)
	v_fma_f32 v2, v40, v2, v26
	v_mul_f32_e32 v26, 0x3d372713, v2
	v_mul_f32_e32 v26, v2, v26
	v_fma_f32 v26, v2, v26, v2
	v_mul_f32_e32 v26, 0x3f4c422a, v26
	v_add_f32_e32 v26, v26, v26
	v_mul_f32_e32 v26, 0xbfb8aa3b, v26
	v_exp_f32_e32 v26, v26
	s_nop 0
	v_add_f32_e32 v26, 1.0, v26
	v_rcp_f32_e32 v26, v26
	s_nop 0
	v_mul_f32_e32 v2, v2, v26
	v_cvt_pk_bf16_f32 v2, v2, s0
	v_add_u32_e32 v26, 33, v38
	global_store_short v[30:31], v2, off
	v_lshl_add_u32 v2, v26, 6, v41
	ds_read_b32 v2, v2
	s_waitcnt lgkmcnt(0)
	v_fma_f32 v2, v40, v2, v27
	v_mul_f32_e32 v27, 0x3d372713, v2
	v_mul_f32_e32 v27, v2, v27
	v_fma_f32 v27, v2, v27, v2
	v_mul_f32_e32 v27, 0x3f4c422a, v27
	v_add_f32_e32 v27, v27, v27
	v_mul_f32_e32 v27, 0xbfb8aa3b, v27
	v_exp_f32_e32 v27, v27
	s_nop 0
	v_add_f32_e32 v27, 1.0, v27
	v_rcp_f32_e32 v27, v27
	s_nop 0
	v_mul_f32_e32 v2, v2, v27
	v_ashrrev_i32_e32 v27, 31, v26
	v_lshl_add_u64 v[26:27], s[12:13], 0, v[26:27]
	v_lshlrev_b64 v[26:27], 11, v[26:27]
	v_cvt_pk_bf16_f32 v2, v2, s0
	v_lshl_add_u64 v[26:27], v[0:1], 0, v[26:27]
	global_store_short v[26:27], v2, off
	v_add_u32_e32 v26, 34, v38
	v_lshl_add_u32 v2, v26, 6, v41
	ds_read_b32 v2, v2
	s_waitcnt lgkmcnt(0)
	v_fma_f32 v2, v40, v2, v28
	v_mul_f32_e32 v27, 0x3d372713, v2
	v_mul_f32_e32 v27, v2, v27
	v_fma_f32 v27, v2, v27, v2
	v_mul_f32_e32 v27, 0x3f4c422a, v27
	v_add_f32_e32 v27, v27, v27
	v_mul_f32_e32 v27, 0xbfb8aa3b, v27
	v_exp_f32_e32 v27, v27
	s_nop 0
	v_add_f32_e32 v27, 1.0, v27
	v_rcp_f32_e32 v27, v27
	s_nop 0
	v_mul_f32_e32 v2, v2, v27
	v_ashrrev_i32_e32 v27, 31, v26
	v_lshl_add_u64 v[26:27], s[12:13], 0, v[26:27]
	v_lshlrev_b64 v[26:27], 11, v[26:27]
	v_cvt_pk_bf16_f32 v2, v2, s0
	v_lshl_add_u64 v[26:27], v[0:1], 0, v[26:27]
	global_store_short v[26:27], v2, off
	v_add_u32_e32 v26, 35, v38
	v_lshl_add_u32 v2, v26, 6, v41
	ds_read_b32 v2, v2
	v_ashrrev_i32_e32 v27, 31, v26
	v_lshl_add_u64 v[26:27], s[12:13], 0, v[26:27]
	v_lshlrev_b64 v[26:27], 11, v[26:27]
	v_lshl_add_u64 v[26:27], v[0:1], 0, v[26:27]
	s_waitcnt lgkmcnt(0)
	v_fmac_f32_e32 v29, v40, v2
	v_mul_f32_e32 v2, 0x3d372713, v29
	v_mul_f32_e32 v2, v29, v2
	v_fma_f32 v2, v29, v2, v29
	v_mul_f32_e32 v2, 0x3f4c422a, v2
	v_add_f32_e32 v2, v2, v2
	v_mul_f32_e32 v2, 0xbfb8aa3b, v2
	v_exp_f32_e32 v2, v2
	s_nop 0
	v_add_f32_e32 v2, 1.0, v2
	v_rcp_f32_e32 v2, v2
	s_nop 0
	v_mul_f32_e32 v2, v29, v2
	v_cvt_pk_bf16_f32 v2, v2, s0
	global_store_short v[26:27], v2, off
	v_add_u32_e32 v26, 48, v38
	v_lshl_add_u32 v2, v26, 6, v41
	ds_read_b32 v2, v2
	v_ashrrev_i32_e32 v27, 31, v26
	v_lshl_add_u64 v[26:27], s[12:13], 0, v[26:27]
	v_lshlrev_b64 v[26:27], 11, v[26:27]
	v_lshl_add_u64 v[26:27], v[0:1], 0, v[26:27]
	s_waitcnt lgkmcnt(0)
	v_fma_f32 v2, v40, v2, v22
	v_mul_f32_e32 v22, 0x3d372713, v2
	v_mul_f32_e32 v22, v2, v22
	v_fma_f32 v22, v2, v22, v2
	v_mul_f32_e32 v22, 0x3f4c422a, v22
	v_add_f32_e32 v22, v22, v22
	v_mul_f32_e32 v22, 0xbfb8aa3b, v22
	v_exp_f32_e32 v22, v22
	s_nop 0
	v_add_f32_e32 v22, 1.0, v22
	v_rcp_f32_e32 v22, v22
	s_nop 0
	v_mul_f32_e32 v2, v2, v22
	v_cvt_pk_bf16_f32 v2, v2, s0
	v_add_u32_e32 v22, 49, v38
	global_store_short v[26:27], v2, off
	v_lshl_add_u32 v2, v22, 6, v41
	ds_read_b32 v2, v2
	s_waitcnt lgkmcnt(0)
	v_fma_f32 v2, v40, v2, v23
	v_mul_f32_e32 v23, 0x3d372713, v2
	v_mul_f32_e32 v23, v2, v23
	v_fma_f32 v23, v2, v23, v2
	v_mul_f32_e32 v23, 0x3f4c422a, v23
	v_add_f32_e32 v23, v23, v23
	v_mul_f32_e32 v23, 0xbfb8aa3b, v23
	v_exp_f32_e32 v23, v23
	s_nop 0
	v_add_f32_e32 v23, 1.0, v23
	v_rcp_f32_e32 v23, v23
	s_nop 0
	v_mul_f32_e32 v2, v2, v23
	v_ashrrev_i32_e32 v23, 31, v22
	v_lshl_add_u64 v[22:23], s[12:13], 0, v[22:23]
	v_lshlrev_b64 v[22:23], 11, v[22:23]
	v_cvt_pk_bf16_f32 v2, v2, s0
	v_lshl_add_u64 v[22:23], v[0:1], 0, v[22:23]
	global_store_short v[22:23], v2, off
	v_add_u32_e32 v22, 50, v38
	v_lshl_add_u32 v2, v22, 6, v41
	ds_read_b32 v2, v2
	s_waitcnt lgkmcnt(0)
; DI bf16 f2bf(float f) { return (bf16)(pk2(f, 0.f) & 0xffffu); }
; DI float gelu_tanh(float x) { const float u = 0.7978845608028654f * (x + 0.044715f * x * x * x); return x * sigm(2.0f * u); }
; DI void s5_passC(const Ctx& C, const S5P& P, const bf16* PROJ, const f32x2* END, bf16* YG  , int item_lo, int item_hi) {
;     ...
;         const float dv = P.d[g * 16 + (lane & 15)];
; #pragma unroll
;         for (int r = 0; r < 8; ++r)
; #pragma unroll
;             for (int j = 0; j < 4; ++j) { const int t = 16 * r + (lane >> 4) * 4 + j; const float y = acc[r][j] + dv * UF[t * 16 + (lane & 15)]; YG[(tok0 + t) * 1024 + g * 16 + (lane & 15)] = f2bf(gelu_tanh(y)); }
	v_fma_f32 v2, v40, v2, v24
	v_mul_f32_e32 v23, 0x3d372713, v2
	v_mul_f32_e32 v23, v2, v23
	v_fma_f32 v23, v2, v23, v2
	v_mul_f32_e32 v23, 0x3f4c422a, v23
	v_add_f32_e32 v23, v23, v23
	v_mul_f32_e32 v23, 0xbfb8aa3b, v23
	v_exp_f32_e32 v23, v23
	s_nop 0
	v_add_f32_e32 v23, 1.0, v23
	v_rcp_f32_e32 v23, v23
	s_nop 0
	v_mul_f32_e32 v2, v2, v23
	v_ashrrev_i32_e32 v23, 31, v22
	v_lshl_add_u64 v[22:23], s[12:13], 0, v[22:23]
	v_lshlrev_b64 v[22:23], 11, v[22:23]
	v_cvt_pk_bf16_f32 v2, v2, s0
	v_lshl_add_u64 v[22:23], v[0:1], 0, v[22:23]
	global_store_short v[22:23], v2, off
	v_add_u32_e32 v22, 51, v38
	v_lshl_add_u32 v2, v22, 6, v41
	ds_read_b32 v2, v2
	v_ashrrev_i32_e32 v23, 31, v22
	v_lshl_add_u64 v[22:23], s[12:13], 0, v[22:23]
	v_lshlrev_b64 v[22:23], 11, v[22:23]
	v_lshl_add_u64 v[22:23], v[0:1], 0, v[22:23]
	s_waitcnt lgkmcnt(0)
	v_fmac_f32_e32 v25, v40, v2
	v_mul_f32_e32 v2, 0x3d372713, v25
	v_mul_f32_e32 v2, v25, v2
	v_fma_f32 v2, v25, v2, v25
	v_mul_f32_e32 v2, 0x3f4c422a, v2
	v_add_f32_e32 v2, v2, v2
	v_mul_f32_e32 v2, 0xbfb8aa3b, v2
	v_exp_f32_e32 v2, v2
	s_nop 0
	v_add_f32_e32 v2, 1.0, v2
	v_rcp_f32_e32 v2, v2
	s_nop 0
	v_mul_f32_e32 v2, v25, v2
	v_cvt_pk_bf16_f32 v2, v2, s0
	global_store_short v[22:23], v2, off
	v_add_u32_e32 v22, 64, v38
	v_lshl_add_u32 v2, v22, 6, v41
	ds_read_b32 v2, v2
	v_ashrrev_i32_e32 v23, 31, v22
	v_lshl_add_u64 v[22:23], s[12:13], 0, v[22:23]
	v_lshlrev_b64 v[22:23], 11, v[22:23]
	v_lshl_add_u64 v[22:23], v[0:1], 0, v[22:23]
	s_waitcnt lgkmcnt(0)
	v_fma_f32 v2, v40, v2, v18
	v_mul_f32_e32 v18, 0x3d372713, v2
	v_mul_f32_e32 v18, v2, v18
	v_fma_f32 v18, v2, v18, v2
	v_mul_f32_e32 v18, 0x3f4c422a, v18
	v_add_f32_e32 v18, v18, v18
	v_mul_f32_e32 v18, 0xbfb8aa3b, v18
	v_exp_f32_e32 v18, v18
	s_nop 0
	v_add_f32_e32 v18, 1.0, v18
	v_rcp_f32_e32 v18, v18
	s_nop 0
	v_mul_f32_e32 v2, v2, v18
	v_cvt_pk_bf16_f32 v2, v2, s0
	v_add_u32_e32 v18, 0x41, v38
	global_store_short v[22:23], v2, off
	v_lshl_add_u32 v2, v18, 6, v41
	ds_read_b32 v2, v2
	s_waitcnt lgkmcnt(0)
	v_fma_f32 v2, v40, v2, v19
	v_mul_f32_e32 v19, 0x3d372713, v2
	v_mul_f32_e32 v19, v2, v19
	v_fma_f32 v19, v2, v19, v2
	v_mul_f32_e32 v19, 0x3f4c422a, v19
	v_add_f32_e32 v19, v19, v19
	v_mul_f32_e32 v19, 0xbfb8aa3b, v19
	v_exp_f32_e32 v19, v19
	s_nop 0
	v_add_f32_e32 v19, 1.0, v19
	v_rcp_f32_e32 v19, v19
	s_nop 0
	v_mul_f32_e32 v2, v2, v19
	v_ashrrev_i32_e32 v19, 31, v18
	v_lshl_add_u64 v[18:19], s[12:13], 0, v[18:19]
	v_lshlrev_b64 v[18:19], 11, v[18:19]
	v_cvt_pk_bf16_f32 v2, v2, s0
	v_lshl_add_u64 v[18:19], v[0:1], 0, v[18:19]
	global_store_short v[18:19], v2, off
	v_add_u32_e32 v18, 0x42, v38
	v_lshl_add_u32 v2, v18, 6, v41
	ds_read_b32 v2, v2
	s_waitcnt lgkmcnt(0)
	v_fma_f32 v2, v40, v2, v20
	v_mul_f32_e32 v19, 0x3d372713, v2
	v_mul_f32_e32 v19, v2, v19
	v_fma_f32 v19, v2, v19, v2
	v_mul_f32_e32 v19, 0x3f4c422a, v19
	v_add_f32_e32 v19, v19, v19
	v_mul_f32_e32 v19, 0xbfb8aa3b, v19
	v_exp_f32_e32 v19, v19
	s_nop 0
	v_add_f32_e32 v19, 1.0, v19
	v_rcp_f32_e32 v19, v19
	s_nop 0
	v_mul_f32_e32 v2, v2, v19
	v_ashrrev_i32_e32 v19, 31, v18
	v_lshl_add_u64 v[18:19], s[12:13], 0, v[18:19]
	v_lshlrev_b64 v[18:19], 11, v[18:19]
	v_cvt_pk_bf16_f32 v2, v2, s0
	v_lshl_add_u64 v[18:19], v[0:1], 0, v[18:19]
	global_store_short v[18:19], v2, off
	v_add_u32_e32 v18, 0x43, v38
	v_lshl_add_u32 v2, v18, 6, v41
	ds_read_b32 v2, v2
	v_ashrrev_i32_e32 v19, 31, v18
	v_lshl_add_u64 v[18:19], s[12:13], 0, v[18:19]
	v_lshlrev_b64 v[18:19], 11, v[18:19]
	v_lshl_add_u64 v[18:19], v[0:1], 0, v[18:19]
	s_waitcnt lgkmcnt(0)
	v_fmac_f32_e32 v21, v40, v2
	v_mul_f32_e32 v2, 0x3d372713, v21
	v_mul_f32_e32 v2, v21, v2
	v_fma_f32 v2, v21, v2, v21
	v_mul_f32_e32 v2, 0x3f4c422a, v2
	v_add_f32_e32 v2, v2, v2
	v_mul_f32_e32 v2, 0xbfb8aa3b, v2
	v_exp_f32_e32 v2, v2
	s_nop 0
	v_add_f32_e32 v2, 1.0, v2
	v_rcp_f32_e32 v2, v2
	s_nop 0
	v_mul_f32_e32 v2, v21, v2
	v_cvt_pk_bf16_f32 v2, v2, s0
	global_store_short v[18:19], v2, off
	v_add_u32_e32 v18, 0x50, v38
	v_lshl_add_u32 v2, v18, 6, v41
	ds_read_b32 v2, v2
	v_ashrrev_i32_e32 v19, 31, v18
	v_lshl_add_u64 v[18:19], s[12:13], 0, v[18:19]
	v_lshlrev_b64 v[18:19], 11, v[18:19]
	v_lshl_add_u64 v[18:19], v[0:1], 0, v[18:19]
	s_waitcnt lgkmcnt(0)
	v_fma_f32 v2, v40, v2, v14
	v_mul_f32_e32 v14, 0x3d372713, v2
	v_mul_f32_e32 v14, v2, v14
	v_fma_f32 v14, v2, v14, v2
	v_mul_f32_e32 v14, 0x3f4c422a, v14
	v_add_f32_e32 v14, v14, v14
	v_mul_f32_e32 v14, 0xbfb8aa3b, v14
	v_exp_f32_e32 v14, v14
	s_nop 0
	v_add_f32_e32 v14, 1.0, v14
	v_rcp_f32_e32 v14, v14
	s_nop 0
	v_mul_f32_e32 v2, v2, v14
	v_cvt_pk_bf16_f32 v2, v2, s0
	v_add_u32_e32 v14, 0x51, v38
	global_store_short v[18:19], v2, off
	v_lshl_add_u32 v2, v14, 6, v41
	ds_read_b32 v2, v2
	s_waitcnt lgkmcnt(0)
	v_fma_f32 v2, v40, v2, v15
	v_mul_f32_e32 v15, 0x3d372713, v2
	v_mul_f32_e32 v15, v2, v15
	v_fma_f32 v15, v2, v15, v2
	v_mul_f32_e32 v15, 0x3f4c422a, v15
	v_add_f32_e32 v15, v15, v15
	v_mul_f32_e32 v15, 0xbfb8aa3b, v15
	v_exp_f32_e32 v15, v15
	s_nop 0
	v_add_f32_e32 v15, 1.0, v15
	v_rcp_f32_e32 v15, v15
	s_nop 0
	v_mul_f32_e32 v2, v2, v15
	v_ashrrev_i32_e32 v15, 31, v14
	v_lshl_add_u64 v[14:15], s[12:13], 0, v[14:15]
	v_lshlrev_b64 v[14:15], 11, v[14:15]
	v_cvt_pk_bf16_f32 v2, v2, s0
	v_lshl_add_u64 v[14:15], v[0:1], 0, v[14:15]
	global_store_short v[14:15], v2, off
	v_add_u32_e32 v14, 0x52, v38
	v_lshl_add_u32 v2, v14, 6, v41
	ds_read_b32 v2, v2
	s_waitcnt lgkmcnt(0)
; DI bf16 f2bf(float f) { return (bf16)(pk2(f, 0.f) & 0xffffu); }
; DI float gelu_tanh(float x) { const float u = 0.7978845608028654f * (x + 0.044715f * x * x * x); return x * sigm(2.0f * u); }
; DI void s5_passC(const Ctx& C, const S5P& P, const bf16* PROJ, const f32x2* END, bf16* YG  , int item_lo, int item_hi) {
;     ...
;         const float dv = P.d[g * 16 + (lane & 15)];
; #pragma unroll
;         for (int r = 0; r < 8; ++r)
; #pragma unroll
;             for (int j = 0; j < 4; ++j) { const int t = 16 * r + (lane >> 4) * 4 + j; const float y = acc[r][j] + dv * UF[t * 16 + (lane & 15)]; YG[(tok0 + t) * 1024 + g * 16 + (lane & 15)] = f2bf(gelu_tanh(y)); }
;         asm volatile("s_waitcnt lgkmcnt(0)" ::: "memory");
	v_fma_f32 v2, v40, v2, v16
	v_mul_f32_e32 v15, 0x3d372713, v2
	v_mul_f32_e32 v15, v2, v15
	v_fma_f32 v15, v2, v15, v2
	v_mul_f32_e32 v15, 0x3f4c422a, v15
	v_add_f32_e32 v15, v15, v15
	v_mul_f32_e32 v15, 0xbfb8aa3b, v15
	v_exp_f32_e32 v15, v15
	s_nop 0
	v_add_f32_e32 v15, 1.0, v15
	v_rcp_f32_e32 v15, v15
	s_nop 0
	v_mul_f32_e32 v2, v2, v15
	v_ashrrev_i32_e32 v15, 31, v14
	v_lshl_add_u64 v[14:15], s[12:13], 0, v[14:15]
	v_lshlrev_b64 v[14:15], 11, v[14:15]
	v_cvt_pk_bf16_f32 v2, v2, s0
	v_lshl_add_u64 v[14:15], v[0:1], 0, v[14:15]
	global_store_short v[14:15], v2, off
	v_add_u32_e32 v14, 0x53, v38
	v_lshl_add_u32 v2, v14, 6, v41
	ds_read_b32 v2, v2
	v_ashrrev_i32_e32 v15, 31, v14
	v_lshl_add_u64 v[14:15], s[12:13], 0, v[14:15]
	v_lshlrev_b64 v[14:15], 11, v[14:15]
	v_lshl_add_u64 v[14:15], v[0:1], 0, v[14:15]
	s_waitcnt lgkmcnt(0)
	v_fmac_f32_e32 v17, v40, v2
	v_mul_f32_e32 v2, 0x3d372713, v17
	v_mul_f32_e32 v2, v17, v2
	v_fma_f32 v2, v17, v2, v17
	v_mul_f32_e32 v2, 0x3f4c422a, v2
	v_add_f32_e32 v2, v2, v2
	v_mul_f32_e32 v2, 0xbfb8aa3b, v2
	v_exp_f32_e32 v2, v2
	s_nop 0
	v_add_f32_e32 v2, 1.0, v2
	v_rcp_f32_e32 v2, v2
	s_nop 0
	v_mul_f32_e32 v2, v17, v2
	v_cvt_pk_bf16_f32 v2, v2, s0
	global_store_short v[14:15], v2, off
	v_add_u32_e32 v14, 0x60, v38
	v_lshl_add_u32 v2, v14, 6, v41
	ds_read_b32 v2, v2
	v_ashrrev_i32_e32 v15, 31, v14
	v_lshl_add_u64 v[14:15], s[12:13], 0, v[14:15]
	v_lshlrev_b64 v[14:15], 11, v[14:15]
	v_lshl_add_u64 v[14:15], v[0:1], 0, v[14:15]
	s_waitcnt lgkmcnt(0)
	v_fma_f32 v2, v40, v2, v10
	v_mul_f32_e32 v10, 0x3d372713, v2
	v_mul_f32_e32 v10, v2, v10
	v_fma_f32 v10, v2, v10, v2
	v_mul_f32_e32 v10, 0x3f4c422a, v10
	v_add_f32_e32 v10, v10, v10
	v_mul_f32_e32 v10, 0xbfb8aa3b, v10
	v_exp_f32_e32 v10, v10
	s_nop 0
	v_add_f32_e32 v10, 1.0, v10
	v_rcp_f32_e32 v10, v10
	s_nop 0
	v_mul_f32_e32 v2, v2, v10
	v_cvt_pk_bf16_f32 v2, v2, s0
	v_add_u32_e32 v10, 0x61, v38
	global_store_short v[14:15], v2, off
	v_lshl_add_u32 v2, v10, 6, v41
	ds_read_b32 v2, v2
	s_waitcnt lgkmcnt(0)
	v_fma_f32 v2, v40, v2, v11
	v_mul_f32_e32 v11, 0x3d372713, v2
	v_mul_f32_e32 v11, v2, v11
	v_fma_f32 v11, v2, v11, v2
	v_mul_f32_e32 v11, 0x3f4c422a, v11
	v_add_f32_e32 v11, v11, v11
	v_mul_f32_e32 v11, 0xbfb8aa3b, v11
	v_exp_f32_e32 v11, v11
	s_nop 0
	v_add_f32_e32 v11, 1.0, v11
	v_rcp_f32_e32 v11, v11
	s_nop 0
	v_mul_f32_e32 v2, v2, v11
	v_ashrrev_i32_e32 v11, 31, v10
	v_lshl_add_u64 v[10:11], s[12:13], 0, v[10:11]
	v_lshlrev_b64 v[10:11], 11, v[10:11]
	v_cvt_pk_bf16_f32 v2, v2, s0
	v_lshl_add_u64 v[10:11], v[0:1], 0, v[10:11]
	global_store_short v[10:11], v2, off
	v_add_u32_e32 v10, 0x62, v38
	v_lshl_add_u32 v2, v10, 6, v41
	ds_read_b32 v2, v2
	s_waitcnt lgkmcnt(0)
	v_fma_f32 v2, v40, v2, v12
	v_mul_f32_e32 v11, 0x3d372713, v2
	v_mul_f32_e32 v11, v2, v11
	v_fma_f32 v11, v2, v11, v2
	v_mul_f32_e32 v11, 0x3f4c422a, v11
	v_add_f32_e32 v11, v11, v11
	v_mul_f32_e32 v11, 0xbfb8aa3b, v11
	v_exp_f32_e32 v11, v11
	s_nop 0
	v_add_f32_e32 v11, 1.0, v11
	v_rcp_f32_e32 v11, v11
	s_nop 0
	v_mul_f32_e32 v2, v2, v11
	v_ashrrev_i32_e32 v11, 31, v10
	v_lshl_add_u64 v[10:11], s[12:13], 0, v[10:11]
	v_lshlrev_b64 v[10:11], 11, v[10:11]
	v_cvt_pk_bf16_f32 v2, v2, s0
	v_lshl_add_u64 v[10:11], v[0:1], 0, v[10:11]
	global_store_short v[10:11], v2, off
	v_add_u32_e32 v10, 0x63, v38
	v_lshl_add_u32 v2, v10, 6, v41
	ds_read_b32 v2, v2
	v_ashrrev_i32_e32 v11, 31, v10
	v_lshl_add_u64 v[10:11], s[12:13], 0, v[10:11]
	v_lshlrev_b64 v[10:11], 11, v[10:11]
	v_lshl_add_u64 v[10:11], v[0:1], 0, v[10:11]
	s_waitcnt lgkmcnt(0)
	v_fmac_f32_e32 v13, v40, v2
	v_mul_f32_e32 v2, 0x3d372713, v13
	v_mul_f32_e32 v2, v13, v2
	v_fma_f32 v2, v13, v2, v13
	v_mul_f32_e32 v2, 0x3f4c422a, v2
	v_add_f32_e32 v2, v2, v2
	v_mul_f32_e32 v2, 0xbfb8aa3b, v2
	v_exp_f32_e32 v2, v2
	s_nop 0
	v_add_f32_e32 v2, 1.0, v2
	v_rcp_f32_e32 v2, v2
	s_nop 0
	v_mul_f32_e32 v2, v13, v2
	v_cvt_pk_bf16_f32 v2, v2, s0
	global_store_short v[10:11], v2, off
	v_add_u32_e32 v10, 0x70, v38
	v_lshl_add_u32 v2, v10, 6, v41
	ds_read_b32 v2, v2
	v_ashrrev_i32_e32 v11, 31, v10
	v_lshl_add_u64 v[10:11], s[12:13], 0, v[10:11]
	v_lshlrev_b64 v[10:11], 11, v[10:11]
	v_lshl_add_u64 v[10:11], v[0:1], 0, v[10:11]
	s_waitcnt lgkmcnt(0)
	v_fma_f32 v2, v40, v2, v6
	v_mul_f32_e32 v6, 0x3d372713, v2
	v_mul_f32_e32 v6, v2, v6
	v_fma_f32 v6, v2, v6, v2
	v_mul_f32_e32 v6, 0x3f4c422a, v6
	v_add_f32_e32 v6, v6, v6
	v_mul_f32_e32 v6, 0xbfb8aa3b, v6
	v_exp_f32_e32 v6, v6
	s_nop 0
	v_add_f32_e32 v6, 1.0, v6
	v_rcp_f32_e32 v6, v6
	s_nop 0
	v_mul_f32_e32 v2, v2, v6
	v_cvt_pk_bf16_f32 v2, v2, s0
	v_add_u32_e32 v6, 0x71, v38
	global_store_short v[10:11], v2, off
	v_lshl_add_u32 v2, v6, 6, v41
	ds_read_b32 v2, v2
	s_waitcnt lgkmcnt(0)
	v_fma_f32 v2, v40, v2, v7
	v_mul_f32_e32 v7, 0x3d372713, v2
	v_mul_f32_e32 v7, v2, v7
	v_fma_f32 v7, v2, v7, v2
	v_mul_f32_e32 v7, 0x3f4c422a, v7
	v_add_f32_e32 v7, v7, v7
	v_mul_f32_e32 v7, 0xbfb8aa3b, v7
	v_exp_f32_e32 v7, v7
	s_nop 0
	v_add_f32_e32 v7, 1.0, v7
	v_rcp_f32_e32 v7, v7
	s_nop 0
	v_mul_f32_e32 v2, v2, v7
	v_ashrrev_i32_e32 v7, 31, v6
	v_lshl_add_u64 v[6:7], s[12:13], 0, v[6:7]
	v_lshlrev_b64 v[6:7], 11, v[6:7]
	v_cvt_pk_bf16_f32 v2, v2, s0
	v_lshl_add_u64 v[6:7], v[0:1], 0, v[6:7]
	global_store_short v[6:7], v2, off
	v_add_u32_e32 v6, 0x72, v38
	v_lshl_add_u32 v2, v6, 6, v41
	ds_read_b32 v2, v2
	s_waitcnt lgkmcnt(0)
	v_fma_f32 v2, v40, v2, v8
	v_mul_f32_e32 v7, 0x3d372713, v2
	v_mul_f32_e32 v7, v2, v7
	v_fma_f32 v7, v2, v7, v2
	v_mul_f32_e32 v7, 0x3f4c422a, v7
	v_add_f32_e32 v7, v7, v7
	v_mul_f32_e32 v7, 0xbfb8aa3b, v7
	v_exp_f32_e32 v7, v7
	s_nop 0
	v_add_f32_e32 v7, 1.0, v7
	v_rcp_f32_e32 v7, v7
	s_nop 0
	v_mul_f32_e32 v2, v2, v7
	v_ashrrev_i32_e32 v7, 31, v6
	v_lshl_add_u64 v[6:7], s[12:13], 0, v[6:7]
	v_lshlrev_b64 v[6:7], 11, v[6:7]
	v_cvt_pk_bf16_f32 v2, v2, s0
	v_lshl_add_u64 v[6:7], v[0:1], 0, v[6:7]
	global_store_short v[6:7], v2, off
	v_add_u32_e32 v6, 0x73, v38
	v_lshl_add_u32 v2, v6, 6, v41
	ds_read_b32 v2, v2
	v_ashrrev_i32_e32 v7, 31, v6
	v_lshl_add_u64 v[6:7], s[12:13], 0, v[6:7]
	v_lshlrev_b64 v[6:7], 11, v[6:7]
	v_lshl_add_u64 v[0:1], v[0:1], 0, v[6:7]
	s_waitcnt lgkmcnt(0)
	v_fmac_f32_e32 v9, v40, v2
	v_mul_f32_e32 v2, 0x3d372713, v9
	v_mul_f32_e32 v2, v9, v2
	v_fma_f32 v2, v9, v2, v9
	v_mul_f32_e32 v2, 0x3f4c422a, v2
	v_add_f32_e32 v2, v2, v2
	v_mul_f32_e32 v2, 0xbfb8aa3b, v2
	v_exp_f32_e32 v2, v2
	s_nop 0
	v_add_f32_e32 v2, 1.0, v2
	v_rcp_f32_e32 v2, v2
	s_nop 0
	v_mul_f32_e32 v2, v9, v2
	v_cvt_pk_bf16_f32 v2, v2, s0
	global_store_short v[0:1], v2, off
	s_waitcnt lgkmcnt(0)
	s_add_i32 s0, s54, 0x400
	s_cmpk_gt_i32 s54, 0x1bff
	s_mov_b32 s54, s0
	s_cbranch_scc0 .LBB0_680
